# hand-written RWKV prompt prep (SGPR addressing, d16_hi loads, exp instead of divide, W renormalised every 8 steps) on top of hand-written scan
# speedup vs baseline: 1.1002x; 1.0128x over previous
.LBB0_1321:
	ds_read_b64 v[6:7], v75
	ds_read_b128 v[2:5], v195
	s_ashr_i32 s40, s72, 1
	s_and_b32 s73, s40, 15
	v_lshl_or_b32 v42, s73, 6, v1
	s_waitcnt lgkmcnt(0)
	v_readfirstlane_b32 s0, v6
	v_readfirstlane_b32 s1, v7
	v_lshlrev_b32_e32 v76, 2, v42
	s_lshl_b32 s41, s72, 6
	v_lshl_add_u64 v[6:7], s[0:1], 0, v[76:77]
	v_add_co_u32_e32 v8, vcc, s67, v6
	s_waitcnt lgkmcnt(0)
	v_readfirstlane_b32 s0, v2
	v_addc_co_u32_e32 v9, vcc, 0, v7, vcc
	v_readfirstlane_b32 s1, v3
	v_add_co_u32_e32 v10, vcc, s68, v6
	s_nop 0
	v_lshl_add_u64 v[2:3], s[0:1], 0, v[76:77]
	v_readfirstlane_b32 s0, v4
	v_readfirstlane_b32 s1, v5
	v_addc_co_u32_e32 v11, vcc, 0, v7, vcc
	s_waitcnt vmcnt(0)
	flat_load_dword v196, v[6:7]
	flat_load_dword v197, v[8:9]
	flat_load_dword v198, v[10:11]
	flat_load_dword v199, v[2:3]
	v_lshl_add_u64 v[2:3], s[0:1], 0, v[76:77]
	flat_load_dword v200, v[2:3]
	s_and_b32 s42, s41, 0xfffff800
	s_and_saveexec_b64 s[0:1], s[4:5]
	s_xor_b64 s[56:57], exec, s[0:1]
	s_setprio 2
	s_lshl_b32 s30, s73, 2
	v_add_u32_e32 v80, s42, v165
	s_or_saveexec_b64 s[56:57], s[56:57]
	v_mov_b64_e32 v[10:11], s[30:31]
	s_xor_b64 exec, exec, s[56:57]
	s_cbranch_execz .LBB0_1345
	v_mov_b32_e32 v100, 0
	v_mov_b32_e32 v101, 0
	v_mov_b32_e32 v102, 0
	v_mov_b32_e32 v103, 0
	v_mov_b32_e32 v104, 0
	v_mov_b32_e32 v105, 0
	v_mov_b32_e32 v106, 0
	v_mov_b32_e32 v107, 0
	v_mov_b32_e32 v108, 0
	v_mov_b32_e32 v109, 0
	v_mov_b32_e32 v110, 0
	v_mov_b32_e32 v111, 0
	v_mov_b32_e32 v112, 0
	v_mov_b32_e32 v113, 0
	v_mov_b32_e32 v114, 0
	v_mov_b32_e32 v115, 0
	v_mov_b32_e32 v116, 0
	v_mov_b32_e32 v117, 0
	v_mov_b32_e32 v118, 0
	v_mov_b32_e32 v119, 0
	v_mov_b32_e32 v120, 0
	v_mov_b32_e32 v121, 0
	v_mov_b32_e32 v122, 0
	v_mov_b32_e32 v123, 0
	v_mov_b32_e32 v124, 0
	v_mov_b32_e32 v125, 0
	v_mov_b32_e32 v126, 0
	v_mov_b32_e32 v127, 0
	v_mov_b32_e32 v128, 0
	v_mov_b32_e32 v129, 0
	v_mov_b32_e32 v130, 0
	v_mov_b32_e32 v131, 0
	v_mov_b32_e32 v132, 0
	v_mov_b32_e32 v133, 0
	v_mov_b32_e32 v134, 0
	v_mov_b32_e32 v135, 0
	v_mov_b32_e32 v136, 0
	v_mov_b32_e32 v137, 0
	v_mov_b32_e32 v138, 0
	v_mov_b32_e32 v139, 0
	v_mov_b32_e32 v172, 0
	v_mov_b32_e32 v173, 0
	v_mov_b32_e32 v174, 0
	v_lshlrev_b32_e32 v175, 1, v1
	v_readfirstlane_b32 s33, v179
	s_nop 0
	s_sub_u32 s33, s33, 4
	s_lshl_b32 s41, s33, 3
	s_add_u32 s41, s41, s42
	s_lshl_b32 s0, s73, 7
	s_mul_i32 s1, s41, 0x5200
	s_add_u32 s1, s1, s0
	s_add_u32 s1, s1, 0x3000
	s_add_u32 s98, s20, s1
	s_addc_u32 s99, s21, 0
	s_lshl_b32 s1, s41, 11
	s_add_u32 s1, s1, s0
	s_add_u32 s100, s22, s1
	s_addc_u32 s101, s23, 0
	s_add_u32 s58, s26, s1
	s_addc_u32 s59, s27, 0
	s_lshl_b32 s1, s41, 8
	s_lshl_b32 s0, s73, 4
	s_add_u32 s1, s1, s0
	s_add_u32 s60, s28, s1
	s_addc_u32 s61, s29, 0
	s_sub_u32 s0, s98, 0x5200
	s_subb_u32 s1, s99, 0
	s_cmp_eq_u32 s33, 0
	s_cbranch_scc1 .Lrwq_noq0_a
	global_load_short_d16_hi v172, v175, s[0:1] offset:-2048
	global_load_short_d16_hi v173, v175, s[0:1]
	global_load_short_d16_hi v174, v175, s[0:1] offset:2048
.Lrwq_noq0_a:
	s_add_u32 s0, s0, 0x5200
	s_addc_u32 s1, s1, 0
	global_load_short_d16_hi v100, v175, s[0:1] offset:-2048
	global_load_short_d16_hi v108, v175, s[0:1]
	global_load_short_d16_hi v116, v175, s[0:1] offset:2048
	s_add_u32 s0, s0, 0x5200
	s_addc_u32 s1, s1, 0
	global_load_short_d16_hi v101, v175, s[0:1] offset:-2048
	global_load_short_d16_hi v109, v175, s[0:1]
	global_load_short_d16_hi v117, v175, s[0:1] offset:2048
	s_add_u32 s0, s0, 0x5200
	s_addc_u32 s1, s1, 0
	global_load_short_d16_hi v102, v175, s[0:1] offset:-2048
	global_load_short_d16_hi v110, v175, s[0:1]
	global_load_short_d16_hi v118, v175, s[0:1] offset:2048
	s_add_u32 s0, s0, 0x5200
	s_addc_u32 s1, s1, 0
	global_load_short_d16_hi v103, v175, s[0:1] offset:-2048
	global_load_short_d16_hi v111, v175, s[0:1]
	global_load_short_d16_hi v119, v175, s[0:1] offset:2048
	s_add_u32 s0, s0, 0x5200
	s_addc_u32 s1, s1, 0
	global_load_short_d16_hi v104, v175, s[0:1] offset:-2048
	global_load_short_d16_hi v112, v175, s[0:1]
	global_load_short_d16_hi v120, v175, s[0:1] offset:2048
	s_add_u32 s0, s0, 0x5200
	s_addc_u32 s1, s1, 0
	global_load_short_d16_hi v105, v175, s[0:1] offset:-2048
	global_load_short_d16_hi v113, v175, s[0:1]
	global_load_short_d16_hi v121, v175, s[0:1] offset:2048
	s_add_u32 s0, s0, 0x5200
	s_addc_u32 s1, s1, 0
	global_load_short_d16_hi v106, v175, s[0:1] offset:-2048
	global_load_short_d16_hi v114, v175, s[0:1]
	global_load_short_d16_hi v122, v175, s[0:1] offset:2048
	s_add_u32 s0, s0, 0x5200
	s_addc_u32 s1, s1, 0
	global_load_short_d16_hi v107, v175, s[0:1] offset:-2048
	global_load_short_d16_hi v115, v175, s[0:1]
	global_load_short_d16_hi v123, v175, s[0:1] offset:2048
	s_add_u32 s0, s100, 0x0
	s_addc_u32 s1, s101, 0
	global_load_short_d16_hi v124, v175, s[0:1]
	global_load_short_d16_hi v125, v175, s[0:1] offset:2048
	s_add_u32 s0, s58, 0x0
	s_addc_u32 s1, s59, 0
	global_load_short_d16_hi v132, v175, s[0:1]
	global_load_short_d16_hi v133, v175, s[0:1] offset:2048
	s_add_u32 s0, s100, 0x1000
	s_addc_u32 s1, s101, 0
	global_load_short_d16_hi v126, v175, s[0:1]
	global_load_short_d16_hi v127, v175, s[0:1] offset:2048
	s_add_u32 s0, s58, 0x1000
	s_addc_u32 s1, s59, 0
	global_load_short_d16_hi v134, v175, s[0:1]
	global_load_short_d16_hi v135, v175, s[0:1] offset:2048
	s_add_u32 s0, s100, 0x2000
	s_addc_u32 s1, s101, 0
	global_load_short_d16_hi v128, v175, s[0:1]
	global_load_short_d16_hi v129, v175, s[0:1] offset:2048
	s_add_u32 s0, s58, 0x2000
	s_addc_u32 s1, s59, 0
	global_load_short_d16_hi v136, v175, s[0:1]
	global_load_short_d16_hi v137, v175, s[0:1] offset:2048
	s_add_u32 s0, s100, 0x3000
	s_addc_u32 s1, s101, 0
	global_load_short_d16_hi v130, v175, s[0:1]
	global_load_short_d16_hi v131, v175, s[0:1] offset:2048
	s_add_u32 s0, s58, 0x3000
	s_addc_u32 s1, s59, 0
	global_load_short_d16_hi v138, v175, s[0:1]
	global_load_short_d16_hi v139, v175, s[0:1] offset:2048
	global_load_dwordx4 v[140:143], v77, s[60:61] offset:-4
	global_load_dwordx4 v[144:147], v77, s[60:61] offset:252
	global_load_dwordx4 v[148:151], v77, s[60:61] offset:508
	global_load_dwordx4 v[152:155], v77, s[60:61] offset:764
	global_load_dwordx4 v[156:159], v77, s[60:61] offset:1020
	global_load_dwordx4 v[160:163], v77, s[60:61] offset:1276
	global_load_dwordx4 v[164:167], v77, s[60:61] offset:1532
	global_load_dwordx4 v[168:171], v77, s[60:61] offset:1788
	s_add_u32 s98, s98, 0xa4000
	s_addc_u32 s99, s99, 0
	s_add_u32 s100, s100, 0x10000
	s_addc_u32 s101, s101, 0
	s_add_u32 s58, s58, 0x10000
	s_addc_u32 s59, s59, 0
	s_add_u32 s60, s60, 0x2000
	s_addc_u32 s61, s61, 0
	s_waitcnt vmcnt(0)
	v_sub_f32_e32 v221, 1.0, v200
	s_mov_b32 s0, 0
	s_waitcnt vmcnt(0)
	v_add_u32_e32 v222, s0, v186
	v_add_u32_e32 v223, s0, v185
	v_mul_f32_e32 v204, 0xbfb8aa3b, v124
	v_mul_f32_e32 v205, 0x3fb8aa3b, v124
	v_sub_f32_e32 v208, v172, v100
	v_exp_f32_e32 v211, v204
	v_exp_f32_e32 v212, v205
	v_sub_f32_e32 v209, v173, v108
	v_sub_f32_e32 v210, v174, v116
	v_fma_f32 v208, v196, v208, v100
	v_fma_f32 v209, v197, v209, v108
	v_fma_f32 v210, v198, v210, v116
	v_mul_f32_e32 v213, v209, v199
	v_fma_f32 v214, v132, v200, v221
	v_mul_f32_e32 v213, v213, v141
	v_mul_f32_e32 v215, v209, v214
	v_mul_f32_e32 v217, -1.0, v213
	v_mul_f32_e32 v216, v213, v132
	v_mul_f32_e32 v218, v211, v208
	ds_write2st64_b32 v222, v217, v218 offset0:0 offset1:1
	v_mul_f32_e32 v219, v216, v212
	v_mul_f32_e32 v220, v215, v212
	ds_write2st64_b32 v222, v211, v219 offset0:2 offset1:3
	ds_write2st64_b32 v222, v220, v210 offset0:4 offset1:5
	v_add_u32_e32 v222, 16, v222
	v_mul_f32_e32 v204, 0xbfb8aa3b, v125
	v_mul_f32_e32 v205, 0x3fb8aa3b, v125
	v_sub_f32_e32 v208, v100, v101
	v_exp_f32_e32 v206, v204
	v_exp_f32_e32 v207, v205
	v_sub_f32_e32 v209, v108, v109
	v_sub_f32_e32 v210, v116, v117
	v_fma_f32 v208, v196, v208, v101
	v_fma_f32 v209, v197, v209, v109
	v_fma_f32 v210, v198, v210, v117
	v_mul_f32_e32 v213, v209, v199
	v_fma_f32 v214, v133, v200, v221
	v_mul_f32_e32 v213, v213, v145
	v_mul_f32_e32 v215, v209, v214
	v_mul_f32_e64 v217, -v213, v211
	v_mul_f32_e32 v211, v211, v206
	v_mul_f32_e32 v212, v212, v207
	v_mul_f32_e32 v216, v213, v133
	v_mul_f32_e32 v218, v211, v208
	ds_write2st64_b32 v222, v217, v218 offset0:6 offset1:7
	v_mul_f32_e32 v219, v216, v212
	v_mul_f32_e32 v220, v215, v212
	ds_write2st64_b32 v222, v211, v219 offset0:8 offset1:9
	ds_write2st64_b32 v222, v220, v210 offset0:10 offset1:11
	v_add_u32_e32 v222, 16, v222
	v_mul_f32_e32 v204, 0xbfb8aa3b, v126
	v_mul_f32_e32 v205, 0x3fb8aa3b, v126
	v_sub_f32_e32 v208, v101, v102
	v_exp_f32_e32 v206, v204
	v_exp_f32_e32 v207, v205
	v_sub_f32_e32 v209, v109, v110
	v_sub_f32_e32 v210, v117, v118
	v_fma_f32 v208, v196, v208, v102
	v_fma_f32 v209, v197, v209, v110
	v_fma_f32 v210, v198, v210, v118
	v_mul_f32_e32 v213, v209, v199
	v_fma_f32 v214, v134, v200, v221
	v_mul_f32_e32 v213, v213, v149
	v_mul_f32_e32 v215, v209, v214
	v_mul_f32_e64 v217, -v213, v211
	v_mul_f32_e32 v211, v211, v206
	v_mul_f32_e32 v212, v212, v207
	v_mul_f32_e32 v216, v213, v134
	v_mul_f32_e32 v218, v211, v208
	ds_write2st64_b32 v222, v217, v218 offset0:12 offset1:13
	v_mul_f32_e32 v219, v216, v212
	v_mul_f32_e32 v220, v215, v212
	ds_write2st64_b32 v222, v211, v219 offset0:14 offset1:15
	ds_write2st64_b32 v222, v220, v210 offset0:16 offset1:17
	v_add_u32_e32 v222, 16, v222
	v_mul_f32_e32 v204, 0xbfb8aa3b, v127
	v_mul_f32_e32 v205, 0x3fb8aa3b, v127
	v_sub_f32_e32 v208, v102, v103
	v_exp_f32_e32 v206, v204
	v_exp_f32_e32 v207, v205
	v_sub_f32_e32 v209, v110, v111
	v_sub_f32_e32 v210, v118, v119
	v_fma_f32 v208, v196, v208, v103
	v_fma_f32 v209, v197, v209, v111
	v_fma_f32 v210, v198, v210, v119
	v_mul_f32_e32 v213, v209, v199
	v_fma_f32 v214, v135, v200, v221
	v_mul_f32_e32 v213, v213, v153
	v_mul_f32_e32 v215, v209, v214
	v_mul_f32_e64 v217, -v213, v211
	v_mul_f32_e32 v211, v211, v206
	v_mul_f32_e32 v212, v212, v207
	v_mul_f32_e32 v216, v213, v135
	v_mul_f32_e32 v218, v211, v208
	ds_write2st64_b32 v222, v217, v218 offset0:18 offset1:19
	v_mul_f32_e32 v219, v216, v212
	v_mul_f32_e32 v220, v215, v212
	ds_write2st64_b32 v222, v211, v219 offset0:20 offset1:21
	ds_write2st64_b32 v222, v220, v210 offset0:22 offset1:23
	v_add_u32_e32 v222, 16, v222
	v_mul_f32_e32 v204, 0xbfb8aa3b, v128
	v_mul_f32_e32 v205, 0x3fb8aa3b, v128
	v_sub_f32_e32 v208, v103, v104
	v_exp_f32_e32 v206, v204
	v_exp_f32_e32 v207, v205
	v_sub_f32_e32 v209, v111, v112
	v_sub_f32_e32 v210, v119, v120
	v_fma_f32 v208, v196, v208, v104
	v_fma_f32 v209, v197, v209, v112
	v_fma_f32 v210, v198, v210, v120
	v_mul_f32_e32 v213, v209, v199
	v_fma_f32 v214, v136, v200, v221
	v_mul_f32_e32 v213, v213, v157
	v_mul_f32_e32 v215, v209, v214
	v_mul_f32_e64 v217, -v213, v211
	v_mul_f32_e32 v211, v211, v206
	v_mul_f32_e32 v212, v212, v207
	v_mul_f32_e32 v216, v213, v136
	v_mul_f32_e32 v218, v211, v208
	ds_write2st64_b32 v222, v217, v218 offset0:24 offset1:25
	v_mul_f32_e32 v219, v216, v212
	v_mul_f32_e32 v220, v215, v212
	ds_write2st64_b32 v222, v211, v219 offset0:26 offset1:27
	ds_write2st64_b32 v222, v220, v210 offset0:28 offset1:29
	v_add_u32_e32 v222, 16, v222
	v_mul_f32_e32 v204, 0xbfb8aa3b, v129
	v_mul_f32_e32 v205, 0x3fb8aa3b, v129
	v_sub_f32_e32 v208, v104, v105
	v_exp_f32_e32 v206, v204
	v_exp_f32_e32 v207, v205
	v_sub_f32_e32 v209, v112, v113
	v_sub_f32_e32 v210, v120, v121
	v_fma_f32 v208, v196, v208, v105
	v_fma_f32 v209, v197, v209, v113
	v_fma_f32 v210, v198, v210, v121
	v_mul_f32_e32 v213, v209, v199
	v_fma_f32 v214, v137, v200, v221
	v_mul_f32_e32 v213, v213, v161
	v_mul_f32_e32 v215, v209, v214
	v_mul_f32_e64 v217, -v213, v211
	v_mul_f32_e32 v211, v211, v206
	v_mul_f32_e32 v212, v212, v207
	v_mul_f32_e32 v216, v213, v137
	v_mul_f32_e32 v218, v211, v208
	ds_write2st64_b32 v222, v217, v218 offset0:30 offset1:31
	v_mul_f32_e32 v219, v216, v212
	v_mul_f32_e32 v220, v215, v212
	ds_write2st64_b32 v222, v211, v219 offset0:32 offset1:33
	ds_write2st64_b32 v222, v220, v210 offset0:34 offset1:35
	v_add_u32_e32 v222, 16, v222
	v_mul_f32_e32 v204, 0xbfb8aa3b, v130
	v_mul_f32_e32 v205, 0x3fb8aa3b, v130
	v_sub_f32_e32 v208, v105, v106
	v_exp_f32_e32 v206, v204
	v_exp_f32_e32 v207, v205
	v_sub_f32_e32 v209, v113, v114
	v_sub_f32_e32 v210, v121, v122
	v_fma_f32 v208, v196, v208, v106
	v_fma_f32 v209, v197, v209, v114
	v_fma_f32 v210, v198, v210, v122
	v_mul_f32_e32 v213, v209, v199
	v_fma_f32 v214, v138, v200, v221
	v_mul_f32_e32 v213, v213, v165
	v_mul_f32_e32 v215, v209, v214
	v_mul_f32_e64 v217, -v213, v211
	v_mul_f32_e32 v211, v211, v206
	v_mul_f32_e32 v212, v212, v207
	v_mul_f32_e32 v216, v213, v138
	v_mul_f32_e32 v218, v211, v208
	ds_write2st64_b32 v222, v217, v218 offset0:36 offset1:37
	v_mul_f32_e32 v219, v216, v212
	v_mul_f32_e32 v220, v215, v212
	ds_write2st64_b32 v222, v211, v219 offset0:38 offset1:39
	ds_write2st64_b32 v222, v220, v210 offset0:40 offset1:41
	v_add_u32_e32 v222, 16, v222
	v_mul_f32_e32 v204, 0xbfb8aa3b, v131
	v_mul_f32_e32 v205, 0x3fb8aa3b, v131
	v_sub_f32_e32 v208, v106, v107
	v_exp_f32_e32 v206, v204
	v_exp_f32_e32 v207, v205
	v_sub_f32_e32 v209, v114, v115
	v_sub_f32_e32 v210, v122, v123
	v_fma_f32 v208, v196, v208, v107
	v_fma_f32 v209, v197, v209, v115
	v_fma_f32 v210, v198, v210, v123
	v_mul_f32_e32 v213, v209, v199
	v_fma_f32 v214, v139, v200, v221
	v_mul_f32_e32 v213, v213, v169
	v_mul_f32_e32 v215, v209, v214
	v_mul_f32_e64 v217, -v213, v211
	v_mul_f32_e32 v211, v211, v206
	v_mul_f32_e32 v212, v212, v207
	v_mul_f32_e32 v216, v213, v139
	v_mul_f32_e32 v218, v211, v208
	ds_write2st64_b32 v222, v217, v218 offset0:42 offset1:43
	v_mul_f32_e32 v219, v216, v212
	v_mul_f32_e32 v220, v215, v212
	ds_write2st64_b32 v222, v211, v219 offset0:44 offset1:45
	ds_write2st64_b32 v222, v220, v210 offset0:46 offset1:47
	s_and_saveexec_b64 s[0:1], s[12:13]
	ds_write_b64 v223, v[142:143] offset:1536
	ds_write_b64 v223, v[146:147] offset:3088
	ds_write_b64 v223, v[150:151] offset:4640
	ds_write_b64 v223, v[154:155] offset:6192
	ds_write_b64 v223, v[158:159] offset:7744
	ds_write_b64 v223, v[162:163] offset:9296
	ds_write_b64 v223, v[166:167] offset:10848
	ds_write_b64 v223, v[170:171] offset:12400
	s_or_b64 exec, exec, s[0:1]
	s_sub_u32 s0, s98, 0x5200
	s_subb_u32 s1, s99, 0
	global_load_short_d16_hi v172, v175, s[0:1] offset:-2048
	global_load_short_d16_hi v173, v175, s[0:1]
	global_load_short_d16_hi v174, v175, s[0:1] offset:2048
	s_add_u32 s0, s0, 0x5200
	s_addc_u32 s1, s1, 0
	global_load_short_d16_hi v100, v175, s[0:1] offset:-2048
	global_load_short_d16_hi v108, v175, s[0:1]
	global_load_short_d16_hi v116, v175, s[0:1] offset:2048
	s_add_u32 s0, s0, 0x5200
	s_addc_u32 s1, s1, 0
	global_load_short_d16_hi v101, v175, s[0:1] offset:-2048
	global_load_short_d16_hi v109, v175, s[0:1]
	global_load_short_d16_hi v117, v175, s[0:1] offset:2048
	s_add_u32 s0, s0, 0x5200
	s_addc_u32 s1, s1, 0
	global_load_short_d16_hi v102, v175, s[0:1] offset:-2048
	global_load_short_d16_hi v110, v175, s[0:1]
	global_load_short_d16_hi v118, v175, s[0:1] offset:2048
	s_add_u32 s0, s0, 0x5200
	s_addc_u32 s1, s1, 0
	global_load_short_d16_hi v103, v175, s[0:1] offset:-2048
	global_load_short_d16_hi v111, v175, s[0:1]
	global_load_short_d16_hi v119, v175, s[0:1] offset:2048
	s_add_u32 s0, s0, 0x5200
	s_addc_u32 s1, s1, 0
	global_load_short_d16_hi v104, v175, s[0:1] offset:-2048
	global_load_short_d16_hi v112, v175, s[0:1]
	global_load_short_d16_hi v120, v175, s[0:1] offset:2048
	s_add_u32 s0, s0, 0x5200
	s_addc_u32 s1, s1, 0
	global_load_short_d16_hi v105, v175, s[0:1] offset:-2048
	global_load_short_d16_hi v113, v175, s[0:1]
	global_load_short_d16_hi v121, v175, s[0:1] offset:2048
	s_add_u32 s0, s0, 0x5200
	s_addc_u32 s1, s1, 0
	global_load_short_d16_hi v106, v175, s[0:1] offset:-2048
	global_load_short_d16_hi v114, v175, s[0:1]
	global_load_short_d16_hi v122, v175, s[0:1] offset:2048
	s_add_u32 s0, s0, 0x5200
	s_addc_u32 s1, s1, 0
	global_load_short_d16_hi v107, v175, s[0:1] offset:-2048
	global_load_short_d16_hi v115, v175, s[0:1]
	global_load_short_d16_hi v123, v175, s[0:1] offset:2048
	s_add_u32 s0, s100, 0x0
	s_addc_u32 s1, s101, 0
	global_load_short_d16_hi v124, v175, s[0:1]
	global_load_short_d16_hi v125, v175, s[0:1] offset:2048
	s_add_u32 s0, s58, 0x0
	s_addc_u32 s1, s59, 0
	global_load_short_d16_hi v132, v175, s[0:1]
	global_load_short_d16_hi v133, v175, s[0:1] offset:2048
	s_add_u32 s0, s100, 0x1000
	s_addc_u32 s1, s101, 0
	global_load_short_d16_hi v126, v175, s[0:1]
	global_load_short_d16_hi v127, v175, s[0:1] offset:2048
	s_add_u32 s0, s58, 0x1000
	s_addc_u32 s1, s59, 0
	global_load_short_d16_hi v134, v175, s[0:1]
	global_load_short_d16_hi v135, v175, s[0:1] offset:2048
	s_add_u32 s0, s100, 0x2000
	s_addc_u32 s1, s101, 0
	global_load_short_d16_hi v128, v175, s[0:1]
	global_load_short_d16_hi v129, v175, s[0:1] offset:2048
	s_add_u32 s0, s58, 0x2000
	s_addc_u32 s1, s59, 0
	global_load_short_d16_hi v136, v175, s[0:1]
	global_load_short_d16_hi v137, v175, s[0:1] offset:2048
	s_add_u32 s0, s100, 0x3000
	s_addc_u32 s1, s101, 0
	global_load_short_d16_hi v130, v175, s[0:1]
	global_load_short_d16_hi v131, v175, s[0:1] offset:2048
	s_add_u32 s0, s58, 0x3000
	s_addc_u32 s1, s59, 0
	global_load_short_d16_hi v138, v175, s[0:1]
	global_load_short_d16_hi v139, v175, s[0:1] offset:2048
	global_load_dwordx4 v[140:143], v77, s[60:61] offset:-4
	global_load_dwordx4 v[144:147], v77, s[60:61] offset:252
	global_load_dwordx4 v[148:151], v77, s[60:61] offset:508
	global_load_dwordx4 v[152:155], v77, s[60:61] offset:764
	global_load_dwordx4 v[156:159], v77, s[60:61] offset:1020
	global_load_dwordx4 v[160:163], v77, s[60:61] offset:1276
	global_load_dwordx4 v[164:167], v77, s[60:61] offset:1532
	global_load_dwordx4 v[168:171], v77, s[60:61] offset:1788
	s_add_u32 s98, s98, 0xa4000
	s_addc_u32 s99, s99, 0
	s_add_u32 s100, s100, 0x10000
	s_addc_u32 s101, s101, 0
	s_add_u32 s58, s58, 0x10000
	s_addc_u32 s59, s59, 0
	s_add_u32 s60, s60, 0x2000
	s_addc_u32 s61, s61, 0

.LBB0_1348:
	s_and_saveexec_b64 s[0:1], s[16:17]
	s_xor_b64 s[56:57], exec, s[0:1]
	s_cbranch_execz .LBB0_1368
	s_cmp_eq_u32 s30, 63
	s_cbranch_scc1 .LBB0_1368
	s_andn2_b32 s0, 1, s30
	s_mul_i32 s0, s0, 0xc200
	s_waitcnt vmcnt(0)
	v_add_u32_e32 v222, s0, v186
	v_add_u32_e32 v223, s0, v185
	v_mul_f32_e32 v204, 0xbfb8aa3b, v124
	v_mul_f32_e32 v205, 0x3fb8aa3b, v124
	v_sub_f32_e32 v208, v172, v100
	v_exp_f32_e32 v211, v204
	v_exp_f32_e32 v212, v205
	v_sub_f32_e32 v209, v173, v108
	v_sub_f32_e32 v210, v174, v116
	v_fma_f32 v208, v196, v208, v100
	v_fma_f32 v209, v197, v209, v108
	v_fma_f32 v210, v198, v210, v116
	v_mul_f32_e32 v213, v209, v199
	v_fma_f32 v214, v132, v200, v221
	v_mul_f32_e32 v213, v213, v141
	v_mul_f32_e32 v215, v209, v214
	v_mul_f32_e32 v217, -1.0, v213
	v_mul_f32_e32 v216, v213, v132
	v_mul_f32_e32 v218, v211, v208
	ds_write2st64_b32 v222, v217, v218 offset0:0 offset1:1
	v_mul_f32_e32 v219, v216, v212
	v_mul_f32_e32 v220, v215, v212
	ds_write2st64_b32 v222, v211, v219 offset0:2 offset1:3
	ds_write2st64_b32 v222, v220, v210 offset0:4 offset1:5
	v_add_u32_e32 v222, 16, v222
	v_mul_f32_e32 v204, 0xbfb8aa3b, v125
	v_mul_f32_e32 v205, 0x3fb8aa3b, v125
	v_sub_f32_e32 v208, v100, v101
	v_exp_f32_e32 v206, v204
	v_exp_f32_e32 v207, v205
	v_sub_f32_e32 v209, v108, v109
	v_sub_f32_e32 v210, v116, v117
	v_fma_f32 v208, v196, v208, v101
	v_fma_f32 v209, v197, v209, v109
	v_fma_f32 v210, v198, v210, v117
	v_mul_f32_e32 v213, v209, v199
	v_fma_f32 v214, v133, v200, v221
	v_mul_f32_e32 v213, v213, v145
	v_mul_f32_e32 v215, v209, v214
	v_mul_f32_e64 v217, -v213, v211
	v_mul_f32_e32 v211, v211, v206
	v_mul_f32_e32 v212, v212, v207
	v_mul_f32_e32 v216, v213, v133
	v_mul_f32_e32 v218, v211, v208
	ds_write2st64_b32 v222, v217, v218 offset0:6 offset1:7
	v_mul_f32_e32 v219, v216, v212
	v_mul_f32_e32 v220, v215, v212
	ds_write2st64_b32 v222, v211, v219 offset0:8 offset1:9
	ds_write2st64_b32 v222, v220, v210 offset0:10 offset1:11
	v_add_u32_e32 v222, 16, v222
	v_mul_f32_e32 v204, 0xbfb8aa3b, v126
	v_mul_f32_e32 v205, 0x3fb8aa3b, v126
	v_sub_f32_e32 v208, v101, v102
	v_exp_f32_e32 v206, v204
	v_exp_f32_e32 v207, v205
	v_sub_f32_e32 v209, v109, v110
	v_sub_f32_e32 v210, v117, v118
	v_fma_f32 v208, v196, v208, v102
	v_fma_f32 v209, v197, v209, v110
	v_fma_f32 v210, v198, v210, v118
	v_mul_f32_e32 v213, v209, v199
	v_fma_f32 v214, v134, v200, v221
	v_mul_f32_e32 v213, v213, v149
	v_mul_f32_e32 v215, v209, v214
	v_mul_f32_e64 v217, -v213, v211
	v_mul_f32_e32 v211, v211, v206
	v_mul_f32_e32 v212, v212, v207
	v_mul_f32_e32 v216, v213, v134
	v_mul_f32_e32 v218, v211, v208
	ds_write2st64_b32 v222, v217, v218 offset0:12 offset1:13
	v_mul_f32_e32 v219, v216, v212
	v_mul_f32_e32 v220, v215, v212
	ds_write2st64_b32 v222, v211, v219 offset0:14 offset1:15
	ds_write2st64_b32 v222, v220, v210 offset0:16 offset1:17
	v_add_u32_e32 v222, 16, v222
	v_mul_f32_e32 v204, 0xbfb8aa3b, v127
	v_mul_f32_e32 v205, 0x3fb8aa3b, v127
	v_sub_f32_e32 v208, v102, v103
	v_exp_f32_e32 v206, v204
	v_exp_f32_e32 v207, v205
	v_sub_f32_e32 v209, v110, v111
	v_sub_f32_e32 v210, v118, v119
	v_fma_f32 v208, v196, v208, v103
	v_fma_f32 v209, v197, v209, v111
	v_fma_f32 v210, v198, v210, v119
	v_mul_f32_e32 v213, v209, v199
	v_fma_f32 v214, v135, v200, v221
	v_mul_f32_e32 v213, v213, v153
	v_mul_f32_e32 v215, v209, v214
	v_mul_f32_e64 v217, -v213, v211
	v_mul_f32_e32 v211, v211, v206
	v_mul_f32_e32 v212, v212, v207
	v_mul_f32_e32 v216, v213, v135
	v_mul_f32_e32 v218, v211, v208
	ds_write2st64_b32 v222, v217, v218 offset0:18 offset1:19
	v_mul_f32_e32 v219, v216, v212
	v_mul_f32_e32 v220, v215, v212
	ds_write2st64_b32 v222, v211, v219 offset0:20 offset1:21
	ds_write2st64_b32 v222, v220, v210 offset0:22 offset1:23
	v_add_u32_e32 v222, 16, v222
	v_mul_f32_e32 v204, 0xbfb8aa3b, v128
	v_mul_f32_e32 v205, 0x3fb8aa3b, v128
	v_sub_f32_e32 v208, v103, v104
	v_exp_f32_e32 v206, v204
	v_exp_f32_e32 v207, v205
	v_sub_f32_e32 v209, v111, v112
	v_sub_f32_e32 v210, v119, v120
	v_fma_f32 v208, v196, v208, v104
	v_fma_f32 v209, v197, v209, v112
	v_fma_f32 v210, v198, v210, v120
	v_mul_f32_e32 v213, v209, v199
	v_fma_f32 v214, v136, v200, v221
	v_mul_f32_e32 v213, v213, v157
	v_mul_f32_e32 v215, v209, v214
	v_mul_f32_e64 v217, -v213, v211
	v_mul_f32_e32 v211, v211, v206
	v_mul_f32_e32 v212, v212, v207
	v_mul_f32_e32 v216, v213, v136
	v_mul_f32_e32 v218, v211, v208
	ds_write2st64_b32 v222, v217, v218 offset0:24 offset1:25
	v_mul_f32_e32 v219, v216, v212
	v_mul_f32_e32 v220, v215, v212
	ds_write2st64_b32 v222, v211, v219 offset0:26 offset1:27
	ds_write2st64_b32 v222, v220, v210 offset0:28 offset1:29
	v_add_u32_e32 v222, 16, v222
	v_mul_f32_e32 v204, 0xbfb8aa3b, v129
	v_mul_f32_e32 v205, 0x3fb8aa3b, v129
	v_sub_f32_e32 v208, v104, v105
	v_exp_f32_e32 v206, v204
	v_exp_f32_e32 v207, v205
	v_sub_f32_e32 v209, v112, v113
	v_sub_f32_e32 v210, v120, v121
	v_fma_f32 v208, v196, v208, v105
	v_fma_f32 v209, v197, v209, v113
	v_fma_f32 v210, v198, v210, v121
	v_mul_f32_e32 v213, v209, v199
	v_fma_f32 v214, v137, v200, v221
	v_mul_f32_e32 v213, v213, v161
	v_mul_f32_e32 v215, v209, v214
	v_mul_f32_e64 v217, -v213, v211
	v_mul_f32_e32 v211, v211, v206
	v_mul_f32_e32 v212, v212, v207
	v_mul_f32_e32 v216, v213, v137
	v_mul_f32_e32 v218, v211, v208
	ds_write2st64_b32 v222, v217, v218 offset0:30 offset1:31
	v_mul_f32_e32 v219, v216, v212
	v_mul_f32_e32 v220, v215, v212
	ds_write2st64_b32 v222, v211, v219 offset0:32 offset1:33
	ds_write2st64_b32 v222, v220, v210 offset0:34 offset1:35
	v_add_u32_e32 v222, 16, v222
	v_mul_f32_e32 v204, 0xbfb8aa3b, v130
	v_mul_f32_e32 v205, 0x3fb8aa3b, v130
	v_sub_f32_e32 v208, v105, v106
	v_exp_f32_e32 v206, v204
	v_exp_f32_e32 v207, v205
	v_sub_f32_e32 v209, v113, v114
	v_sub_f32_e32 v210, v121, v122
	v_fma_f32 v208, v196, v208, v106
	v_fma_f32 v209, v197, v209, v114
	v_fma_f32 v210, v198, v210, v122
	v_mul_f32_e32 v213, v209, v199
	v_fma_f32 v214, v138, v200, v221
	v_mul_f32_e32 v213, v213, v165
	v_mul_f32_e32 v215, v209, v214
	v_mul_f32_e64 v217, -v213, v211
	v_mul_f32_e32 v211, v211, v206
	v_mul_f32_e32 v212, v212, v207
	v_mul_f32_e32 v216, v213, v138
	v_mul_f32_e32 v218, v211, v208
	ds_write2st64_b32 v222, v217, v218 offset0:36 offset1:37
	v_mul_f32_e32 v219, v216, v212
	v_mul_f32_e32 v220, v215, v212
	ds_write2st64_b32 v222, v211, v219 offset0:38 offset1:39
	ds_write2st64_b32 v222, v220, v210 offset0:40 offset1:41
	v_add_u32_e32 v222, 16, v222
	v_mul_f32_e32 v204, 0xbfb8aa3b, v131
	v_mul_f32_e32 v205, 0x3fb8aa3b, v131
	v_sub_f32_e32 v208, v106, v107
	v_exp_f32_e32 v206, v204
	v_exp_f32_e32 v207, v205
	v_sub_f32_e32 v209, v114, v115
	v_sub_f32_e32 v210, v122, v123
	v_fma_f32 v208, v196, v208, v107
	v_fma_f32 v209, v197, v209, v115
	v_fma_f32 v210, v198, v210, v123
	v_mul_f32_e32 v213, v209, v199
	v_fma_f32 v214, v139, v200, v221
	v_mul_f32_e32 v213, v213, v169
	v_mul_f32_e32 v215, v209, v214
	v_mul_f32_e64 v217, -v213, v211
	v_mul_f32_e32 v211, v211, v206
	v_mul_f32_e32 v212, v212, v207
	v_mul_f32_e32 v216, v213, v139
	v_mul_f32_e32 v218, v211, v208
	ds_write2st64_b32 v222, v217, v218 offset0:42 offset1:43
	v_mul_f32_e32 v219, v216, v212
	v_mul_f32_e32 v220, v215, v212
	ds_write2st64_b32 v222, v211, v219 offset0:44 offset1:45
	ds_write2st64_b32 v222, v220, v210 offset0:46 offset1:47
	s_and_saveexec_b64 s[0:1], s[12:13]
	ds_write_b64 v223, v[142:143] offset:1536
	ds_write_b64 v223, v[146:147] offset:3088
	ds_write_b64 v223, v[150:151] offset:4640
	ds_write_b64 v223, v[154:155] offset:6192
	ds_write_b64 v223, v[158:159] offset:7744
	ds_write_b64 v223, v[162:163] offset:9296
	ds_write_b64 v223, v[166:167] offset:10848
	ds_write_b64 v223, v[170:171] offset:12400
	s_or_b64 exec, exec, s[0:1]
	s_cmp_gt_u32 s30, 61
	s_cbranch_scc1 .LBB0_1368
	s_sub_u32 s0, s98, 0x5200
	s_subb_u32 s1, s99, 0
	global_load_short_d16_hi v172, v175, s[0:1] offset:-2048
	global_load_short_d16_hi v173, v175, s[0:1]
	global_load_short_d16_hi v174, v175, s[0:1] offset:2048
	s_add_u32 s0, s0, 0x5200
	s_addc_u32 s1, s1, 0
	global_load_short_d16_hi v100, v175, s[0:1] offset:-2048
	global_load_short_d16_hi v108, v175, s[0:1]
	global_load_short_d16_hi v116, v175, s[0:1] offset:2048
	s_add_u32 s0, s0, 0x5200
	s_addc_u32 s1, s1, 0
	global_load_short_d16_hi v101, v175, s[0:1] offset:-2048
	global_load_short_d16_hi v109, v175, s[0:1]
	global_load_short_d16_hi v117, v175, s[0:1] offset:2048
	s_add_u32 s0, s0, 0x5200
	s_addc_u32 s1, s1, 0
	global_load_short_d16_hi v102, v175, s[0:1] offset:-2048
	global_load_short_d16_hi v110, v175, s[0:1]
	global_load_short_d16_hi v118, v175, s[0:1] offset:2048
	s_add_u32 s0, s0, 0x5200
	s_addc_u32 s1, s1, 0
	global_load_short_d16_hi v103, v175, s[0:1] offset:-2048
	global_load_short_d16_hi v111, v175, s[0:1]
	global_load_short_d16_hi v119, v175, s[0:1] offset:2048
	s_add_u32 s0, s0, 0x5200
	s_addc_u32 s1, s1, 0
	global_load_short_d16_hi v104, v175, s[0:1] offset:-2048
	global_load_short_d16_hi v112, v175, s[0:1]
	global_load_short_d16_hi v120, v175, s[0:1] offset:2048
	s_add_u32 s0, s0, 0x5200
	s_addc_u32 s1, s1, 0
	global_load_short_d16_hi v105, v175, s[0:1] offset:-2048
	global_load_short_d16_hi v113, v175, s[0:1]
	global_load_short_d16_hi v121, v175, s[0:1] offset:2048
	s_add_u32 s0, s0, 0x5200
	s_addc_u32 s1, s1, 0
	global_load_short_d16_hi v106, v175, s[0:1] offset:-2048
	global_load_short_d16_hi v114, v175, s[0:1]
	global_load_short_d16_hi v122, v175, s[0:1] offset:2048
	s_add_u32 s0, s0, 0x5200
	s_addc_u32 s1, s1, 0
	global_load_short_d16_hi v107, v175, s[0:1] offset:-2048
	global_load_short_d16_hi v115, v175, s[0:1]
	global_load_short_d16_hi v123, v175, s[0:1] offset:2048
	s_add_u32 s0, s100, 0x0
	s_addc_u32 s1, s101, 0
	global_load_short_d16_hi v124, v175, s[0:1]
	global_load_short_d16_hi v125, v175, s[0:1] offset:2048
	s_add_u32 s0, s58, 0x0
	s_addc_u32 s1, s59, 0
	global_load_short_d16_hi v132, v175, s[0:1]
	global_load_short_d16_hi v133, v175, s[0:1] offset:2048
	s_add_u32 s0, s100, 0x1000
	s_addc_u32 s1, s101, 0
	global_load_short_d16_hi v126, v175, s[0:1]
	global_load_short_d16_hi v127, v175, s[0:1] offset:2048
	s_add_u32 s0, s58, 0x1000
	s_addc_u32 s1, s59, 0
	global_load_short_d16_hi v134, v175, s[0:1]
	global_load_short_d16_hi v135, v175, s[0:1] offset:2048
	s_add_u32 s0, s100, 0x2000
	s_addc_u32 s1, s101, 0
	global_load_short_d16_hi v128, v175, s[0:1]
	global_load_short_d16_hi v129, v175, s[0:1] offset:2048
	s_add_u32 s0, s58, 0x2000
	s_addc_u32 s1, s59, 0
	global_load_short_d16_hi v136, v175, s[0:1]
	global_load_short_d16_hi v137, v175, s[0:1] offset:2048
	s_add_u32 s0, s100, 0x3000
	s_addc_u32 s1, s101, 0
	global_load_short_d16_hi v130, v175, s[0:1]
	global_load_short_d16_hi v131, v175, s[0:1] offset:2048
	s_add_u32 s0, s58, 0x3000
	s_addc_u32 s1, s59, 0
	global_load_short_d16_hi v138, v175, s[0:1]
	global_load_short_d16_hi v139, v175, s[0:1] offset:2048
	global_load_dwordx4 v[140:143], v77, s[60:61] offset:-4
	global_load_dwordx4 v[144:147], v77, s[60:61] offset:252
	global_load_dwordx4 v[148:151], v77, s[60:61] offset:508
	global_load_dwordx4 v[152:155], v77, s[60:61] offset:764
	global_load_dwordx4 v[156:159], v77, s[60:61] offset:1020
	global_load_dwordx4 v[160:163], v77, s[60:61] offset:1276
	global_load_dwordx4 v[164:167], v77, s[60:61] offset:1532
	global_load_dwordx4 v[168:171], v77, s[60:61] offset:1788
	s_add_u32 s98, s98, 0xa4000
	s_addc_u32 s99, s99, 0
	s_add_u32 s100, s100, 0x10000
	s_addc_u32 s101, s101, 0
	s_add_u32 s58, s58, 0x10000
	s_addc_u32 s59, s59, 0
	s_add_u32 s60, s60, 0x2000
	s_addc_u32 s61, s61, 0

.Lrwp_go:
	s_setprio 3
	s_and_b32 s0, s30, 1
	s_mul_i32 s0, s0, 0xc200
	s_movk_i32 s33, 0x5200
	v_add_u32_e32 v156, s0, v159
	v_add_u32_e32 v157, s0, v208
	v_add_u32_e32 v158, s0, v209
	s_mov_b32 s60, 0x52000
	s_mov_b32 s61, 0
	ds_read_b128 v[108:111], v156 offset:0
	ds_read_b128 v[112:115], v156 offset:256
	ds_read_b128 v[120:123], v156 offset:1024
	ds_read_b64 v[124:125], v157 offset:0
	ds_read_b128 v[116:119], v156 offset:768
	ds_read_b64 v[126:127], v158 offset:0
	v_mad_u64_u32 v[160:161], s[58:59], v210, s33, v[88:89]
	s_waitcnt lgkmcnt(0)
	ds_read_b128 v[128:131], v156 offset:1552
	ds_read_b128 v[132:135], v156 offset:1808
	ds_read_b128 v[140:143], v156 offset:2576
	ds_read_b64 v[144:145], v157 offset:1552
	ds_read_b128 v[136:139], v156 offset:2320
	ds_read_b64 v[146:147], v158 offset:1552
	v_pk_mul_f32 v[148:149], v[100:101], v[108:109] op_sel_hi:[1,0]
	v_pk_mul_f32 v[150:151], v[100:101], v[112:113] op_sel_hi:[1,0]
	v_pk_fma_f32 v[148:149], v[102:103], v[108:109], v[148:149] op_sel:[0,1,0]
	v_pk_fma_f32 v[150:151], v[102:103], v[112:113], v[150:151] op_sel:[0,1,0]
	v_pk_fma_f32 v[148:149], v[104:105], v[110:111], v[148:149] op_sel_hi:[1,0,1]
	v_pk_fma_f32 v[150:151], v[104:105], v[114:115], v[150:151] op_sel_hi:[1,0,1]
	v_pk_fma_f32 v[148:149], v[106:107], v[110:111], v[148:149] op_sel:[0,1,0]
	v_pk_fma_f32 v[150:151], v[106:107], v[114:115], v[150:151] op_sel:[0,1,0]
	v_pk_fma_f32 v[100:101], v[124:125], v[120:121], v[100:101] op_sel_hi:[1,0,1]
	v_add_f32_dpp v148, v148, v148 quad_perm:[1,0,3,2] row_mask:0xf bank_mask:0xf bound_ctrl:1
	v_add_f32_dpp v149, v149, v149 quad_perm:[1,0,3,2] row_mask:0xf bank_mask:0xf bound_ctrl:1
	v_add_f32_dpp v150, v150, v150 quad_perm:[1,0,3,2] row_mask:0xf bank_mask:0xf bound_ctrl:1
	v_add_f32_dpp v151, v151, v151 quad_perm:[1,0,3,2] row_mask:0xf bank_mask:0xf bound_ctrl:1
	v_pk_fma_f32 v[102:103], v[124:125], v[120:121], v[102:103] op_sel:[0,1,0]
	v_add_f32_dpp v148, v148, v148 quad_perm:[2,3,0,1] row_mask:0xf bank_mask:0xf bound_ctrl:1
	v_add_f32_dpp v149, v149, v149 quad_perm:[2,3,0,1] row_mask:0xf bank_mask:0xf bound_ctrl:1
	v_add_f32_dpp v150, v150, v150 quad_perm:[2,3,0,1] row_mask:0xf bank_mask:0xf bound_ctrl:1
	v_add_f32_dpp v151, v151, v151 quad_perm:[2,3,0,1] row_mask:0xf bank_mask:0xf bound_ctrl:1
	v_pk_fma_f32 v[104:105], v[124:125], v[122:123], v[104:105] op_sel_hi:[1,0,1]
	v_add_f32_dpp v148, v148, v148 row_half_mirror row_mask:0xf bank_mask:0xf bound_ctrl:1
	v_add_f32_dpp v149, v149, v149 row_half_mirror row_mask:0xf bank_mask:0xf bound_ctrl:1
	v_add_f32_dpp v150, v150, v150 row_half_mirror row_mask:0xf bank_mask:0xf bound_ctrl:1
	v_add_f32_dpp v151, v151, v151 row_half_mirror row_mask:0xf bank_mask:0xf bound_ctrl:1
	v_pk_fma_f32 v[106:107], v[124:125], v[122:123], v[106:107] op_sel:[0,1,0]
	v_add_f32_dpp v148, v148, v148 row_mirror row_mask:0xf bank_mask:0xf bound_ctrl:1
	v_add_f32_dpp v149, v149, v149 row_mirror row_mask:0xf bank_mask:0xf bound_ctrl:1
	v_add_f32_dpp v150, v150, v150 row_mirror row_mask:0xf bank_mask:0xf bound_ctrl:1
	v_pk_fma_f32 v[100:101], v[148:149], v[116:117], v[100:101] op_sel_hi:[1,0,1]
	v_pk_fma_f32 v[102:103], v[148:149], v[116:117], v[102:103] op_sel:[0,1,0]
	v_pk_fma_f32 v[104:105], v[148:149], v[118:119], v[104:105] op_sel_hi:[1,0,1]
	v_pk_fma_f32 v[106:107], v[148:149], v[118:119], v[106:107] op_sel:[0,1,0]
	v_add_f32_dpp v151, v151, v151 row_mirror row_mask:0xf bank_mask:0xf bound_ctrl:1
	v_pk_fma_f32 v[152:153], v[148:149], v[126:127], v[150:151] op_sel_hi:[1,0,1]
	v_pk_fma_f32 v[152:153], v[124:125], v[126:127], v[152:153] op_sel:[0,1,0]
	v_cvt_pk_bf16_f32 v154, v152, v153
	s_waitcnt lgkmcnt(0)
	ds_read_b128 v[108:111], v156 offset:3104
	ds_read_b128 v[112:115], v156 offset:3360
	ds_read_b128 v[120:123], v156 offset:4128
	ds_read_b64 v[124:125], v157 offset:3104
	ds_read_b128 v[116:119], v156 offset:3872
	ds_read_b64 v[126:127], v158 offset:3104
	v_mov_b32_e32 v155, v154
	v_pk_mul_f32 v[148:149], v[100:101], v[128:129] op_sel_hi:[1,0]
	v_pk_mul_f32 v[150:151], v[100:101], v[132:133] op_sel_hi:[1,0]
	v_pk_fma_f32 v[148:149], v[102:103], v[128:129], v[148:149] op_sel:[0,1,0]
	v_pk_fma_f32 v[150:151], v[102:103], v[132:133], v[150:151] op_sel:[0,1,0]
	v_pk_fma_f32 v[148:149], v[104:105], v[130:131], v[148:149] op_sel_hi:[1,0,1]
	v_pk_fma_f32 v[150:151], v[104:105], v[134:135], v[150:151] op_sel_hi:[1,0,1]
	v_pk_fma_f32 v[148:149], v[106:107], v[130:131], v[148:149] op_sel:[0,1,0]
	v_pk_fma_f32 v[150:151], v[106:107], v[134:135], v[150:151] op_sel:[0,1,0]
	v_pk_fma_f32 v[100:101], v[144:145], v[140:141], v[100:101] op_sel_hi:[1,0,1]
	v_add_f32_dpp v148, v148, v148 quad_perm:[1,0,3,2] row_mask:0xf bank_mask:0xf bound_ctrl:1
	v_add_f32_dpp v149, v149, v149 quad_perm:[1,0,3,2] row_mask:0xf bank_mask:0xf bound_ctrl:1
	v_add_f32_dpp v150, v150, v150 quad_perm:[1,0,3,2] row_mask:0xf bank_mask:0xf bound_ctrl:1
	v_add_f32_dpp v151, v151, v151 quad_perm:[1,0,3,2] row_mask:0xf bank_mask:0xf bound_ctrl:1
	v_pk_fma_f32 v[102:103], v[144:145], v[140:141], v[102:103] op_sel:[0,1,0]
	v_add_f32_dpp v148, v148, v148 quad_perm:[2,3,0,1] row_mask:0xf bank_mask:0xf bound_ctrl:1
	v_add_f32_dpp v149, v149, v149 quad_perm:[2,3,0,1] row_mask:0xf bank_mask:0xf bound_ctrl:1
	v_add_f32_dpp v150, v150, v150 quad_perm:[2,3,0,1] row_mask:0xf bank_mask:0xf bound_ctrl:1
	v_add_f32_dpp v151, v151, v151 quad_perm:[2,3,0,1] row_mask:0xf bank_mask:0xf bound_ctrl:1
	v_pk_fma_f32 v[104:105], v[144:145], v[142:143], v[104:105] op_sel_hi:[1,0,1]
	v_add_f32_dpp v148, v148, v148 row_half_mirror row_mask:0xf bank_mask:0xf bound_ctrl:1
	v_add_f32_dpp v149, v149, v149 row_half_mirror row_mask:0xf bank_mask:0xf bound_ctrl:1
	v_add_f32_dpp v150, v150, v150 row_half_mirror row_mask:0xf bank_mask:0xf bound_ctrl:1
	v_add_f32_dpp v151, v151, v151 row_half_mirror row_mask:0xf bank_mask:0xf bound_ctrl:1
	v_pk_fma_f32 v[106:107], v[144:145], v[142:143], v[106:107] op_sel:[0,1,0]
	v_add_f32_dpp v148, v148, v148 row_mirror row_mask:0xf bank_mask:0xf bound_ctrl:1
	v_add_f32_dpp v149, v149, v149 row_mirror row_mask:0xf bank_mask:0xf bound_ctrl:1
	v_add_f32_dpp v150, v150, v150 row_mirror row_mask:0xf bank_mask:0xf bound_ctrl:1
	v_pk_fma_f32 v[100:101], v[148:149], v[136:137], v[100:101] op_sel_hi:[1,0,1]
	v_pk_fma_f32 v[102:103], v[148:149], v[136:137], v[102:103] op_sel:[0,1,0]
	v_pk_fma_f32 v[104:105], v[148:149], v[138:139], v[104:105] op_sel_hi:[1,0,1]
	v_pk_fma_f32 v[106:107], v[148:149], v[138:139], v[106:107] op_sel:[0,1,0]
	v_add_f32_dpp v151, v151, v151 row_mirror row_mask:0xf bank_mask:0xf bound_ctrl:1
	v_pk_fma_f32 v[152:153], v[148:149], v[146:147], v[150:151] op_sel_hi:[1,0,1]
	v_pk_fma_f32 v[152:153], v[144:145], v[146:147], v[152:153] op_sel:[0,1,0]
	v_cvt_pk_bf16_f32 v154, v152, v153
	s_waitcnt lgkmcnt(0)
	ds_read_b128 v[128:131], v156 offset:4656
	ds_read_b128 v[132:135], v156 offset:4912
	ds_read_b128 v[140:143], v156 offset:5680
	ds_read_b64 v[144:145], v157 offset:4656
	ds_read_b128 v[136:139], v156 offset:5424
	ds_read_b64 v[146:147], v158 offset:4656
	v_mov_b32_dpp v155, v154 row_shr:1 row_mask:0xf bank_mask:0xf
	v_pk_mul_f32 v[148:149], v[100:101], v[108:109] op_sel_hi:[1,0]
	v_pk_mul_f32 v[150:151], v[100:101], v[112:113] op_sel_hi:[1,0]
	v_pk_fma_f32 v[148:149], v[102:103], v[108:109], v[148:149] op_sel:[0,1,0]
	v_pk_fma_f32 v[150:151], v[102:103], v[112:113], v[150:151] op_sel:[0,1,0]
	v_pk_fma_f32 v[148:149], v[104:105], v[110:111], v[148:149] op_sel_hi:[1,0,1]
	v_pk_fma_f32 v[150:151], v[104:105], v[114:115], v[150:151] op_sel_hi:[1,0,1]
	v_pk_fma_f32 v[148:149], v[106:107], v[110:111], v[148:149] op_sel:[0,1,0]
	v_pk_fma_f32 v[150:151], v[106:107], v[114:115], v[150:151] op_sel:[0,1,0]
	v_pk_fma_f32 v[100:101], v[124:125], v[120:121], v[100:101] op_sel_hi:[1,0,1]
	v_add_f32_dpp v148, v148, v148 quad_perm:[1,0,3,2] row_mask:0xf bank_mask:0xf bound_ctrl:1
	v_add_f32_dpp v149, v149, v149 quad_perm:[1,0,3,2] row_mask:0xf bank_mask:0xf bound_ctrl:1
	v_add_f32_dpp v150, v150, v150 quad_perm:[1,0,3,2] row_mask:0xf bank_mask:0xf bound_ctrl:1
	v_add_f32_dpp v151, v151, v151 quad_perm:[1,0,3,2] row_mask:0xf bank_mask:0xf bound_ctrl:1
	v_pk_fma_f32 v[102:103], v[124:125], v[120:121], v[102:103] op_sel:[0,1,0]
	v_add_f32_dpp v148, v148, v148 quad_perm:[2,3,0,1] row_mask:0xf bank_mask:0xf bound_ctrl:1
	v_add_f32_dpp v149, v149, v149 quad_perm:[2,3,0,1] row_mask:0xf bank_mask:0xf bound_ctrl:1
	v_add_f32_dpp v150, v150, v150 quad_perm:[2,3,0,1] row_mask:0xf bank_mask:0xf bound_ctrl:1
	v_add_f32_dpp v151, v151, v151 quad_perm:[2,3,0,1] row_mask:0xf bank_mask:0xf bound_ctrl:1
	v_pk_fma_f32 v[104:105], v[124:125], v[122:123], v[104:105] op_sel_hi:[1,0,1]
	v_add_f32_dpp v148, v148, v148 row_half_mirror row_mask:0xf bank_mask:0xf bound_ctrl:1
	v_add_f32_dpp v149, v149, v149 row_half_mirror row_mask:0xf bank_mask:0xf bound_ctrl:1
	v_add_f32_dpp v150, v150, v150 row_half_mirror row_mask:0xf bank_mask:0xf bound_ctrl:1
	v_add_f32_dpp v151, v151, v151 row_half_mirror row_mask:0xf bank_mask:0xf bound_ctrl:1
	v_pk_fma_f32 v[106:107], v[124:125], v[122:123], v[106:107] op_sel:[0,1,0]
	v_add_f32_dpp v148, v148, v148 row_mirror row_mask:0xf bank_mask:0xf bound_ctrl:1
	v_add_f32_dpp v149, v149, v149 row_mirror row_mask:0xf bank_mask:0xf bound_ctrl:1
	v_add_f32_dpp v150, v150, v150 row_mirror row_mask:0xf bank_mask:0xf bound_ctrl:1
	v_pk_fma_f32 v[100:101], v[148:149], v[116:117], v[100:101] op_sel_hi:[1,0,1]
	v_pk_fma_f32 v[102:103], v[148:149], v[116:117], v[102:103] op_sel:[0,1,0]
	v_pk_fma_f32 v[104:105], v[148:149], v[118:119], v[104:105] op_sel_hi:[1,0,1]
	v_pk_fma_f32 v[106:107], v[148:149], v[118:119], v[106:107] op_sel:[0,1,0]
	v_add_f32_dpp v151, v151, v151 row_mirror row_mask:0xf bank_mask:0xf bound_ctrl:1
	v_pk_fma_f32 v[152:153], v[148:149], v[126:127], v[150:151] op_sel_hi:[1,0,1]
	v_pk_fma_f32 v[152:153], v[124:125], v[126:127], v[152:153] op_sel:[0,1,0]
	v_cvt_pk_bf16_f32 v154, v152, v153
	s_waitcnt lgkmcnt(0)
	ds_read_b128 v[108:111], v156 offset:6208
	ds_read_b128 v[112:115], v156 offset:6464
	ds_read_b128 v[120:123], v156 offset:7232
	ds_read_b64 v[124:125], v157 offset:6208
	ds_read_b128 v[116:119], v156 offset:6976
	ds_read_b64 v[126:127], v158 offset:6208
	v_mov_b32_dpp v155, v154 row_shr:2 row_mask:0xf bank_mask:0xf
	v_pk_mul_f32 v[148:149], v[100:101], v[128:129] op_sel_hi:[1,0]
	v_pk_mul_f32 v[150:151], v[100:101], v[132:133] op_sel_hi:[1,0]
	v_pk_fma_f32 v[148:149], v[102:103], v[128:129], v[148:149] op_sel:[0,1,0]
	v_pk_fma_f32 v[150:151], v[102:103], v[132:133], v[150:151] op_sel:[0,1,0]
	v_pk_fma_f32 v[148:149], v[104:105], v[130:131], v[148:149] op_sel_hi:[1,0,1]
	v_pk_fma_f32 v[150:151], v[104:105], v[134:135], v[150:151] op_sel_hi:[1,0,1]
	v_pk_fma_f32 v[148:149], v[106:107], v[130:131], v[148:149] op_sel:[0,1,0]
	v_pk_fma_f32 v[150:151], v[106:107], v[134:135], v[150:151] op_sel:[0,1,0]
	v_pk_fma_f32 v[100:101], v[144:145], v[140:141], v[100:101] op_sel_hi:[1,0,1]
	v_add_f32_dpp v148, v148, v148 quad_perm:[1,0,3,2] row_mask:0xf bank_mask:0xf bound_ctrl:1
	v_add_f32_dpp v149, v149, v149 quad_perm:[1,0,3,2] row_mask:0xf bank_mask:0xf bound_ctrl:1
	v_add_f32_dpp v150, v150, v150 quad_perm:[1,0,3,2] row_mask:0xf bank_mask:0xf bound_ctrl:1
	v_add_f32_dpp v151, v151, v151 quad_perm:[1,0,3,2] row_mask:0xf bank_mask:0xf bound_ctrl:1
	v_pk_fma_f32 v[102:103], v[144:145], v[140:141], v[102:103] op_sel:[0,1,0]
	v_add_f32_dpp v148, v148, v148 quad_perm:[2,3,0,1] row_mask:0xf bank_mask:0xf bound_ctrl:1
	v_add_f32_dpp v149, v149, v149 quad_perm:[2,3,0,1] row_mask:0xf bank_mask:0xf bound_ctrl:1
	v_add_f32_dpp v150, v150, v150 quad_perm:[2,3,0,1] row_mask:0xf bank_mask:0xf bound_ctrl:1
	v_add_f32_dpp v151, v151, v151 quad_perm:[2,3,0,1] row_mask:0xf bank_mask:0xf bound_ctrl:1
	v_pk_fma_f32 v[104:105], v[144:145], v[142:143], v[104:105] op_sel_hi:[1,0,1]
	v_add_f32_dpp v148, v148, v148 row_half_mirror row_mask:0xf bank_mask:0xf bound_ctrl:1
	v_add_f32_dpp v149, v149, v149 row_half_mirror row_mask:0xf bank_mask:0xf bound_ctrl:1
	v_add_f32_dpp v150, v150, v150 row_half_mirror row_mask:0xf bank_mask:0xf bound_ctrl:1
	v_add_f32_dpp v151, v151, v151 row_half_mirror row_mask:0xf bank_mask:0xf bound_ctrl:1
	v_pk_fma_f32 v[106:107], v[144:145], v[142:143], v[106:107] op_sel:[0,1,0]
	v_add_f32_dpp v148, v148, v148 row_mirror row_mask:0xf bank_mask:0xf bound_ctrl:1
	v_add_f32_dpp v149, v149, v149 row_mirror row_mask:0xf bank_mask:0xf bound_ctrl:1
	v_add_f32_dpp v150, v150, v150 row_mirror row_mask:0xf bank_mask:0xf bound_ctrl:1
	v_pk_fma_f32 v[100:101], v[148:149], v[136:137], v[100:101] op_sel_hi:[1,0,1]
	v_pk_fma_f32 v[102:103], v[148:149], v[136:137], v[102:103] op_sel:[0,1,0]
	v_pk_fma_f32 v[104:105], v[148:149], v[138:139], v[104:105] op_sel_hi:[1,0,1]
	v_pk_fma_f32 v[106:107], v[148:149], v[138:139], v[106:107] op_sel:[0,1,0]
	v_add_f32_dpp v151, v151, v151 row_mirror row_mask:0xf bank_mask:0xf bound_ctrl:1
	v_pk_fma_f32 v[152:153], v[148:149], v[146:147], v[150:151] op_sel_hi:[1,0,1]
	v_pk_fma_f32 v[152:153], v[144:145], v[146:147], v[152:153] op_sel:[0,1,0]
	v_cvt_pk_bf16_f32 v154, v152, v153
	s_waitcnt lgkmcnt(0)
	ds_read_b128 v[128:131], v156 offset:7760
	ds_read_b128 v[132:135], v156 offset:8016
	ds_read_b128 v[140:143], v156 offset:8784
	ds_read_b64 v[144:145], v157 offset:7760
	ds_read_b128 v[136:139], v156 offset:8528
	ds_read_b64 v[146:147], v158 offset:7760
	v_mov_b32_dpp v155, v154 row_shr:3 row_mask:0xf bank_mask:0xf
	v_pk_mul_f32 v[148:149], v[100:101], v[108:109] op_sel_hi:[1,0]
	v_pk_mul_f32 v[150:151], v[100:101], v[112:113] op_sel_hi:[1,0]
	v_pk_fma_f32 v[148:149], v[102:103], v[108:109], v[148:149] op_sel:[0,1,0]
	v_pk_fma_f32 v[150:151], v[102:103], v[112:113], v[150:151] op_sel:[0,1,0]
	v_pk_fma_f32 v[148:149], v[104:105], v[110:111], v[148:149] op_sel_hi:[1,0,1]
	v_pk_fma_f32 v[150:151], v[104:105], v[114:115], v[150:151] op_sel_hi:[1,0,1]
	v_pk_fma_f32 v[148:149], v[106:107], v[110:111], v[148:149] op_sel:[0,1,0]
	v_pk_fma_f32 v[150:151], v[106:107], v[114:115], v[150:151] op_sel:[0,1,0]
	v_pk_fma_f32 v[100:101], v[124:125], v[120:121], v[100:101] op_sel_hi:[1,0,1]
	v_add_f32_dpp v148, v148, v148 quad_perm:[1,0,3,2] row_mask:0xf bank_mask:0xf bound_ctrl:1
	v_add_f32_dpp v149, v149, v149 quad_perm:[1,0,3,2] row_mask:0xf bank_mask:0xf bound_ctrl:1
	v_add_f32_dpp v150, v150, v150 quad_perm:[1,0,3,2] row_mask:0xf bank_mask:0xf bound_ctrl:1
	v_add_f32_dpp v151, v151, v151 quad_perm:[1,0,3,2] row_mask:0xf bank_mask:0xf bound_ctrl:1
	v_pk_fma_f32 v[102:103], v[124:125], v[120:121], v[102:103] op_sel:[0,1,0]
	v_add_f32_dpp v148, v148, v148 quad_perm:[2,3,0,1] row_mask:0xf bank_mask:0xf bound_ctrl:1
	v_add_f32_dpp v149, v149, v149 quad_perm:[2,3,0,1] row_mask:0xf bank_mask:0xf bound_ctrl:1
	v_add_f32_dpp v150, v150, v150 quad_perm:[2,3,0,1] row_mask:0xf bank_mask:0xf bound_ctrl:1
	v_add_f32_dpp v151, v151, v151 quad_perm:[2,3,0,1] row_mask:0xf bank_mask:0xf bound_ctrl:1
	v_pk_fma_f32 v[104:105], v[124:125], v[122:123], v[104:105] op_sel_hi:[1,0,1]
	v_add_f32_dpp v148, v148, v148 row_half_mirror row_mask:0xf bank_mask:0xf bound_ctrl:1
	v_add_f32_dpp v149, v149, v149 row_half_mirror row_mask:0xf bank_mask:0xf bound_ctrl:1
	v_add_f32_dpp v150, v150, v150 row_half_mirror row_mask:0xf bank_mask:0xf bound_ctrl:1
	v_add_f32_dpp v151, v151, v151 row_half_mirror row_mask:0xf bank_mask:0xf bound_ctrl:1
	v_pk_fma_f32 v[106:107], v[124:125], v[122:123], v[106:107] op_sel:[0,1,0]
	v_add_f32_dpp v148, v148, v148 row_mirror row_mask:0xf bank_mask:0xf bound_ctrl:1
	v_add_f32_dpp v149, v149, v149 row_mirror row_mask:0xf bank_mask:0xf bound_ctrl:1
	v_add_f32_dpp v150, v150, v150 row_mirror row_mask:0xf bank_mask:0xf bound_ctrl:1
	v_pk_fma_f32 v[100:101], v[148:149], v[116:117], v[100:101] op_sel_hi:[1,0,1]
	v_pk_fma_f32 v[102:103], v[148:149], v[116:117], v[102:103] op_sel:[0,1,0]
	v_pk_fma_f32 v[104:105], v[148:149], v[118:119], v[104:105] op_sel_hi:[1,0,1]
	v_pk_fma_f32 v[106:107], v[148:149], v[118:119], v[106:107] op_sel:[0,1,0]
	v_add_f32_dpp v151, v151, v151 row_mirror row_mask:0xf bank_mask:0xf bound_ctrl:1
	v_pk_fma_f32 v[152:153], v[148:149], v[126:127], v[150:151] op_sel_hi:[1,0,1]
	v_pk_fma_f32 v[152:153], v[124:125], v[126:127], v[152:153] op_sel:[0,1,0]
	v_cvt_pk_bf16_f32 v154, v152, v153
	s_waitcnt lgkmcnt(0)
	ds_read_b128 v[108:111], v156 offset:9312
	ds_read_b128 v[112:115], v156 offset:9568
	ds_read_b128 v[120:123], v156 offset:10336
	ds_read_b64 v[124:125], v157 offset:9312
	ds_read_b128 v[116:119], v156 offset:10080
	ds_read_b64 v[126:127], v158 offset:9312
	v_mov_b32_dpp v155, v154 row_shr:4 row_mask:0xf bank_mask:0xf
	v_pk_mul_f32 v[148:149], v[100:101], v[128:129] op_sel_hi:[1,0]
	v_pk_mul_f32 v[150:151], v[100:101], v[132:133] op_sel_hi:[1,0]
	v_pk_fma_f32 v[148:149], v[102:103], v[128:129], v[148:149] op_sel:[0,1,0]
	v_pk_fma_f32 v[150:151], v[102:103], v[132:133], v[150:151] op_sel:[0,1,0]
	v_pk_fma_f32 v[148:149], v[104:105], v[130:131], v[148:149] op_sel_hi:[1,0,1]
	v_pk_fma_f32 v[150:151], v[104:105], v[134:135], v[150:151] op_sel_hi:[1,0,1]
	v_pk_fma_f32 v[148:149], v[106:107], v[130:131], v[148:149] op_sel:[0,1,0]
	v_pk_fma_f32 v[150:151], v[106:107], v[134:135], v[150:151] op_sel:[0,1,0]
	v_pk_fma_f32 v[100:101], v[144:145], v[140:141], v[100:101] op_sel_hi:[1,0,1]
	v_add_f32_dpp v148, v148, v148 quad_perm:[1,0,3,2] row_mask:0xf bank_mask:0xf bound_ctrl:1
	v_add_f32_dpp v149, v149, v149 quad_perm:[1,0,3,2] row_mask:0xf bank_mask:0xf bound_ctrl:1
	v_add_f32_dpp v150, v150, v150 quad_perm:[1,0,3,2] row_mask:0xf bank_mask:0xf bound_ctrl:1
	v_add_f32_dpp v151, v151, v151 quad_perm:[1,0,3,2] row_mask:0xf bank_mask:0xf bound_ctrl:1
	v_pk_fma_f32 v[102:103], v[144:145], v[140:141], v[102:103] op_sel:[0,1,0]
	v_add_f32_dpp v148, v148, v148 quad_perm:[2,3,0,1] row_mask:0xf bank_mask:0xf bound_ctrl:1
	v_add_f32_dpp v149, v149, v149 quad_perm:[2,3,0,1] row_mask:0xf bank_mask:0xf bound_ctrl:1
	v_add_f32_dpp v150, v150, v150 quad_perm:[2,3,0,1] row_mask:0xf bank_mask:0xf bound_ctrl:1
	v_add_f32_dpp v151, v151, v151 quad_perm:[2,3,0,1] row_mask:0xf bank_mask:0xf bound_ctrl:1
	v_pk_fma_f32 v[104:105], v[144:145], v[142:143], v[104:105] op_sel_hi:[1,0,1]
	v_add_f32_dpp v148, v148, v148 row_half_mirror row_mask:0xf bank_mask:0xf bound_ctrl:1
	v_add_f32_dpp v149, v149, v149 row_half_mirror row_mask:0xf bank_mask:0xf bound_ctrl:1
	v_add_f32_dpp v150, v150, v150 row_half_mirror row_mask:0xf bank_mask:0xf bound_ctrl:1
	v_add_f32_dpp v151, v151, v151 row_half_mirror row_mask:0xf bank_mask:0xf bound_ctrl:1
	v_pk_fma_f32 v[106:107], v[144:145], v[142:143], v[106:107] op_sel:[0,1,0]
	v_add_f32_dpp v148, v148, v148 row_mirror row_mask:0xf bank_mask:0xf bound_ctrl:1
	v_add_f32_dpp v149, v149, v149 row_mirror row_mask:0xf bank_mask:0xf bound_ctrl:1
	v_add_f32_dpp v150, v150, v150 row_mirror row_mask:0xf bank_mask:0xf bound_ctrl:1
	v_pk_fma_f32 v[100:101], v[148:149], v[136:137], v[100:101] op_sel_hi:[1,0,1]
	v_pk_fma_f32 v[102:103], v[148:149], v[136:137], v[102:103] op_sel:[0,1,0]
	v_pk_fma_f32 v[104:105], v[148:149], v[138:139], v[104:105] op_sel_hi:[1,0,1]
	v_pk_fma_f32 v[106:107], v[148:149], v[138:139], v[106:107] op_sel:[0,1,0]
	v_add_f32_dpp v151, v151, v151 row_mirror row_mask:0xf bank_mask:0xf bound_ctrl:1
	v_pk_fma_f32 v[152:153], v[148:149], v[146:147], v[150:151] op_sel_hi:[1,0,1]
	v_pk_fma_f32 v[152:153], v[144:145], v[146:147], v[152:153] op_sel:[0,1,0]
	v_cvt_pk_bf16_f32 v154, v152, v153
	s_waitcnt lgkmcnt(0)
	ds_read_b128 v[128:131], v156 offset:10864
	ds_read_b128 v[132:135], v156 offset:11120
	ds_read_b128 v[140:143], v156 offset:11888
	ds_read_b64 v[144:145], v157 offset:10864
	ds_read_b128 v[136:139], v156 offset:11632
	ds_read_b64 v[146:147], v158 offset:10864
	v_mov_b32_dpp v155, v154 row_shr:5 row_mask:0xf bank_mask:0xf
	v_pk_mul_f32 v[148:149], v[100:101], v[108:109] op_sel_hi:[1,0]
	v_pk_mul_f32 v[150:151], v[100:101], v[112:113] op_sel_hi:[1,0]
	v_pk_fma_f32 v[148:149], v[102:103], v[108:109], v[148:149] op_sel:[0,1,0]
	v_pk_fma_f32 v[150:151], v[102:103], v[112:113], v[150:151] op_sel:[0,1,0]
	v_pk_fma_f32 v[148:149], v[104:105], v[110:111], v[148:149] op_sel_hi:[1,0,1]
	v_pk_fma_f32 v[150:151], v[104:105], v[114:115], v[150:151] op_sel_hi:[1,0,1]
	v_pk_fma_f32 v[148:149], v[106:107], v[110:111], v[148:149] op_sel:[0,1,0]
	v_pk_fma_f32 v[150:151], v[106:107], v[114:115], v[150:151] op_sel:[0,1,0]
	v_pk_fma_f32 v[100:101], v[124:125], v[120:121], v[100:101] op_sel_hi:[1,0,1]
	v_add_f32_dpp v148, v148, v148 quad_perm:[1,0,3,2] row_mask:0xf bank_mask:0xf bound_ctrl:1
	v_add_f32_dpp v149, v149, v149 quad_perm:[1,0,3,2] row_mask:0xf bank_mask:0xf bound_ctrl:1
	v_add_f32_dpp v150, v150, v150 quad_perm:[1,0,3,2] row_mask:0xf bank_mask:0xf bound_ctrl:1
	v_add_f32_dpp v151, v151, v151 quad_perm:[1,0,3,2] row_mask:0xf bank_mask:0xf bound_ctrl:1
	v_pk_fma_f32 v[102:103], v[124:125], v[120:121], v[102:103] op_sel:[0,1,0]
	v_add_f32_dpp v148, v148, v148 quad_perm:[2,3,0,1] row_mask:0xf bank_mask:0xf bound_ctrl:1
	v_add_f32_dpp v149, v149, v149 quad_perm:[2,3,0,1] row_mask:0xf bank_mask:0xf bound_ctrl:1
	v_add_f32_dpp v150, v150, v150 quad_perm:[2,3,0,1] row_mask:0xf bank_mask:0xf bound_ctrl:1
	v_add_f32_dpp v151, v151, v151 quad_perm:[2,3,0,1] row_mask:0xf bank_mask:0xf bound_ctrl:1
	v_pk_fma_f32 v[104:105], v[124:125], v[122:123], v[104:105] op_sel_hi:[1,0,1]
	v_add_f32_dpp v148, v148, v148 row_half_mirror row_mask:0xf bank_mask:0xf bound_ctrl:1
	v_add_f32_dpp v149, v149, v149 row_half_mirror row_mask:0xf bank_mask:0xf bound_ctrl:1
	v_add_f32_dpp v150, v150, v150 row_half_mirror row_mask:0xf bank_mask:0xf bound_ctrl:1
	v_add_f32_dpp v151, v151, v151 row_half_mirror row_mask:0xf bank_mask:0xf bound_ctrl:1
	v_pk_fma_f32 v[106:107], v[124:125], v[122:123], v[106:107] op_sel:[0,1,0]
	v_add_f32_dpp v148, v148, v148 row_mirror row_mask:0xf bank_mask:0xf bound_ctrl:1
	v_add_f32_dpp v149, v149, v149 row_mirror row_mask:0xf bank_mask:0xf bound_ctrl:1
	v_add_f32_dpp v150, v150, v150 row_mirror row_mask:0xf bank_mask:0xf bound_ctrl:1
	v_pk_fma_f32 v[100:101], v[148:149], v[116:117], v[100:101] op_sel_hi:[1,0,1]
	v_pk_fma_f32 v[102:103], v[148:149], v[116:117], v[102:103] op_sel:[0,1,0]
	v_pk_fma_f32 v[104:105], v[148:149], v[118:119], v[104:105] op_sel_hi:[1,0,1]
	v_pk_fma_f32 v[106:107], v[148:149], v[118:119], v[106:107] op_sel:[0,1,0]
	v_add_f32_dpp v151, v151, v151 row_mirror row_mask:0xf bank_mask:0xf bound_ctrl:1
	v_pk_fma_f32 v[152:153], v[148:149], v[126:127], v[150:151] op_sel_hi:[1,0,1]
	v_pk_fma_f32 v[152:153], v[124:125], v[126:127], v[152:153] op_sel:[0,1,0]
	v_cvt_pk_bf16_f32 v154, v152, v153
	s_waitcnt lgkmcnt(0)
	ds_read_b128 v[108:111], v156 offset:12416
	ds_read_b128 v[112:115], v156 offset:12672
	ds_read_b128 v[120:123], v156 offset:13440
	ds_read_b64 v[124:125], v157 offset:12416
	ds_read_b128 v[116:119], v156 offset:13184
	ds_read_b64 v[126:127], v158 offset:12416
	ds_read_b128 v[204:207], v156 offset:11376
	v_mov_b32_dpp v155, v154 row_shr:6 row_mask:0xf bank_mask:0xf
	v_pk_mul_f32 v[148:149], v[100:101], v[128:129] op_sel_hi:[1,0]
	v_pk_mul_f32 v[150:151], v[100:101], v[132:133] op_sel_hi:[1,0]
	v_pk_fma_f32 v[148:149], v[102:103], v[128:129], v[148:149] op_sel:[0,1,0]
	v_pk_fma_f32 v[150:151], v[102:103], v[132:133], v[150:151] op_sel:[0,1,0]
	v_pk_fma_f32 v[148:149], v[104:105], v[130:131], v[148:149] op_sel_hi:[1,0,1]
	v_pk_fma_f32 v[150:151], v[104:105], v[134:135], v[150:151] op_sel_hi:[1,0,1]
	v_pk_fma_f32 v[148:149], v[106:107], v[130:131], v[148:149] op_sel:[0,1,0]
	v_pk_fma_f32 v[150:151], v[106:107], v[134:135], v[150:151] op_sel:[0,1,0]
	v_pk_fma_f32 v[100:101], v[144:145], v[140:141], v[100:101] op_sel_hi:[1,0,1]
	v_add_f32_dpp v148, v148, v148 quad_perm:[1,0,3,2] row_mask:0xf bank_mask:0xf bound_ctrl:1
	v_add_f32_dpp v149, v149, v149 quad_perm:[1,0,3,2] row_mask:0xf bank_mask:0xf bound_ctrl:1
	v_add_f32_dpp v150, v150, v150 quad_perm:[1,0,3,2] row_mask:0xf bank_mask:0xf bound_ctrl:1
	v_add_f32_dpp v151, v151, v151 quad_perm:[1,0,3,2] row_mask:0xf bank_mask:0xf bound_ctrl:1
	v_pk_fma_f32 v[102:103], v[144:145], v[140:141], v[102:103] op_sel:[0,1,0]
	v_add_f32_dpp v148, v148, v148 quad_perm:[2,3,0,1] row_mask:0xf bank_mask:0xf bound_ctrl:1
	v_add_f32_dpp v149, v149, v149 quad_perm:[2,3,0,1] row_mask:0xf bank_mask:0xf bound_ctrl:1
	v_add_f32_dpp v150, v150, v150 quad_perm:[2,3,0,1] row_mask:0xf bank_mask:0xf bound_ctrl:1
	v_add_f32_dpp v151, v151, v151 quad_perm:[2,3,0,1] row_mask:0xf bank_mask:0xf bound_ctrl:1
	v_pk_fma_f32 v[104:105], v[144:145], v[142:143], v[104:105] op_sel_hi:[1,0,1]
	v_add_f32_dpp v148, v148, v148 row_half_mirror row_mask:0xf bank_mask:0xf bound_ctrl:1
	v_add_f32_dpp v149, v149, v149 row_half_mirror row_mask:0xf bank_mask:0xf bound_ctrl:1
	v_add_f32_dpp v150, v150, v150 row_half_mirror row_mask:0xf bank_mask:0xf bound_ctrl:1
	v_add_f32_dpp v151, v151, v151 row_half_mirror row_mask:0xf bank_mask:0xf bound_ctrl:1
	v_pk_fma_f32 v[106:107], v[144:145], v[142:143], v[106:107] op_sel:[0,1,0]
	v_add_f32_dpp v148, v148, v148 row_mirror row_mask:0xf bank_mask:0xf bound_ctrl:1
	v_add_f32_dpp v149, v149, v149 row_mirror row_mask:0xf bank_mask:0xf bound_ctrl:1
	v_add_f32_dpp v150, v150, v150 row_mirror row_mask:0xf bank_mask:0xf bound_ctrl:1
	v_pk_fma_f32 v[100:101], v[148:149], v[136:137], v[100:101] op_sel_hi:[1,0,1]
	v_pk_fma_f32 v[102:103], v[148:149], v[136:137], v[102:103] op_sel:[0,1,0]
	v_pk_fma_f32 v[104:105], v[148:149], v[138:139], v[104:105] op_sel_hi:[1,0,1]
	v_pk_fma_f32 v[106:107], v[148:149], v[138:139], v[106:107] op_sel:[0,1,0]
	v_add_f32_dpp v151, v151, v151 row_mirror row_mask:0xf bank_mask:0xf bound_ctrl:1
	v_pk_fma_f32 v[152:153], v[148:149], v[146:147], v[150:151] op_sel_hi:[1,0,1]
	v_pk_fma_f32 v[152:153], v[144:145], v[146:147], v[152:153] op_sel:[0,1,0]
	v_cvt_pk_bf16_f32 v154, v152, v153
	s_waitcnt lgkmcnt(0)
	v_pk_mul_f32 v[100:101], v[100:101], v[204:205] op_sel_hi:[1,0]
	v_pk_mul_f32 v[102:103], v[102:103], v[204:205] op_sel:[0,1]
	v_pk_mul_f32 v[104:105], v[104:105], v[206:207] op_sel_hi:[1,0]
	v_pk_mul_f32 v[106:107], v[106:107], v[206:207] op_sel:[0,1]
	ds_read_b128 v[128:131], v156 offset:13968
	ds_read_b128 v[132:135], v156 offset:14224
	ds_read_b128 v[140:143], v156 offset:14992
	ds_read_b64 v[144:145], v157 offset:13968
	ds_read_b128 v[136:139], v156 offset:14736
	ds_read_b64 v[146:147], v158 offset:13968
	v_mov_b32_dpp v155, v154 row_shr:7 row_mask:0xf bank_mask:0xf
	v_pk_mul_f32 v[148:149], v[100:101], v[108:109] op_sel_hi:[1,0]
	v_pk_mul_f32 v[150:151], v[100:101], v[112:113] op_sel_hi:[1,0]
	v_pk_fma_f32 v[148:149], v[102:103], v[108:109], v[148:149] op_sel:[0,1,0]
	v_pk_fma_f32 v[150:151], v[102:103], v[112:113], v[150:151] op_sel:[0,1,0]
	v_pk_fma_f32 v[148:149], v[104:105], v[110:111], v[148:149] op_sel_hi:[1,0,1]
	v_pk_fma_f32 v[150:151], v[104:105], v[114:115], v[150:151] op_sel_hi:[1,0,1]
	v_pk_fma_f32 v[148:149], v[106:107], v[110:111], v[148:149] op_sel:[0,1,0]
	v_pk_fma_f32 v[150:151], v[106:107], v[114:115], v[150:151] op_sel:[0,1,0]
	v_pk_fma_f32 v[100:101], v[124:125], v[120:121], v[100:101] op_sel_hi:[1,0,1]
	v_add_f32_dpp v148, v148, v148 quad_perm:[1,0,3,2] row_mask:0xf bank_mask:0xf bound_ctrl:1
	v_add_f32_dpp v149, v149, v149 quad_perm:[1,0,3,2] row_mask:0xf bank_mask:0xf bound_ctrl:1
	v_add_f32_dpp v150, v150, v150 quad_perm:[1,0,3,2] row_mask:0xf bank_mask:0xf bound_ctrl:1
	v_add_f32_dpp v151, v151, v151 quad_perm:[1,0,3,2] row_mask:0xf bank_mask:0xf bound_ctrl:1
	v_pk_fma_f32 v[102:103], v[124:125], v[120:121], v[102:103] op_sel:[0,1,0]
	v_add_f32_dpp v148, v148, v148 quad_perm:[2,3,0,1] row_mask:0xf bank_mask:0xf bound_ctrl:1
	v_add_f32_dpp v149, v149, v149 quad_perm:[2,3,0,1] row_mask:0xf bank_mask:0xf bound_ctrl:1
	v_add_f32_dpp v150, v150, v150 quad_perm:[2,3,0,1] row_mask:0xf bank_mask:0xf bound_ctrl:1
	v_add_f32_dpp v151, v151, v151 quad_perm:[2,3,0,1] row_mask:0xf bank_mask:0xf bound_ctrl:1
	v_pk_fma_f32 v[104:105], v[124:125], v[122:123], v[104:105] op_sel_hi:[1,0,1]
	v_add_f32_dpp v148, v148, v148 row_half_mirror row_mask:0xf bank_mask:0xf bound_ctrl:1
	v_add_f32_dpp v149, v149, v149 row_half_mirror row_mask:0xf bank_mask:0xf bound_ctrl:1
	v_add_f32_dpp v150, v150, v150 row_half_mirror row_mask:0xf bank_mask:0xf bound_ctrl:1
	v_add_f32_dpp v151, v151, v151 row_half_mirror row_mask:0xf bank_mask:0xf bound_ctrl:1
	v_pk_fma_f32 v[106:107], v[124:125], v[122:123], v[106:107] op_sel:[0,1,0]
	v_add_f32_dpp v148, v148, v148 row_mirror row_mask:0xf bank_mask:0xf bound_ctrl:1
	v_add_f32_dpp v149, v149, v149 row_mirror row_mask:0xf bank_mask:0xf bound_ctrl:1
	v_add_f32_dpp v150, v150, v150 row_mirror row_mask:0xf bank_mask:0xf bound_ctrl:1
	v_pk_fma_f32 v[100:101], v[148:149], v[116:117], v[100:101] op_sel_hi:[1,0,1]
	v_pk_fma_f32 v[102:103], v[148:149], v[116:117], v[102:103] op_sel:[0,1,0]
	v_pk_fma_f32 v[104:105], v[148:149], v[118:119], v[104:105] op_sel_hi:[1,0,1]
	v_pk_fma_f32 v[106:107], v[148:149], v[118:119], v[106:107] op_sel:[0,1,0]
	v_add_f32_dpp v151, v151, v151 row_mirror row_mask:0xf bank_mask:0xf bound_ctrl:1
	v_pk_fma_f32 v[152:153], v[148:149], v[126:127], v[150:151] op_sel_hi:[1,0,1]
	v_pk_fma_f32 v[152:153], v[124:125], v[126:127], v[152:153] op_sel:[0,1,0]
	v_cvt_pk_bf16_f32 v154, v152, v153
	s_waitcnt lgkmcnt(0)
	ds_read_b128 v[108:111], v156 offset:15520
	ds_read_b128 v[112:115], v156 offset:15776
	ds_read_b128 v[120:123], v156 offset:16544
	ds_read_b64 v[124:125], v157 offset:15520
	ds_read_b128 v[116:119], v156 offset:16288
	ds_read_b64 v[126:127], v158 offset:15520
	v_mov_b32_dpp v155, v154 row_shr:8 row_mask:0xf bank_mask:0xf
	v_pk_mul_f32 v[148:149], v[100:101], v[128:129] op_sel_hi:[1,0]
	v_pk_mul_f32 v[150:151], v[100:101], v[132:133] op_sel_hi:[1,0]
	v_pk_fma_f32 v[148:149], v[102:103], v[128:129], v[148:149] op_sel:[0,1,0]
	v_pk_fma_f32 v[150:151], v[102:103], v[132:133], v[150:151] op_sel:[0,1,0]
	v_pk_fma_f32 v[148:149], v[104:105], v[130:131], v[148:149] op_sel_hi:[1,0,1]
	v_pk_fma_f32 v[150:151], v[104:105], v[134:135], v[150:151] op_sel_hi:[1,0,1]
	v_pk_fma_f32 v[148:149], v[106:107], v[130:131], v[148:149] op_sel:[0,1,0]
	v_pk_fma_f32 v[150:151], v[106:107], v[134:135], v[150:151] op_sel:[0,1,0]
	v_pk_fma_f32 v[100:101], v[144:145], v[140:141], v[100:101] op_sel_hi:[1,0,1]
	v_add_f32_dpp v148, v148, v148 quad_perm:[1,0,3,2] row_mask:0xf bank_mask:0xf bound_ctrl:1
	v_add_f32_dpp v149, v149, v149 quad_perm:[1,0,3,2] row_mask:0xf bank_mask:0xf bound_ctrl:1
	v_add_f32_dpp v150, v150, v150 quad_perm:[1,0,3,2] row_mask:0xf bank_mask:0xf bound_ctrl:1
	v_add_f32_dpp v151, v151, v151 quad_perm:[1,0,3,2] row_mask:0xf bank_mask:0xf bound_ctrl:1
	v_pk_fma_f32 v[102:103], v[144:145], v[140:141], v[102:103] op_sel:[0,1,0]
	v_add_f32_dpp v148, v148, v148 quad_perm:[2,3,0,1] row_mask:0xf bank_mask:0xf bound_ctrl:1
	v_add_f32_dpp v149, v149, v149 quad_perm:[2,3,0,1] row_mask:0xf bank_mask:0xf bound_ctrl:1
	v_add_f32_dpp v150, v150, v150 quad_perm:[2,3,0,1] row_mask:0xf bank_mask:0xf bound_ctrl:1
	v_add_f32_dpp v151, v151, v151 quad_perm:[2,3,0,1] row_mask:0xf bank_mask:0xf bound_ctrl:1
	v_pk_fma_f32 v[104:105], v[144:145], v[142:143], v[104:105] op_sel_hi:[1,0,1]
	v_add_f32_dpp v148, v148, v148 row_half_mirror row_mask:0xf bank_mask:0xf bound_ctrl:1
	v_add_f32_dpp v149, v149, v149 row_half_mirror row_mask:0xf bank_mask:0xf bound_ctrl:1
	v_add_f32_dpp v150, v150, v150 row_half_mirror row_mask:0xf bank_mask:0xf bound_ctrl:1
	v_add_f32_dpp v151, v151, v151 row_half_mirror row_mask:0xf bank_mask:0xf bound_ctrl:1
	v_pk_fma_f32 v[106:107], v[144:145], v[142:143], v[106:107] op_sel:[0,1,0]
	v_add_f32_dpp v148, v148, v148 row_mirror row_mask:0xf bank_mask:0xf bound_ctrl:1
	v_add_f32_dpp v149, v149, v149 row_mirror row_mask:0xf bank_mask:0xf bound_ctrl:1
	v_add_f32_dpp v150, v150, v150 row_mirror row_mask:0xf bank_mask:0xf bound_ctrl:1
	v_pk_fma_f32 v[100:101], v[148:149], v[136:137], v[100:101] op_sel_hi:[1,0,1]
	v_pk_fma_f32 v[102:103], v[148:149], v[136:137], v[102:103] op_sel:[0,1,0]
	v_pk_fma_f32 v[104:105], v[148:149], v[138:139], v[104:105] op_sel_hi:[1,0,1]
	v_pk_fma_f32 v[106:107], v[148:149], v[138:139], v[106:107] op_sel:[0,1,0]
	v_add_f32_dpp v151, v151, v151 row_mirror row_mask:0xf bank_mask:0xf bound_ctrl:1
	v_pk_fma_f32 v[152:153], v[148:149], v[146:147], v[150:151] op_sel_hi:[1,0,1]
	v_pk_fma_f32 v[152:153], v[144:145], v[146:147], v[152:153] op_sel:[0,1,0]
	v_cvt_pk_bf16_f32 v154, v152, v153
	s_waitcnt lgkmcnt(0)
	ds_read_b128 v[128:131], v156 offset:17072
	ds_read_b128 v[132:135], v156 offset:17328
	ds_read_b128 v[140:143], v156 offset:18096
	ds_read_b64 v[144:145], v157 offset:17072
	ds_read_b128 v[136:139], v156 offset:17840
	ds_read_b64 v[146:147], v158 offset:17072
	v_mov_b32_dpp v155, v154 row_shr:9 row_mask:0xf bank_mask:0xf
	v_pk_mul_f32 v[148:149], v[100:101], v[108:109] op_sel_hi:[1,0]
	v_pk_mul_f32 v[150:151], v[100:101], v[112:113] op_sel_hi:[1,0]
	v_pk_fma_f32 v[148:149], v[102:103], v[108:109], v[148:149] op_sel:[0,1,0]
	v_pk_fma_f32 v[150:151], v[102:103], v[112:113], v[150:151] op_sel:[0,1,0]
	v_pk_fma_f32 v[148:149], v[104:105], v[110:111], v[148:149] op_sel_hi:[1,0,1]
	v_pk_fma_f32 v[150:151], v[104:105], v[114:115], v[150:151] op_sel_hi:[1,0,1]
	v_pk_fma_f32 v[148:149], v[106:107], v[110:111], v[148:149] op_sel:[0,1,0]
	v_pk_fma_f32 v[150:151], v[106:107], v[114:115], v[150:151] op_sel:[0,1,0]
	v_pk_fma_f32 v[100:101], v[124:125], v[120:121], v[100:101] op_sel_hi:[1,0,1]
	v_add_f32_dpp v148, v148, v148 quad_perm:[1,0,3,2] row_mask:0xf bank_mask:0xf bound_ctrl:1
	v_add_f32_dpp v149, v149, v149 quad_perm:[1,0,3,2] row_mask:0xf bank_mask:0xf bound_ctrl:1
	v_add_f32_dpp v150, v150, v150 quad_perm:[1,0,3,2] row_mask:0xf bank_mask:0xf bound_ctrl:1
	v_add_f32_dpp v151, v151, v151 quad_perm:[1,0,3,2] row_mask:0xf bank_mask:0xf bound_ctrl:1
	v_pk_fma_f32 v[102:103], v[124:125], v[120:121], v[102:103] op_sel:[0,1,0]
	v_add_f32_dpp v148, v148, v148 quad_perm:[2,3,0,1] row_mask:0xf bank_mask:0xf bound_ctrl:1
	v_add_f32_dpp v149, v149, v149 quad_perm:[2,3,0,1] row_mask:0xf bank_mask:0xf bound_ctrl:1
	v_add_f32_dpp v150, v150, v150 quad_perm:[2,3,0,1] row_mask:0xf bank_mask:0xf bound_ctrl:1
	v_add_f32_dpp v151, v151, v151 quad_perm:[2,3,0,1] row_mask:0xf bank_mask:0xf bound_ctrl:1
	v_pk_fma_f32 v[104:105], v[124:125], v[122:123], v[104:105] op_sel_hi:[1,0,1]
	v_add_f32_dpp v148, v148, v148 row_half_mirror row_mask:0xf bank_mask:0xf bound_ctrl:1
	v_add_f32_dpp v149, v149, v149 row_half_mirror row_mask:0xf bank_mask:0xf bound_ctrl:1
	v_add_f32_dpp v150, v150, v150 row_half_mirror row_mask:0xf bank_mask:0xf bound_ctrl:1
	v_add_f32_dpp v151, v151, v151 row_half_mirror row_mask:0xf bank_mask:0xf bound_ctrl:1
	v_pk_fma_f32 v[106:107], v[124:125], v[122:123], v[106:107] op_sel:[0,1,0]
	v_add_f32_dpp v148, v148, v148 row_mirror row_mask:0xf bank_mask:0xf bound_ctrl:1
	v_add_f32_dpp v149, v149, v149 row_mirror row_mask:0xf bank_mask:0xf bound_ctrl:1
	v_add_f32_dpp v150, v150, v150 row_mirror row_mask:0xf bank_mask:0xf bound_ctrl:1
	v_pk_fma_f32 v[100:101], v[148:149], v[116:117], v[100:101] op_sel_hi:[1,0,1]
	v_pk_fma_f32 v[102:103], v[148:149], v[116:117], v[102:103] op_sel:[0,1,0]
	v_pk_fma_f32 v[104:105], v[148:149], v[118:119], v[104:105] op_sel_hi:[1,0,1]
	v_pk_fma_f32 v[106:107], v[148:149], v[118:119], v[106:107] op_sel:[0,1,0]
	v_add_f32_dpp v151, v151, v151 row_mirror row_mask:0xf bank_mask:0xf bound_ctrl:1
	v_pk_fma_f32 v[152:153], v[148:149], v[126:127], v[150:151] op_sel_hi:[1,0,1]
	v_pk_fma_f32 v[152:153], v[124:125], v[126:127], v[152:153] op_sel:[0,1,0]
	v_cvt_pk_bf16_f32 v154, v152, v153
	s_waitcnt lgkmcnt(0)
	ds_read_b128 v[108:111], v156 offset:18624
	ds_read_b128 v[112:115], v156 offset:18880
	ds_read_b128 v[120:123], v156 offset:19648
	ds_read_b64 v[124:125], v157 offset:18624
	ds_read_b128 v[116:119], v156 offset:19392
	ds_read_b64 v[126:127], v158 offset:18624
	v_mov_b32_dpp v155, v154 row_shr:10 row_mask:0xf bank_mask:0xf
	v_pk_mul_f32 v[148:149], v[100:101], v[128:129] op_sel_hi:[1,0]
	v_pk_mul_f32 v[150:151], v[100:101], v[132:133] op_sel_hi:[1,0]
	v_pk_fma_f32 v[148:149], v[102:103], v[128:129], v[148:149] op_sel:[0,1,0]
	v_pk_fma_f32 v[150:151], v[102:103], v[132:133], v[150:151] op_sel:[0,1,0]
	v_pk_fma_f32 v[148:149], v[104:105], v[130:131], v[148:149] op_sel_hi:[1,0,1]
	v_pk_fma_f32 v[150:151], v[104:105], v[134:135], v[150:151] op_sel_hi:[1,0,1]
	v_pk_fma_f32 v[148:149], v[106:107], v[130:131], v[148:149] op_sel:[0,1,0]
	v_pk_fma_f32 v[150:151], v[106:107], v[134:135], v[150:151] op_sel:[0,1,0]
	v_pk_fma_f32 v[100:101], v[144:145], v[140:141], v[100:101] op_sel_hi:[1,0,1]
	v_add_f32_dpp v148, v148, v148 quad_perm:[1,0,3,2] row_mask:0xf bank_mask:0xf bound_ctrl:1
	v_add_f32_dpp v149, v149, v149 quad_perm:[1,0,3,2] row_mask:0xf bank_mask:0xf bound_ctrl:1
	v_add_f32_dpp v150, v150, v150 quad_perm:[1,0,3,2] row_mask:0xf bank_mask:0xf bound_ctrl:1
	v_add_f32_dpp v151, v151, v151 quad_perm:[1,0,3,2] row_mask:0xf bank_mask:0xf bound_ctrl:1
	v_pk_fma_f32 v[102:103], v[144:145], v[140:141], v[102:103] op_sel:[0,1,0]
	v_add_f32_dpp v148, v148, v148 quad_perm:[2,3,0,1] row_mask:0xf bank_mask:0xf bound_ctrl:1
	v_add_f32_dpp v149, v149, v149 quad_perm:[2,3,0,1] row_mask:0xf bank_mask:0xf bound_ctrl:1
	v_add_f32_dpp v150, v150, v150 quad_perm:[2,3,0,1] row_mask:0xf bank_mask:0xf bound_ctrl:1
	v_add_f32_dpp v151, v151, v151 quad_perm:[2,3,0,1] row_mask:0xf bank_mask:0xf bound_ctrl:1
	v_pk_fma_f32 v[104:105], v[144:145], v[142:143], v[104:105] op_sel_hi:[1,0,1]
	v_add_f32_dpp v148, v148, v148 row_half_mirror row_mask:0xf bank_mask:0xf bound_ctrl:1
	v_add_f32_dpp v149, v149, v149 row_half_mirror row_mask:0xf bank_mask:0xf bound_ctrl:1
	v_add_f32_dpp v150, v150, v150 row_half_mirror row_mask:0xf bank_mask:0xf bound_ctrl:1
	v_add_f32_dpp v151, v151, v151 row_half_mirror row_mask:0xf bank_mask:0xf bound_ctrl:1
	v_pk_fma_f32 v[106:107], v[144:145], v[142:143], v[106:107] op_sel:[0,1,0]
	v_add_f32_dpp v148, v148, v148 row_mirror row_mask:0xf bank_mask:0xf bound_ctrl:1
	v_add_f32_dpp v149, v149, v149 row_mirror row_mask:0xf bank_mask:0xf bound_ctrl:1
	v_add_f32_dpp v150, v150, v150 row_mirror row_mask:0xf bank_mask:0xf bound_ctrl:1
	v_pk_fma_f32 v[100:101], v[148:149], v[136:137], v[100:101] op_sel_hi:[1,0,1]
	v_pk_fma_f32 v[102:103], v[148:149], v[136:137], v[102:103] op_sel:[0,1,0]
	v_pk_fma_f32 v[104:105], v[148:149], v[138:139], v[104:105] op_sel_hi:[1,0,1]
	v_pk_fma_f32 v[106:107], v[148:149], v[138:139], v[106:107] op_sel:[0,1,0]
	v_add_f32_dpp v151, v151, v151 row_mirror row_mask:0xf bank_mask:0xf bound_ctrl:1
	v_pk_fma_f32 v[152:153], v[148:149], v[146:147], v[150:151] op_sel_hi:[1,0,1]
	v_pk_fma_f32 v[152:153], v[144:145], v[146:147], v[152:153] op_sel:[0,1,0]
	v_cvt_pk_bf16_f32 v154, v152, v153
	s_waitcnt lgkmcnt(0)
	ds_read_b128 v[128:131], v156 offset:20176
	ds_read_b128 v[132:135], v156 offset:20432
	ds_read_b128 v[140:143], v156 offset:21200
	ds_read_b64 v[144:145], v157 offset:20176
	ds_read_b128 v[136:139], v156 offset:20944
	ds_read_b64 v[146:147], v158 offset:20176
	v_mov_b32_dpp v155, v154 row_shr:11 row_mask:0xf bank_mask:0xf
	v_pk_mul_f32 v[148:149], v[100:101], v[108:109] op_sel_hi:[1,0]
	v_pk_mul_f32 v[150:151], v[100:101], v[112:113] op_sel_hi:[1,0]
	v_pk_fma_f32 v[148:149], v[102:103], v[108:109], v[148:149] op_sel:[0,1,0]
	v_pk_fma_f32 v[150:151], v[102:103], v[112:113], v[150:151] op_sel:[0,1,0]
	v_pk_fma_f32 v[148:149], v[104:105], v[110:111], v[148:149] op_sel_hi:[1,0,1]
	v_pk_fma_f32 v[150:151], v[104:105], v[114:115], v[150:151] op_sel_hi:[1,0,1]
	v_pk_fma_f32 v[148:149], v[106:107], v[110:111], v[148:149] op_sel:[0,1,0]
	v_pk_fma_f32 v[150:151], v[106:107], v[114:115], v[150:151] op_sel:[0,1,0]
	v_pk_fma_f32 v[100:101], v[124:125], v[120:121], v[100:101] op_sel_hi:[1,0,1]
	v_add_f32_dpp v148, v148, v148 quad_perm:[1,0,3,2] row_mask:0xf bank_mask:0xf bound_ctrl:1
	v_add_f32_dpp v149, v149, v149 quad_perm:[1,0,3,2] row_mask:0xf bank_mask:0xf bound_ctrl:1
	v_add_f32_dpp v150, v150, v150 quad_perm:[1,0,3,2] row_mask:0xf bank_mask:0xf bound_ctrl:1
	v_add_f32_dpp v151, v151, v151 quad_perm:[1,0,3,2] row_mask:0xf bank_mask:0xf bound_ctrl:1
	v_pk_fma_f32 v[102:103], v[124:125], v[120:121], v[102:103] op_sel:[0,1,0]
	v_add_f32_dpp v148, v148, v148 quad_perm:[2,3,0,1] row_mask:0xf bank_mask:0xf bound_ctrl:1
	v_add_f32_dpp v149, v149, v149 quad_perm:[2,3,0,1] row_mask:0xf bank_mask:0xf bound_ctrl:1
	v_add_f32_dpp v150, v150, v150 quad_perm:[2,3,0,1] row_mask:0xf bank_mask:0xf bound_ctrl:1
	v_add_f32_dpp v151, v151, v151 quad_perm:[2,3,0,1] row_mask:0xf bank_mask:0xf bound_ctrl:1
	v_pk_fma_f32 v[104:105], v[124:125], v[122:123], v[104:105] op_sel_hi:[1,0,1]
	v_add_f32_dpp v148, v148, v148 row_half_mirror row_mask:0xf bank_mask:0xf bound_ctrl:1
	v_add_f32_dpp v149, v149, v149 row_half_mirror row_mask:0xf bank_mask:0xf bound_ctrl:1
	v_add_f32_dpp v150, v150, v150 row_half_mirror row_mask:0xf bank_mask:0xf bound_ctrl:1
	v_add_f32_dpp v151, v151, v151 row_half_mirror row_mask:0xf bank_mask:0xf bound_ctrl:1
	v_pk_fma_f32 v[106:107], v[124:125], v[122:123], v[106:107] op_sel:[0,1,0]
	v_add_f32_dpp v148, v148, v148 row_mirror row_mask:0xf bank_mask:0xf bound_ctrl:1
	v_add_f32_dpp v149, v149, v149 row_mirror row_mask:0xf bank_mask:0xf bound_ctrl:1
	v_add_f32_dpp v150, v150, v150 row_mirror row_mask:0xf bank_mask:0xf bound_ctrl:1
	v_pk_fma_f32 v[100:101], v[148:149], v[116:117], v[100:101] op_sel_hi:[1,0,1]
	v_pk_fma_f32 v[102:103], v[148:149], v[116:117], v[102:103] op_sel:[0,1,0]
	v_pk_fma_f32 v[104:105], v[148:149], v[118:119], v[104:105] op_sel_hi:[1,0,1]
	v_pk_fma_f32 v[106:107], v[148:149], v[118:119], v[106:107] op_sel:[0,1,0]
	v_add_f32_dpp v151, v151, v151 row_mirror row_mask:0xf bank_mask:0xf bound_ctrl:1
	v_pk_fma_f32 v[152:153], v[148:149], v[126:127], v[150:151] op_sel_hi:[1,0,1]
	v_pk_fma_f32 v[152:153], v[124:125], v[126:127], v[152:153] op_sel:[0,1,0]
	v_cvt_pk_bf16_f32 v154, v152, v153
	s_waitcnt lgkmcnt(0)
	ds_read_b128 v[108:111], v156 offset:21728
	ds_read_b128 v[112:115], v156 offset:21984
	ds_read_b128 v[120:123], v156 offset:22752
	ds_read_b64 v[124:125], v157 offset:21728
	ds_read_b128 v[116:119], v156 offset:22496
	ds_read_b64 v[126:127], v158 offset:21728
	v_mov_b32_dpp v155, v154 row_shr:12 row_mask:0xf bank_mask:0xf
	v_pk_mul_f32 v[148:149], v[100:101], v[128:129] op_sel_hi:[1,0]
	v_pk_mul_f32 v[150:151], v[100:101], v[132:133] op_sel_hi:[1,0]
	v_pk_fma_f32 v[148:149], v[102:103], v[128:129], v[148:149] op_sel:[0,1,0]
	v_pk_fma_f32 v[150:151], v[102:103], v[132:133], v[150:151] op_sel:[0,1,0]
	v_pk_fma_f32 v[148:149], v[104:105], v[130:131], v[148:149] op_sel_hi:[1,0,1]
	v_pk_fma_f32 v[150:151], v[104:105], v[134:135], v[150:151] op_sel_hi:[1,0,1]
	v_pk_fma_f32 v[148:149], v[106:107], v[130:131], v[148:149] op_sel:[0,1,0]
	v_pk_fma_f32 v[150:151], v[106:107], v[134:135], v[150:151] op_sel:[0,1,0]
	v_pk_fma_f32 v[100:101], v[144:145], v[140:141], v[100:101] op_sel_hi:[1,0,1]
	v_add_f32_dpp v148, v148, v148 quad_perm:[1,0,3,2] row_mask:0xf bank_mask:0xf bound_ctrl:1
	v_add_f32_dpp v149, v149, v149 quad_perm:[1,0,3,2] row_mask:0xf bank_mask:0xf bound_ctrl:1
	v_add_f32_dpp v150, v150, v150 quad_perm:[1,0,3,2] row_mask:0xf bank_mask:0xf bound_ctrl:1
	v_add_f32_dpp v151, v151, v151 quad_perm:[1,0,3,2] row_mask:0xf bank_mask:0xf bound_ctrl:1
	v_pk_fma_f32 v[102:103], v[144:145], v[140:141], v[102:103] op_sel:[0,1,0]
	v_add_f32_dpp v148, v148, v148 quad_perm:[2,3,0,1] row_mask:0xf bank_mask:0xf bound_ctrl:1
	v_add_f32_dpp v149, v149, v149 quad_perm:[2,3,0,1] row_mask:0xf bank_mask:0xf bound_ctrl:1
	v_add_f32_dpp v150, v150, v150 quad_perm:[2,3,0,1] row_mask:0xf bank_mask:0xf bound_ctrl:1
	v_add_f32_dpp v151, v151, v151 quad_perm:[2,3,0,1] row_mask:0xf bank_mask:0xf bound_ctrl:1
	v_pk_fma_f32 v[104:105], v[144:145], v[142:143], v[104:105] op_sel_hi:[1,0,1]
	v_add_f32_dpp v148, v148, v148 row_half_mirror row_mask:0xf bank_mask:0xf bound_ctrl:1
	v_add_f32_dpp v149, v149, v149 row_half_mirror row_mask:0xf bank_mask:0xf bound_ctrl:1
	v_add_f32_dpp v150, v150, v150 row_half_mirror row_mask:0xf bank_mask:0xf bound_ctrl:1
	v_add_f32_dpp v151, v151, v151 row_half_mirror row_mask:0xf bank_mask:0xf bound_ctrl:1
	v_pk_fma_f32 v[106:107], v[144:145], v[142:143], v[106:107] op_sel:[0,1,0]
	v_add_f32_dpp v148, v148, v148 row_mirror row_mask:0xf bank_mask:0xf bound_ctrl:1
	v_add_f32_dpp v149, v149, v149 row_mirror row_mask:0xf bank_mask:0xf bound_ctrl:1
	v_add_f32_dpp v150, v150, v150 row_mirror row_mask:0xf bank_mask:0xf bound_ctrl:1
	v_pk_fma_f32 v[100:101], v[148:149], v[136:137], v[100:101] op_sel_hi:[1,0,1]
	v_pk_fma_f32 v[102:103], v[148:149], v[136:137], v[102:103] op_sel:[0,1,0]
	v_pk_fma_f32 v[104:105], v[148:149], v[138:139], v[104:105] op_sel_hi:[1,0,1]
	v_pk_fma_f32 v[106:107], v[148:149], v[138:139], v[106:107] op_sel:[0,1,0]
	v_add_f32_dpp v151, v151, v151 row_mirror row_mask:0xf bank_mask:0xf bound_ctrl:1
	v_pk_fma_f32 v[152:153], v[148:149], v[146:147], v[150:151] op_sel_hi:[1,0,1]
	v_pk_fma_f32 v[152:153], v[144:145], v[146:147], v[152:153] op_sel:[0,1,0]
	v_cvt_pk_bf16_f32 v154, v152, v153
	s_waitcnt lgkmcnt(0)
	ds_read_b128 v[128:131], v156 offset:23280
	ds_read_b128 v[132:135], v156 offset:23536
	ds_read_b128 v[140:143], v156 offset:24304
	ds_read_b64 v[144:145], v157 offset:23280
	ds_read_b128 v[136:139], v156 offset:24048
	ds_read_b64 v[146:147], v158 offset:23280
	v_mov_b32_dpp v155, v154 row_shr:13 row_mask:0xf bank_mask:0xf
	v_pk_mul_f32 v[148:149], v[100:101], v[108:109] op_sel_hi:[1,0]
	v_pk_mul_f32 v[150:151], v[100:101], v[112:113] op_sel_hi:[1,0]
	v_pk_fma_f32 v[148:149], v[102:103], v[108:109], v[148:149] op_sel:[0,1,0]
	v_pk_fma_f32 v[150:151], v[102:103], v[112:113], v[150:151] op_sel:[0,1,0]
	v_pk_fma_f32 v[148:149], v[104:105], v[110:111], v[148:149] op_sel_hi:[1,0,1]
	v_pk_fma_f32 v[150:151], v[104:105], v[114:115], v[150:151] op_sel_hi:[1,0,1]
	v_pk_fma_f32 v[148:149], v[106:107], v[110:111], v[148:149] op_sel:[0,1,0]
	v_pk_fma_f32 v[150:151], v[106:107], v[114:115], v[150:151] op_sel:[0,1,0]
	v_pk_fma_f32 v[100:101], v[124:125], v[120:121], v[100:101] op_sel_hi:[1,0,1]
	v_add_f32_dpp v148, v148, v148 quad_perm:[1,0,3,2] row_mask:0xf bank_mask:0xf bound_ctrl:1
	v_add_f32_dpp v149, v149, v149 quad_perm:[1,0,3,2] row_mask:0xf bank_mask:0xf bound_ctrl:1
	v_add_f32_dpp v150, v150, v150 quad_perm:[1,0,3,2] row_mask:0xf bank_mask:0xf bound_ctrl:1
	v_add_f32_dpp v151, v151, v151 quad_perm:[1,0,3,2] row_mask:0xf bank_mask:0xf bound_ctrl:1
	v_pk_fma_f32 v[102:103], v[124:125], v[120:121], v[102:103] op_sel:[0,1,0]
	v_add_f32_dpp v148, v148, v148 quad_perm:[2,3,0,1] row_mask:0xf bank_mask:0xf bound_ctrl:1
	v_add_f32_dpp v149, v149, v149 quad_perm:[2,3,0,1] row_mask:0xf bank_mask:0xf bound_ctrl:1
	v_add_f32_dpp v150, v150, v150 quad_perm:[2,3,0,1] row_mask:0xf bank_mask:0xf bound_ctrl:1
	v_add_f32_dpp v151, v151, v151 quad_perm:[2,3,0,1] row_mask:0xf bank_mask:0xf bound_ctrl:1
	v_pk_fma_f32 v[104:105], v[124:125], v[122:123], v[104:105] op_sel_hi:[1,0,1]
	v_add_f32_dpp v148, v148, v148 row_half_mirror row_mask:0xf bank_mask:0xf bound_ctrl:1
	v_add_f32_dpp v149, v149, v149 row_half_mirror row_mask:0xf bank_mask:0xf bound_ctrl:1
	v_add_f32_dpp v150, v150, v150 row_half_mirror row_mask:0xf bank_mask:0xf bound_ctrl:1
	v_add_f32_dpp v151, v151, v151 row_half_mirror row_mask:0xf bank_mask:0xf bound_ctrl:1
	v_pk_fma_f32 v[106:107], v[124:125], v[122:123], v[106:107] op_sel:[0,1,0]
	v_add_f32_dpp v148, v148, v148 row_mirror row_mask:0xf bank_mask:0xf bound_ctrl:1
	v_add_f32_dpp v149, v149, v149 row_mirror row_mask:0xf bank_mask:0xf bound_ctrl:1
	v_add_f32_dpp v150, v150, v150 row_mirror row_mask:0xf bank_mask:0xf bound_ctrl:1
	v_pk_fma_f32 v[100:101], v[148:149], v[116:117], v[100:101] op_sel_hi:[1,0,1]
	v_pk_fma_f32 v[102:103], v[148:149], v[116:117], v[102:103] op_sel:[0,1,0]
	v_pk_fma_f32 v[104:105], v[148:149], v[118:119], v[104:105] op_sel_hi:[1,0,1]
	v_pk_fma_f32 v[106:107], v[148:149], v[118:119], v[106:107] op_sel:[0,1,0]
	v_add_f32_dpp v151, v151, v151 row_mirror row_mask:0xf bank_mask:0xf bound_ctrl:1
	v_pk_fma_f32 v[152:153], v[148:149], v[126:127], v[150:151] op_sel_hi:[1,0,1]
	v_pk_fma_f32 v[152:153], v[124:125], v[126:127], v[152:153] op_sel:[0,1,0]
	v_cvt_pk_bf16_f32 v154, v152, v153
	s_waitcnt lgkmcnt(0)
	ds_read_b128 v[108:111], v156 offset:24832
	ds_read_b128 v[112:115], v156 offset:25088
	ds_read_b128 v[120:123], v156 offset:25856
	ds_read_b64 v[124:125], v157 offset:24832
	ds_read_b128 v[116:119], v156 offset:25600
	ds_read_b64 v[126:127], v158 offset:24832
	ds_read_b128 v[204:207], v156 offset:23792
	v_mov_b32_dpp v155, v154 row_shr:14 row_mask:0xf bank_mask:0xf
	v_pk_mul_f32 v[148:149], v[100:101], v[128:129] op_sel_hi:[1,0]
	v_pk_mul_f32 v[150:151], v[100:101], v[132:133] op_sel_hi:[1,0]
	v_pk_fma_f32 v[148:149], v[102:103], v[128:129], v[148:149] op_sel:[0,1,0]
	v_pk_fma_f32 v[150:151], v[102:103], v[132:133], v[150:151] op_sel:[0,1,0]
	v_pk_fma_f32 v[148:149], v[104:105], v[130:131], v[148:149] op_sel_hi:[1,0,1]
	v_pk_fma_f32 v[150:151], v[104:105], v[134:135], v[150:151] op_sel_hi:[1,0,1]
	v_pk_fma_f32 v[148:149], v[106:107], v[130:131], v[148:149] op_sel:[0,1,0]
	v_pk_fma_f32 v[150:151], v[106:107], v[134:135], v[150:151] op_sel:[0,1,0]
	v_pk_fma_f32 v[100:101], v[144:145], v[140:141], v[100:101] op_sel_hi:[1,0,1]
	v_add_f32_dpp v148, v148, v148 quad_perm:[1,0,3,2] row_mask:0xf bank_mask:0xf bound_ctrl:1
	v_add_f32_dpp v149, v149, v149 quad_perm:[1,0,3,2] row_mask:0xf bank_mask:0xf bound_ctrl:1
	v_add_f32_dpp v150, v150, v150 quad_perm:[1,0,3,2] row_mask:0xf bank_mask:0xf bound_ctrl:1
	v_add_f32_dpp v151, v151, v151 quad_perm:[1,0,3,2] row_mask:0xf bank_mask:0xf bound_ctrl:1
	v_pk_fma_f32 v[102:103], v[144:145], v[140:141], v[102:103] op_sel:[0,1,0]
	v_add_f32_dpp v148, v148, v148 quad_perm:[2,3,0,1] row_mask:0xf bank_mask:0xf bound_ctrl:1
	v_add_f32_dpp v149, v149, v149 quad_perm:[2,3,0,1] row_mask:0xf bank_mask:0xf bound_ctrl:1
	v_add_f32_dpp v150, v150, v150 quad_perm:[2,3,0,1] row_mask:0xf bank_mask:0xf bound_ctrl:1
	v_add_f32_dpp v151, v151, v151 quad_perm:[2,3,0,1] row_mask:0xf bank_mask:0xf bound_ctrl:1
	v_pk_fma_f32 v[104:105], v[144:145], v[142:143], v[104:105] op_sel_hi:[1,0,1]
	v_add_f32_dpp v148, v148, v148 row_half_mirror row_mask:0xf bank_mask:0xf bound_ctrl:1
	v_add_f32_dpp v149, v149, v149 row_half_mirror row_mask:0xf bank_mask:0xf bound_ctrl:1
	v_add_f32_dpp v150, v150, v150 row_half_mirror row_mask:0xf bank_mask:0xf bound_ctrl:1
	v_add_f32_dpp v151, v151, v151 row_half_mirror row_mask:0xf bank_mask:0xf bound_ctrl:1
	v_pk_fma_f32 v[106:107], v[144:145], v[142:143], v[106:107] op_sel:[0,1,0]
	v_add_f32_dpp v148, v148, v148 row_mirror row_mask:0xf bank_mask:0xf bound_ctrl:1
	v_add_f32_dpp v149, v149, v149 row_mirror row_mask:0xf bank_mask:0xf bound_ctrl:1
	v_add_f32_dpp v150, v150, v150 row_mirror row_mask:0xf bank_mask:0xf bound_ctrl:1
	v_pk_fma_f32 v[100:101], v[148:149], v[136:137], v[100:101] op_sel_hi:[1,0,1]
	v_pk_fma_f32 v[102:103], v[148:149], v[136:137], v[102:103] op_sel:[0,1,0]
	v_pk_fma_f32 v[104:105], v[148:149], v[138:139], v[104:105] op_sel_hi:[1,0,1]
	v_pk_fma_f32 v[106:107], v[148:149], v[138:139], v[106:107] op_sel:[0,1,0]
	v_add_f32_dpp v151, v151, v151 row_mirror row_mask:0xf bank_mask:0xf bound_ctrl:1
	v_pk_fma_f32 v[152:153], v[148:149], v[146:147], v[150:151] op_sel_hi:[1,0,1]
	v_pk_fma_f32 v[152:153], v[144:145], v[146:147], v[152:153] op_sel:[0,1,0]
	v_cvt_pk_bf16_f32 v154, v152, v153
	s_waitcnt lgkmcnt(0)
	v_pk_mul_f32 v[100:101], v[100:101], v[204:205] op_sel_hi:[1,0]
	v_pk_mul_f32 v[102:103], v[102:103], v[204:205] op_sel:[0,1]
	v_pk_mul_f32 v[104:105], v[104:105], v[206:207] op_sel_hi:[1,0]
	v_pk_mul_f32 v[106:107], v[106:107], v[206:207] op_sel:[0,1]
	ds_read_b128 v[128:131], v156 offset:26384
	ds_read_b128 v[132:135], v156 offset:26640
	ds_read_b128 v[140:143], v156 offset:27408
	ds_read_b64 v[144:145], v157 offset:26384
	ds_read_b128 v[136:139], v156 offset:27152
	ds_read_b64 v[146:147], v158 offset:26384
	v_mov_b32_dpp v155, v154 row_shr:15 row_mask:0xf bank_mask:0xf
	global_store_dword v[160:161], v155, off
	v_lshl_add_u64 v[160:161], v[160:161], 0, s[60:61]
	v_pk_mul_f32 v[148:149], v[100:101], v[108:109] op_sel_hi:[1,0]
	v_pk_mul_f32 v[150:151], v[100:101], v[112:113] op_sel_hi:[1,0]
	v_pk_fma_f32 v[148:149], v[102:103], v[108:109], v[148:149] op_sel:[0,1,0]
	v_pk_fma_f32 v[150:151], v[102:103], v[112:113], v[150:151] op_sel:[0,1,0]
	v_pk_fma_f32 v[148:149], v[104:105], v[110:111], v[148:149] op_sel_hi:[1,0,1]
	v_pk_fma_f32 v[150:151], v[104:105], v[114:115], v[150:151] op_sel_hi:[1,0,1]
	v_pk_fma_f32 v[148:149], v[106:107], v[110:111], v[148:149] op_sel:[0,1,0]
	v_pk_fma_f32 v[150:151], v[106:107], v[114:115], v[150:151] op_sel:[0,1,0]
	v_pk_fma_f32 v[100:101], v[124:125], v[120:121], v[100:101] op_sel_hi:[1,0,1]
	v_add_f32_dpp v148, v148, v148 quad_perm:[1,0,3,2] row_mask:0xf bank_mask:0xf bound_ctrl:1
	v_add_f32_dpp v149, v149, v149 quad_perm:[1,0,3,2] row_mask:0xf bank_mask:0xf bound_ctrl:1
	v_add_f32_dpp v150, v150, v150 quad_perm:[1,0,3,2] row_mask:0xf bank_mask:0xf bound_ctrl:1
	v_add_f32_dpp v151, v151, v151 quad_perm:[1,0,3,2] row_mask:0xf bank_mask:0xf bound_ctrl:1
	v_pk_fma_f32 v[102:103], v[124:125], v[120:121], v[102:103] op_sel:[0,1,0]
	v_add_f32_dpp v148, v148, v148 quad_perm:[2,3,0,1] row_mask:0xf bank_mask:0xf bound_ctrl:1
	v_add_f32_dpp v149, v149, v149 quad_perm:[2,3,0,1] row_mask:0xf bank_mask:0xf bound_ctrl:1
	v_add_f32_dpp v150, v150, v150 quad_perm:[2,3,0,1] row_mask:0xf bank_mask:0xf bound_ctrl:1
	v_add_f32_dpp v151, v151, v151 quad_perm:[2,3,0,1] row_mask:0xf bank_mask:0xf bound_ctrl:1
	v_pk_fma_f32 v[104:105], v[124:125], v[122:123], v[104:105] op_sel_hi:[1,0,1]
	v_add_f32_dpp v148, v148, v148 row_half_mirror row_mask:0xf bank_mask:0xf bound_ctrl:1
	v_add_f32_dpp v149, v149, v149 row_half_mirror row_mask:0xf bank_mask:0xf bound_ctrl:1
	v_add_f32_dpp v150, v150, v150 row_half_mirror row_mask:0xf bank_mask:0xf bound_ctrl:1
	v_add_f32_dpp v151, v151, v151 row_half_mirror row_mask:0xf bank_mask:0xf bound_ctrl:1
	v_pk_fma_f32 v[106:107], v[124:125], v[122:123], v[106:107] op_sel:[0,1,0]
	v_add_f32_dpp v148, v148, v148 row_mirror row_mask:0xf bank_mask:0xf bound_ctrl:1
	v_add_f32_dpp v149, v149, v149 row_mirror row_mask:0xf bank_mask:0xf bound_ctrl:1
	v_add_f32_dpp v150, v150, v150 row_mirror row_mask:0xf bank_mask:0xf bound_ctrl:1
	v_pk_fma_f32 v[100:101], v[148:149], v[116:117], v[100:101] op_sel_hi:[1,0,1]
	v_pk_fma_f32 v[102:103], v[148:149], v[116:117], v[102:103] op_sel:[0,1,0]
	v_pk_fma_f32 v[104:105], v[148:149], v[118:119], v[104:105] op_sel_hi:[1,0,1]
	v_pk_fma_f32 v[106:107], v[148:149], v[118:119], v[106:107] op_sel:[0,1,0]
	v_add_f32_dpp v151, v151, v151 row_mirror row_mask:0xf bank_mask:0xf bound_ctrl:1
	v_pk_fma_f32 v[152:153], v[148:149], v[126:127], v[150:151] op_sel_hi:[1,0,1]
	v_pk_fma_f32 v[152:153], v[124:125], v[126:127], v[152:153] op_sel:[0,1,0]
	v_cvt_pk_bf16_f32 v154, v152, v153
	s_waitcnt lgkmcnt(0)
	ds_read_b128 v[108:111], v156 offset:27936
	ds_read_b128 v[112:115], v156 offset:28192
	ds_read_b128 v[120:123], v156 offset:28960
	ds_read_b64 v[124:125], v157 offset:27936
	ds_read_b128 v[116:119], v156 offset:28704
	ds_read_b64 v[126:127], v158 offset:27936
	v_mov_b32_e32 v155, v154
	v_pk_mul_f32 v[148:149], v[100:101], v[128:129] op_sel_hi:[1,0]
	v_pk_mul_f32 v[150:151], v[100:101], v[132:133] op_sel_hi:[1,0]
	v_pk_fma_f32 v[148:149], v[102:103], v[128:129], v[148:149] op_sel:[0,1,0]
	v_pk_fma_f32 v[150:151], v[102:103], v[132:133], v[150:151] op_sel:[0,1,0]
	v_pk_fma_f32 v[148:149], v[104:105], v[130:131], v[148:149] op_sel_hi:[1,0,1]
	v_pk_fma_f32 v[150:151], v[104:105], v[134:135], v[150:151] op_sel_hi:[1,0,1]
	v_pk_fma_f32 v[148:149], v[106:107], v[130:131], v[148:149] op_sel:[0,1,0]
	v_pk_fma_f32 v[150:151], v[106:107], v[134:135], v[150:151] op_sel:[0,1,0]
	v_pk_fma_f32 v[100:101], v[144:145], v[140:141], v[100:101] op_sel_hi:[1,0,1]
	v_add_f32_dpp v148, v148, v148 quad_perm:[1,0,3,2] row_mask:0xf bank_mask:0xf bound_ctrl:1
	v_add_f32_dpp v149, v149, v149 quad_perm:[1,0,3,2] row_mask:0xf bank_mask:0xf bound_ctrl:1
	v_add_f32_dpp v150, v150, v150 quad_perm:[1,0,3,2] row_mask:0xf bank_mask:0xf bound_ctrl:1
	v_add_f32_dpp v151, v151, v151 quad_perm:[1,0,3,2] row_mask:0xf bank_mask:0xf bound_ctrl:1
	v_pk_fma_f32 v[102:103], v[144:145], v[140:141], v[102:103] op_sel:[0,1,0]
	v_add_f32_dpp v148, v148, v148 quad_perm:[2,3,0,1] row_mask:0xf bank_mask:0xf bound_ctrl:1
	v_add_f32_dpp v149, v149, v149 quad_perm:[2,3,0,1] row_mask:0xf bank_mask:0xf bound_ctrl:1
	v_add_f32_dpp v150, v150, v150 quad_perm:[2,3,0,1] row_mask:0xf bank_mask:0xf bound_ctrl:1
	v_add_f32_dpp v151, v151, v151 quad_perm:[2,3,0,1] row_mask:0xf bank_mask:0xf bound_ctrl:1
	v_pk_fma_f32 v[104:105], v[144:145], v[142:143], v[104:105] op_sel_hi:[1,0,1]
	v_add_f32_dpp v148, v148, v148 row_half_mirror row_mask:0xf bank_mask:0xf bound_ctrl:1
	v_add_f32_dpp v149, v149, v149 row_half_mirror row_mask:0xf bank_mask:0xf bound_ctrl:1
	v_add_f32_dpp v150, v150, v150 row_half_mirror row_mask:0xf bank_mask:0xf bound_ctrl:1
	v_add_f32_dpp v151, v151, v151 row_half_mirror row_mask:0xf bank_mask:0xf bound_ctrl:1
	v_pk_fma_f32 v[106:107], v[144:145], v[142:143], v[106:107] op_sel:[0,1,0]
	v_add_f32_dpp v148, v148, v148 row_mirror row_mask:0xf bank_mask:0xf bound_ctrl:1
	v_add_f32_dpp v149, v149, v149 row_mirror row_mask:0xf bank_mask:0xf bound_ctrl:1
	v_add_f32_dpp v150, v150, v150 row_mirror row_mask:0xf bank_mask:0xf bound_ctrl:1
	v_pk_fma_f32 v[100:101], v[148:149], v[136:137], v[100:101] op_sel_hi:[1,0,1]
	v_pk_fma_f32 v[102:103], v[148:149], v[136:137], v[102:103] op_sel:[0,1,0]
	v_pk_fma_f32 v[104:105], v[148:149], v[138:139], v[104:105] op_sel_hi:[1,0,1]
	v_pk_fma_f32 v[106:107], v[148:149], v[138:139], v[106:107] op_sel:[0,1,0]
	v_add_f32_dpp v151, v151, v151 row_mirror row_mask:0xf bank_mask:0xf bound_ctrl:1
	v_pk_fma_f32 v[152:153], v[148:149], v[146:147], v[150:151] op_sel_hi:[1,0,1]
	v_pk_fma_f32 v[152:153], v[144:145], v[146:147], v[152:153] op_sel:[0,1,0]
	v_cvt_pk_bf16_f32 v154, v152, v153
	s_waitcnt lgkmcnt(0)
	ds_read_b128 v[128:131], v156 offset:29488
	ds_read_b128 v[132:135], v156 offset:29744
	ds_read_b128 v[140:143], v156 offset:30512
	ds_read_b64 v[144:145], v157 offset:29488
	ds_read_b128 v[136:139], v156 offset:30256
	ds_read_b64 v[146:147], v158 offset:29488
	v_mov_b32_dpp v155, v154 row_shr:1 row_mask:0xf bank_mask:0xf
	v_pk_mul_f32 v[148:149], v[100:101], v[108:109] op_sel_hi:[1,0]
	v_pk_mul_f32 v[150:151], v[100:101], v[112:113] op_sel_hi:[1,0]
	v_pk_fma_f32 v[148:149], v[102:103], v[108:109], v[148:149] op_sel:[0,1,0]
	v_pk_fma_f32 v[150:151], v[102:103], v[112:113], v[150:151] op_sel:[0,1,0]
	v_pk_fma_f32 v[148:149], v[104:105], v[110:111], v[148:149] op_sel_hi:[1,0,1]
	v_pk_fma_f32 v[150:151], v[104:105], v[114:115], v[150:151] op_sel_hi:[1,0,1]
	v_pk_fma_f32 v[148:149], v[106:107], v[110:111], v[148:149] op_sel:[0,1,0]
	v_pk_fma_f32 v[150:151], v[106:107], v[114:115], v[150:151] op_sel:[0,1,0]
	v_pk_fma_f32 v[100:101], v[124:125], v[120:121], v[100:101] op_sel_hi:[1,0,1]
	v_add_f32_dpp v148, v148, v148 quad_perm:[1,0,3,2] row_mask:0xf bank_mask:0xf bound_ctrl:1
	v_add_f32_dpp v149, v149, v149 quad_perm:[1,0,3,2] row_mask:0xf bank_mask:0xf bound_ctrl:1
	v_add_f32_dpp v150, v150, v150 quad_perm:[1,0,3,2] row_mask:0xf bank_mask:0xf bound_ctrl:1
	v_add_f32_dpp v151, v151, v151 quad_perm:[1,0,3,2] row_mask:0xf bank_mask:0xf bound_ctrl:1
	v_pk_fma_f32 v[102:103], v[124:125], v[120:121], v[102:103] op_sel:[0,1,0]
	v_add_f32_dpp v148, v148, v148 quad_perm:[2,3,0,1] row_mask:0xf bank_mask:0xf bound_ctrl:1
	v_add_f32_dpp v149, v149, v149 quad_perm:[2,3,0,1] row_mask:0xf bank_mask:0xf bound_ctrl:1
	v_add_f32_dpp v150, v150, v150 quad_perm:[2,3,0,1] row_mask:0xf bank_mask:0xf bound_ctrl:1
	v_add_f32_dpp v151, v151, v151 quad_perm:[2,3,0,1] row_mask:0xf bank_mask:0xf bound_ctrl:1
	v_pk_fma_f32 v[104:105], v[124:125], v[122:123], v[104:105] op_sel_hi:[1,0,1]
	v_add_f32_dpp v148, v148, v148 row_half_mirror row_mask:0xf bank_mask:0xf bound_ctrl:1
	v_add_f32_dpp v149, v149, v149 row_half_mirror row_mask:0xf bank_mask:0xf bound_ctrl:1
	v_add_f32_dpp v150, v150, v150 row_half_mirror row_mask:0xf bank_mask:0xf bound_ctrl:1
	v_add_f32_dpp v151, v151, v151 row_half_mirror row_mask:0xf bank_mask:0xf bound_ctrl:1
	v_pk_fma_f32 v[106:107], v[124:125], v[122:123], v[106:107] op_sel:[0,1,0]
	v_add_f32_dpp v148, v148, v148 row_mirror row_mask:0xf bank_mask:0xf bound_ctrl:1
	v_add_f32_dpp v149, v149, v149 row_mirror row_mask:0xf bank_mask:0xf bound_ctrl:1
	v_add_f32_dpp v150, v150, v150 row_mirror row_mask:0xf bank_mask:0xf bound_ctrl:1
	v_pk_fma_f32 v[100:101], v[148:149], v[116:117], v[100:101] op_sel_hi:[1,0,1]
	v_pk_fma_f32 v[102:103], v[148:149], v[116:117], v[102:103] op_sel:[0,1,0]
	v_pk_fma_f32 v[104:105], v[148:149], v[118:119], v[104:105] op_sel_hi:[1,0,1]
	v_pk_fma_f32 v[106:107], v[148:149], v[118:119], v[106:107] op_sel:[0,1,0]
	v_add_f32_dpp v151, v151, v151 row_mirror row_mask:0xf bank_mask:0xf bound_ctrl:1
	v_pk_fma_f32 v[152:153], v[148:149], v[126:127], v[150:151] op_sel_hi:[1,0,1]
	v_pk_fma_f32 v[152:153], v[124:125], v[126:127], v[152:153] op_sel:[0,1,0]
	v_cvt_pk_bf16_f32 v154, v152, v153
	s_waitcnt lgkmcnt(0)
	ds_read_b128 v[108:111], v156 offset:31040
	ds_read_b128 v[112:115], v156 offset:31296
	ds_read_b128 v[120:123], v156 offset:32064
	ds_read_b64 v[124:125], v157 offset:31040
	ds_read_b128 v[116:119], v156 offset:31808
	ds_read_b64 v[126:127], v158 offset:31040
	v_mov_b32_dpp v155, v154 row_shr:2 row_mask:0xf bank_mask:0xf
	v_pk_mul_f32 v[148:149], v[100:101], v[128:129] op_sel_hi:[1,0]
	v_pk_mul_f32 v[150:151], v[100:101], v[132:133] op_sel_hi:[1,0]
	v_pk_fma_f32 v[148:149], v[102:103], v[128:129], v[148:149] op_sel:[0,1,0]
	v_pk_fma_f32 v[150:151], v[102:103], v[132:133], v[150:151] op_sel:[0,1,0]
	v_pk_fma_f32 v[148:149], v[104:105], v[130:131], v[148:149] op_sel_hi:[1,0,1]
	v_pk_fma_f32 v[150:151], v[104:105], v[134:135], v[150:151] op_sel_hi:[1,0,1]
	v_pk_fma_f32 v[148:149], v[106:107], v[130:131], v[148:149] op_sel:[0,1,0]
	v_pk_fma_f32 v[150:151], v[106:107], v[134:135], v[150:151] op_sel:[0,1,0]
	v_pk_fma_f32 v[100:101], v[144:145], v[140:141], v[100:101] op_sel_hi:[1,0,1]
	v_add_f32_dpp v148, v148, v148 quad_perm:[1,0,3,2] row_mask:0xf bank_mask:0xf bound_ctrl:1
	v_add_f32_dpp v149, v149, v149 quad_perm:[1,0,3,2] row_mask:0xf bank_mask:0xf bound_ctrl:1
	v_add_f32_dpp v150, v150, v150 quad_perm:[1,0,3,2] row_mask:0xf bank_mask:0xf bound_ctrl:1
	v_add_f32_dpp v151, v151, v151 quad_perm:[1,0,3,2] row_mask:0xf bank_mask:0xf bound_ctrl:1
	v_pk_fma_f32 v[102:103], v[144:145], v[140:141], v[102:103] op_sel:[0,1,0]
	v_add_f32_dpp v148, v148, v148 quad_perm:[2,3,0,1] row_mask:0xf bank_mask:0xf bound_ctrl:1
	v_add_f32_dpp v149, v149, v149 quad_perm:[2,3,0,1] row_mask:0xf bank_mask:0xf bound_ctrl:1
	v_add_f32_dpp v150, v150, v150 quad_perm:[2,3,0,1] row_mask:0xf bank_mask:0xf bound_ctrl:1
	v_add_f32_dpp v151, v151, v151 quad_perm:[2,3,0,1] row_mask:0xf bank_mask:0xf bound_ctrl:1
	v_pk_fma_f32 v[104:105], v[144:145], v[142:143], v[104:105] op_sel_hi:[1,0,1]
	v_add_f32_dpp v148, v148, v148 row_half_mirror row_mask:0xf bank_mask:0xf bound_ctrl:1
	v_add_f32_dpp v149, v149, v149 row_half_mirror row_mask:0xf bank_mask:0xf bound_ctrl:1
	v_add_f32_dpp v150, v150, v150 row_half_mirror row_mask:0xf bank_mask:0xf bound_ctrl:1
	v_add_f32_dpp v151, v151, v151 row_half_mirror row_mask:0xf bank_mask:0xf bound_ctrl:1
	v_pk_fma_f32 v[106:107], v[144:145], v[142:143], v[106:107] op_sel:[0,1,0]
	v_add_f32_dpp v148, v148, v148 row_mirror row_mask:0xf bank_mask:0xf bound_ctrl:1
	v_add_f32_dpp v149, v149, v149 row_mirror row_mask:0xf bank_mask:0xf bound_ctrl:1
	v_add_f32_dpp v150, v150, v150 row_mirror row_mask:0xf bank_mask:0xf bound_ctrl:1
	v_pk_fma_f32 v[100:101], v[148:149], v[136:137], v[100:101] op_sel_hi:[1,0,1]
	v_pk_fma_f32 v[102:103], v[148:149], v[136:137], v[102:103] op_sel:[0,1,0]
	v_pk_fma_f32 v[104:105], v[148:149], v[138:139], v[104:105] op_sel_hi:[1,0,1]
	v_pk_fma_f32 v[106:107], v[148:149], v[138:139], v[106:107] op_sel:[0,1,0]
	v_add_f32_dpp v151, v151, v151 row_mirror row_mask:0xf bank_mask:0xf bound_ctrl:1
	v_pk_fma_f32 v[152:153], v[148:149], v[146:147], v[150:151] op_sel_hi:[1,0,1]
	v_pk_fma_f32 v[152:153], v[144:145], v[146:147], v[152:153] op_sel:[0,1,0]
	v_cvt_pk_bf16_f32 v154, v152, v153
	s_waitcnt lgkmcnt(0)
	ds_read_b128 v[128:131], v156 offset:32592
	ds_read_b128 v[132:135], v156 offset:32848
	ds_read_b128 v[140:143], v156 offset:33616
	ds_read_b64 v[144:145], v157 offset:32592
	ds_read_b128 v[136:139], v156 offset:33360
	ds_read_b64 v[146:147], v158 offset:32592
	v_mov_b32_dpp v155, v154 row_shr:3 row_mask:0xf bank_mask:0xf
	v_pk_mul_f32 v[148:149], v[100:101], v[108:109] op_sel_hi:[1,0]
	v_pk_mul_f32 v[150:151], v[100:101], v[112:113] op_sel_hi:[1,0]
	v_pk_fma_f32 v[148:149], v[102:103], v[108:109], v[148:149] op_sel:[0,1,0]
	v_pk_fma_f32 v[150:151], v[102:103], v[112:113], v[150:151] op_sel:[0,1,0]
	v_pk_fma_f32 v[148:149], v[104:105], v[110:111], v[148:149] op_sel_hi:[1,0,1]
	v_pk_fma_f32 v[150:151], v[104:105], v[114:115], v[150:151] op_sel_hi:[1,0,1]
	v_pk_fma_f32 v[148:149], v[106:107], v[110:111], v[148:149] op_sel:[0,1,0]
	v_pk_fma_f32 v[150:151], v[106:107], v[114:115], v[150:151] op_sel:[0,1,0]
	v_pk_fma_f32 v[100:101], v[124:125], v[120:121], v[100:101] op_sel_hi:[1,0,1]
	v_add_f32_dpp v148, v148, v148 quad_perm:[1,0,3,2] row_mask:0xf bank_mask:0xf bound_ctrl:1
	v_add_f32_dpp v149, v149, v149 quad_perm:[1,0,3,2] row_mask:0xf bank_mask:0xf bound_ctrl:1
	v_add_f32_dpp v150, v150, v150 quad_perm:[1,0,3,2] row_mask:0xf bank_mask:0xf bound_ctrl:1
	v_add_f32_dpp v151, v151, v151 quad_perm:[1,0,3,2] row_mask:0xf bank_mask:0xf bound_ctrl:1
	v_pk_fma_f32 v[102:103], v[124:125], v[120:121], v[102:103] op_sel:[0,1,0]
	v_add_f32_dpp v148, v148, v148 quad_perm:[2,3,0,1] row_mask:0xf bank_mask:0xf bound_ctrl:1
	v_add_f32_dpp v149, v149, v149 quad_perm:[2,3,0,1] row_mask:0xf bank_mask:0xf bound_ctrl:1
	v_add_f32_dpp v150, v150, v150 quad_perm:[2,3,0,1] row_mask:0xf bank_mask:0xf bound_ctrl:1
	v_add_f32_dpp v151, v151, v151 quad_perm:[2,3,0,1] row_mask:0xf bank_mask:0xf bound_ctrl:1
	v_pk_fma_f32 v[104:105], v[124:125], v[122:123], v[104:105] op_sel_hi:[1,0,1]
	v_add_f32_dpp v148, v148, v148 row_half_mirror row_mask:0xf bank_mask:0xf bound_ctrl:1
	v_add_f32_dpp v149, v149, v149 row_half_mirror row_mask:0xf bank_mask:0xf bound_ctrl:1
	v_add_f32_dpp v150, v150, v150 row_half_mirror row_mask:0xf bank_mask:0xf bound_ctrl:1
	v_add_f32_dpp v151, v151, v151 row_half_mirror row_mask:0xf bank_mask:0xf bound_ctrl:1
	v_pk_fma_f32 v[106:107], v[124:125], v[122:123], v[106:107] op_sel:[0,1,0]
	v_add_f32_dpp v148, v148, v148 row_mirror row_mask:0xf bank_mask:0xf bound_ctrl:1
	v_add_f32_dpp v149, v149, v149 row_mirror row_mask:0xf bank_mask:0xf bound_ctrl:1
	v_add_f32_dpp v150, v150, v150 row_mirror row_mask:0xf bank_mask:0xf bound_ctrl:1
	v_pk_fma_f32 v[100:101], v[148:149], v[116:117], v[100:101] op_sel_hi:[1,0,1]
	v_pk_fma_f32 v[102:103], v[148:149], v[116:117], v[102:103] op_sel:[0,1,0]
	v_pk_fma_f32 v[104:105], v[148:149], v[118:119], v[104:105] op_sel_hi:[1,0,1]
	v_pk_fma_f32 v[106:107], v[148:149], v[118:119], v[106:107] op_sel:[0,1,0]
	v_add_f32_dpp v151, v151, v151 row_mirror row_mask:0xf bank_mask:0xf bound_ctrl:1
	v_pk_fma_f32 v[152:153], v[148:149], v[126:127], v[150:151] op_sel_hi:[1,0,1]
	v_pk_fma_f32 v[152:153], v[124:125], v[126:127], v[152:153] op_sel:[0,1,0]
	v_cvt_pk_bf16_f32 v154, v152, v153
	s_waitcnt lgkmcnt(0)
	ds_read_b128 v[108:111], v156 offset:34144
	ds_read_b128 v[112:115], v156 offset:34400
	ds_read_b128 v[120:123], v156 offset:35168
	ds_read_b64 v[124:125], v157 offset:34144
	ds_read_b128 v[116:119], v156 offset:34912
	ds_read_b64 v[126:127], v158 offset:34144
	v_mov_b32_dpp v155, v154 row_shr:4 row_mask:0xf bank_mask:0xf
	v_pk_mul_f32 v[148:149], v[100:101], v[128:129] op_sel_hi:[1,0]
	v_pk_mul_f32 v[150:151], v[100:101], v[132:133] op_sel_hi:[1,0]
	v_pk_fma_f32 v[148:149], v[102:103], v[128:129], v[148:149] op_sel:[0,1,0]
	v_pk_fma_f32 v[150:151], v[102:103], v[132:133], v[150:151] op_sel:[0,1,0]
	v_pk_fma_f32 v[148:149], v[104:105], v[130:131], v[148:149] op_sel_hi:[1,0,1]
	v_pk_fma_f32 v[150:151], v[104:105], v[134:135], v[150:151] op_sel_hi:[1,0,1]
	v_pk_fma_f32 v[148:149], v[106:107], v[130:131], v[148:149] op_sel:[0,1,0]
	v_pk_fma_f32 v[150:151], v[106:107], v[134:135], v[150:151] op_sel:[0,1,0]
	v_pk_fma_f32 v[100:101], v[144:145], v[140:141], v[100:101] op_sel_hi:[1,0,1]
	v_add_f32_dpp v148, v148, v148 quad_perm:[1,0,3,2] row_mask:0xf bank_mask:0xf bound_ctrl:1
	v_add_f32_dpp v149, v149, v149 quad_perm:[1,0,3,2] row_mask:0xf bank_mask:0xf bound_ctrl:1
	v_add_f32_dpp v150, v150, v150 quad_perm:[1,0,3,2] row_mask:0xf bank_mask:0xf bound_ctrl:1
	v_add_f32_dpp v151, v151, v151 quad_perm:[1,0,3,2] row_mask:0xf bank_mask:0xf bound_ctrl:1
	v_pk_fma_f32 v[102:103], v[144:145], v[140:141], v[102:103] op_sel:[0,1,0]
	v_add_f32_dpp v148, v148, v148 quad_perm:[2,3,0,1] row_mask:0xf bank_mask:0xf bound_ctrl:1
	v_add_f32_dpp v149, v149, v149 quad_perm:[2,3,0,1] row_mask:0xf bank_mask:0xf bound_ctrl:1
	v_add_f32_dpp v150, v150, v150 quad_perm:[2,3,0,1] row_mask:0xf bank_mask:0xf bound_ctrl:1
	v_add_f32_dpp v151, v151, v151 quad_perm:[2,3,0,1] row_mask:0xf bank_mask:0xf bound_ctrl:1
	v_pk_fma_f32 v[104:105], v[144:145], v[142:143], v[104:105] op_sel_hi:[1,0,1]
	v_add_f32_dpp v148, v148, v148 row_half_mirror row_mask:0xf bank_mask:0xf bound_ctrl:1
	v_add_f32_dpp v149, v149, v149 row_half_mirror row_mask:0xf bank_mask:0xf bound_ctrl:1
	v_add_f32_dpp v150, v150, v150 row_half_mirror row_mask:0xf bank_mask:0xf bound_ctrl:1
	v_add_f32_dpp v151, v151, v151 row_half_mirror row_mask:0xf bank_mask:0xf bound_ctrl:1
	v_pk_fma_f32 v[106:107], v[144:145], v[142:143], v[106:107] op_sel:[0,1,0]
	v_add_f32_dpp v148, v148, v148 row_mirror row_mask:0xf bank_mask:0xf bound_ctrl:1
	v_add_f32_dpp v149, v149, v149 row_mirror row_mask:0xf bank_mask:0xf bound_ctrl:1
	v_add_f32_dpp v150, v150, v150 row_mirror row_mask:0xf bank_mask:0xf bound_ctrl:1
	v_pk_fma_f32 v[100:101], v[148:149], v[136:137], v[100:101] op_sel_hi:[1,0,1]
	v_pk_fma_f32 v[102:103], v[148:149], v[136:137], v[102:103] op_sel:[0,1,0]
	v_pk_fma_f32 v[104:105], v[148:149], v[138:139], v[104:105] op_sel_hi:[1,0,1]
	v_pk_fma_f32 v[106:107], v[148:149], v[138:139], v[106:107] op_sel:[0,1,0]
	v_add_f32_dpp v151, v151, v151 row_mirror row_mask:0xf bank_mask:0xf bound_ctrl:1
	v_pk_fma_f32 v[152:153], v[148:149], v[146:147], v[150:151] op_sel_hi:[1,0,1]
	v_pk_fma_f32 v[152:153], v[144:145], v[146:147], v[152:153] op_sel:[0,1,0]
	v_cvt_pk_bf16_f32 v154, v152, v153
	s_waitcnt lgkmcnt(0)
	ds_read_b128 v[128:131], v156 offset:35696
	ds_read_b128 v[132:135], v156 offset:35952
	ds_read_b128 v[140:143], v156 offset:36720
	ds_read_b64 v[144:145], v157 offset:35696
	ds_read_b128 v[136:139], v156 offset:36464
	ds_read_b64 v[146:147], v158 offset:35696
	v_mov_b32_dpp v155, v154 row_shr:5 row_mask:0xf bank_mask:0xf
	v_pk_mul_f32 v[148:149], v[100:101], v[108:109] op_sel_hi:[1,0]
	v_pk_mul_f32 v[150:151], v[100:101], v[112:113] op_sel_hi:[1,0]
	v_pk_fma_f32 v[148:149], v[102:103], v[108:109], v[148:149] op_sel:[0,1,0]
	v_pk_fma_f32 v[150:151], v[102:103], v[112:113], v[150:151] op_sel:[0,1,0]
	v_pk_fma_f32 v[148:149], v[104:105], v[110:111], v[148:149] op_sel_hi:[1,0,1]
	v_pk_fma_f32 v[150:151], v[104:105], v[114:115], v[150:151] op_sel_hi:[1,0,1]
	v_pk_fma_f32 v[148:149], v[106:107], v[110:111], v[148:149] op_sel:[0,1,0]
	v_pk_fma_f32 v[150:151], v[106:107], v[114:115], v[150:151] op_sel:[0,1,0]
	v_pk_fma_f32 v[100:101], v[124:125], v[120:121], v[100:101] op_sel_hi:[1,0,1]
	v_add_f32_dpp v148, v148, v148 quad_perm:[1,0,3,2] row_mask:0xf bank_mask:0xf bound_ctrl:1
	v_add_f32_dpp v149, v149, v149 quad_perm:[1,0,3,2] row_mask:0xf bank_mask:0xf bound_ctrl:1
	v_add_f32_dpp v150, v150, v150 quad_perm:[1,0,3,2] row_mask:0xf bank_mask:0xf bound_ctrl:1
	v_add_f32_dpp v151, v151, v151 quad_perm:[1,0,3,2] row_mask:0xf bank_mask:0xf bound_ctrl:1
	v_pk_fma_f32 v[102:103], v[124:125], v[120:121], v[102:103] op_sel:[0,1,0]
	v_add_f32_dpp v148, v148, v148 quad_perm:[2,3,0,1] row_mask:0xf bank_mask:0xf bound_ctrl:1
	v_add_f32_dpp v149, v149, v149 quad_perm:[2,3,0,1] row_mask:0xf bank_mask:0xf bound_ctrl:1
	v_add_f32_dpp v150, v150, v150 quad_perm:[2,3,0,1] row_mask:0xf bank_mask:0xf bound_ctrl:1
	v_add_f32_dpp v151, v151, v151 quad_perm:[2,3,0,1] row_mask:0xf bank_mask:0xf bound_ctrl:1
	v_pk_fma_f32 v[104:105], v[124:125], v[122:123], v[104:105] op_sel_hi:[1,0,1]
	v_add_f32_dpp v148, v148, v148 row_half_mirror row_mask:0xf bank_mask:0xf bound_ctrl:1
	v_add_f32_dpp v149, v149, v149 row_half_mirror row_mask:0xf bank_mask:0xf bound_ctrl:1
	v_add_f32_dpp v150, v150, v150 row_half_mirror row_mask:0xf bank_mask:0xf bound_ctrl:1
	v_add_f32_dpp v151, v151, v151 row_half_mirror row_mask:0xf bank_mask:0xf bound_ctrl:1
	v_pk_fma_f32 v[106:107], v[124:125], v[122:123], v[106:107] op_sel:[0,1,0]
	v_add_f32_dpp v148, v148, v148 row_mirror row_mask:0xf bank_mask:0xf bound_ctrl:1
	v_add_f32_dpp v149, v149, v149 row_mirror row_mask:0xf bank_mask:0xf bound_ctrl:1
	v_add_f32_dpp v150, v150, v150 row_mirror row_mask:0xf bank_mask:0xf bound_ctrl:1
	v_pk_fma_f32 v[100:101], v[148:149], v[116:117], v[100:101] op_sel_hi:[1,0,1]
	v_pk_fma_f32 v[102:103], v[148:149], v[116:117], v[102:103] op_sel:[0,1,0]
	v_pk_fma_f32 v[104:105], v[148:149], v[118:119], v[104:105] op_sel_hi:[1,0,1]
	v_pk_fma_f32 v[106:107], v[148:149], v[118:119], v[106:107] op_sel:[0,1,0]
	v_add_f32_dpp v151, v151, v151 row_mirror row_mask:0xf bank_mask:0xf bound_ctrl:1
	v_pk_fma_f32 v[152:153], v[148:149], v[126:127], v[150:151] op_sel_hi:[1,0,1]
	v_pk_fma_f32 v[152:153], v[124:125], v[126:127], v[152:153] op_sel:[0,1,0]
	v_cvt_pk_bf16_f32 v154, v152, v153
	s_waitcnt lgkmcnt(0)
	ds_read_b128 v[108:111], v156 offset:37248
	ds_read_b128 v[112:115], v156 offset:37504
	ds_read_b128 v[120:123], v156 offset:38272
	ds_read_b64 v[124:125], v157 offset:37248
	ds_read_b128 v[116:119], v156 offset:38016
	ds_read_b64 v[126:127], v158 offset:37248
	ds_read_b128 v[204:207], v156 offset:36208
	v_mov_b32_dpp v155, v154 row_shr:6 row_mask:0xf bank_mask:0xf
	v_pk_mul_f32 v[148:149], v[100:101], v[128:129] op_sel_hi:[1,0]
	v_pk_mul_f32 v[150:151], v[100:101], v[132:133] op_sel_hi:[1,0]
	v_pk_fma_f32 v[148:149], v[102:103], v[128:129], v[148:149] op_sel:[0,1,0]
	v_pk_fma_f32 v[150:151], v[102:103], v[132:133], v[150:151] op_sel:[0,1,0]
	v_pk_fma_f32 v[148:149], v[104:105], v[130:131], v[148:149] op_sel_hi:[1,0,1]
	v_pk_fma_f32 v[150:151], v[104:105], v[134:135], v[150:151] op_sel_hi:[1,0,1]
	v_pk_fma_f32 v[148:149], v[106:107], v[130:131], v[148:149] op_sel:[0,1,0]
	v_pk_fma_f32 v[150:151], v[106:107], v[134:135], v[150:151] op_sel:[0,1,0]
	v_pk_fma_f32 v[100:101], v[144:145], v[140:141], v[100:101] op_sel_hi:[1,0,1]
	v_add_f32_dpp v148, v148, v148 quad_perm:[1,0,3,2] row_mask:0xf bank_mask:0xf bound_ctrl:1
	v_add_f32_dpp v149, v149, v149 quad_perm:[1,0,3,2] row_mask:0xf bank_mask:0xf bound_ctrl:1
	v_add_f32_dpp v150, v150, v150 quad_perm:[1,0,3,2] row_mask:0xf bank_mask:0xf bound_ctrl:1
	v_add_f32_dpp v151, v151, v151 quad_perm:[1,0,3,2] row_mask:0xf bank_mask:0xf bound_ctrl:1
	v_pk_fma_f32 v[102:103], v[144:145], v[140:141], v[102:103] op_sel:[0,1,0]
	v_add_f32_dpp v148, v148, v148 quad_perm:[2,3,0,1] row_mask:0xf bank_mask:0xf bound_ctrl:1
	v_add_f32_dpp v149, v149, v149 quad_perm:[2,3,0,1] row_mask:0xf bank_mask:0xf bound_ctrl:1
	v_add_f32_dpp v150, v150, v150 quad_perm:[2,3,0,1] row_mask:0xf bank_mask:0xf bound_ctrl:1
	v_add_f32_dpp v151, v151, v151 quad_perm:[2,3,0,1] row_mask:0xf bank_mask:0xf bound_ctrl:1
	v_pk_fma_f32 v[104:105], v[144:145], v[142:143], v[104:105] op_sel_hi:[1,0,1]
	v_add_f32_dpp v148, v148, v148 row_half_mirror row_mask:0xf bank_mask:0xf bound_ctrl:1
	v_add_f32_dpp v149, v149, v149 row_half_mirror row_mask:0xf bank_mask:0xf bound_ctrl:1
	v_add_f32_dpp v150, v150, v150 row_half_mirror row_mask:0xf bank_mask:0xf bound_ctrl:1
	v_add_f32_dpp v151, v151, v151 row_half_mirror row_mask:0xf bank_mask:0xf bound_ctrl:1
	v_pk_fma_f32 v[106:107], v[144:145], v[142:143], v[106:107] op_sel:[0,1,0]
	v_add_f32_dpp v148, v148, v148 row_mirror row_mask:0xf bank_mask:0xf bound_ctrl:1
	v_add_f32_dpp v149, v149, v149 row_mirror row_mask:0xf bank_mask:0xf bound_ctrl:1
	v_add_f32_dpp v150, v150, v150 row_mirror row_mask:0xf bank_mask:0xf bound_ctrl:1
	v_pk_fma_f32 v[100:101], v[148:149], v[136:137], v[100:101] op_sel_hi:[1,0,1]
	v_pk_fma_f32 v[102:103], v[148:149], v[136:137], v[102:103] op_sel:[0,1,0]
	v_pk_fma_f32 v[104:105], v[148:149], v[138:139], v[104:105] op_sel_hi:[1,0,1]
	v_pk_fma_f32 v[106:107], v[148:149], v[138:139], v[106:107] op_sel:[0,1,0]
	v_add_f32_dpp v151, v151, v151 row_mirror row_mask:0xf bank_mask:0xf bound_ctrl:1
	v_pk_fma_f32 v[152:153], v[148:149], v[146:147], v[150:151] op_sel_hi:[1,0,1]
	v_pk_fma_f32 v[152:153], v[144:145], v[146:147], v[152:153] op_sel:[0,1,0]
	v_cvt_pk_bf16_f32 v154, v152, v153
	s_waitcnt lgkmcnt(0)
	v_pk_mul_f32 v[100:101], v[100:101], v[204:205] op_sel_hi:[1,0]
	v_pk_mul_f32 v[102:103], v[102:103], v[204:205] op_sel:[0,1]
	v_pk_mul_f32 v[104:105], v[104:105], v[206:207] op_sel_hi:[1,0]
	v_pk_mul_f32 v[106:107], v[106:107], v[206:207] op_sel:[0,1]
	ds_read_b128 v[128:131], v156 offset:38800
	ds_read_b128 v[132:135], v156 offset:39056
	ds_read_b128 v[140:143], v156 offset:39824
	ds_read_b64 v[144:145], v157 offset:38800
	ds_read_b128 v[136:139], v156 offset:39568
	ds_read_b64 v[146:147], v158 offset:38800
	v_mov_b32_dpp v155, v154 row_shr:7 row_mask:0xf bank_mask:0xf
	v_pk_mul_f32 v[148:149], v[100:101], v[108:109] op_sel_hi:[1,0]
	v_pk_mul_f32 v[150:151], v[100:101], v[112:113] op_sel_hi:[1,0]
	v_pk_fma_f32 v[148:149], v[102:103], v[108:109], v[148:149] op_sel:[0,1,0]
	v_pk_fma_f32 v[150:151], v[102:103], v[112:113], v[150:151] op_sel:[0,1,0]
	v_pk_fma_f32 v[148:149], v[104:105], v[110:111], v[148:149] op_sel_hi:[1,0,1]
	v_pk_fma_f32 v[150:151], v[104:105], v[114:115], v[150:151] op_sel_hi:[1,0,1]
	v_pk_fma_f32 v[148:149], v[106:107], v[110:111], v[148:149] op_sel:[0,1,0]
	v_pk_fma_f32 v[150:151], v[106:107], v[114:115], v[150:151] op_sel:[0,1,0]
	v_pk_fma_f32 v[100:101], v[124:125], v[120:121], v[100:101] op_sel_hi:[1,0,1]
	v_add_f32_dpp v148, v148, v148 quad_perm:[1,0,3,2] row_mask:0xf bank_mask:0xf bound_ctrl:1
	v_add_f32_dpp v149, v149, v149 quad_perm:[1,0,3,2] row_mask:0xf bank_mask:0xf bound_ctrl:1
	v_add_f32_dpp v150, v150, v150 quad_perm:[1,0,3,2] row_mask:0xf bank_mask:0xf bound_ctrl:1
	v_add_f32_dpp v151, v151, v151 quad_perm:[1,0,3,2] row_mask:0xf bank_mask:0xf bound_ctrl:1
	v_pk_fma_f32 v[102:103], v[124:125], v[120:121], v[102:103] op_sel:[0,1,0]
	v_add_f32_dpp v148, v148, v148 quad_perm:[2,3,0,1] row_mask:0xf bank_mask:0xf bound_ctrl:1
	v_add_f32_dpp v149, v149, v149 quad_perm:[2,3,0,1] row_mask:0xf bank_mask:0xf bound_ctrl:1
	v_add_f32_dpp v150, v150, v150 quad_perm:[2,3,0,1] row_mask:0xf bank_mask:0xf bound_ctrl:1
	v_add_f32_dpp v151, v151, v151 quad_perm:[2,3,0,1] row_mask:0xf bank_mask:0xf bound_ctrl:1
	v_pk_fma_f32 v[104:105], v[124:125], v[122:123], v[104:105] op_sel_hi:[1,0,1]
	v_add_f32_dpp v148, v148, v148 row_half_mirror row_mask:0xf bank_mask:0xf bound_ctrl:1
	v_add_f32_dpp v149, v149, v149 row_half_mirror row_mask:0xf bank_mask:0xf bound_ctrl:1
	v_add_f32_dpp v150, v150, v150 row_half_mirror row_mask:0xf bank_mask:0xf bound_ctrl:1
	v_add_f32_dpp v151, v151, v151 row_half_mirror row_mask:0xf bank_mask:0xf bound_ctrl:1
	v_pk_fma_f32 v[106:107], v[124:125], v[122:123], v[106:107] op_sel:[0,1,0]
	v_add_f32_dpp v148, v148, v148 row_mirror row_mask:0xf bank_mask:0xf bound_ctrl:1
	v_add_f32_dpp v149, v149, v149 row_mirror row_mask:0xf bank_mask:0xf bound_ctrl:1
	v_add_f32_dpp v150, v150, v150 row_mirror row_mask:0xf bank_mask:0xf bound_ctrl:1
	v_pk_fma_f32 v[100:101], v[148:149], v[116:117], v[100:101] op_sel_hi:[1,0,1]
	v_pk_fma_f32 v[102:103], v[148:149], v[116:117], v[102:103] op_sel:[0,1,0]
	v_pk_fma_f32 v[104:105], v[148:149], v[118:119], v[104:105] op_sel_hi:[1,0,1]
	v_pk_fma_f32 v[106:107], v[148:149], v[118:119], v[106:107] op_sel:[0,1,0]
	v_add_f32_dpp v151, v151, v151 row_mirror row_mask:0xf bank_mask:0xf bound_ctrl:1
	v_pk_fma_f32 v[152:153], v[148:149], v[126:127], v[150:151] op_sel_hi:[1,0,1]
	v_pk_fma_f32 v[152:153], v[124:125], v[126:127], v[152:153] op_sel:[0,1,0]
	v_cvt_pk_bf16_f32 v154, v152, v153
	s_waitcnt lgkmcnt(0)
	ds_read_b128 v[108:111], v156 offset:40352
	ds_read_b128 v[112:115], v156 offset:40608
	ds_read_b128 v[120:123], v156 offset:41376
	ds_read_b64 v[124:125], v157 offset:40352
	ds_read_b128 v[116:119], v156 offset:41120
	ds_read_b64 v[126:127], v158 offset:40352
	v_mov_b32_dpp v155, v154 row_shr:8 row_mask:0xf bank_mask:0xf
	v_pk_mul_f32 v[148:149], v[100:101], v[128:129] op_sel_hi:[1,0]
	v_pk_mul_f32 v[150:151], v[100:101], v[132:133] op_sel_hi:[1,0]
	v_pk_fma_f32 v[148:149], v[102:103], v[128:129], v[148:149] op_sel:[0,1,0]
	v_pk_fma_f32 v[150:151], v[102:103], v[132:133], v[150:151] op_sel:[0,1,0]
	v_pk_fma_f32 v[148:149], v[104:105], v[130:131], v[148:149] op_sel_hi:[1,0,1]
	v_pk_fma_f32 v[150:151], v[104:105], v[134:135], v[150:151] op_sel_hi:[1,0,1]
	v_pk_fma_f32 v[148:149], v[106:107], v[130:131], v[148:149] op_sel:[0,1,0]
	v_pk_fma_f32 v[150:151], v[106:107], v[134:135], v[150:151] op_sel:[0,1,0]
	v_pk_fma_f32 v[100:101], v[144:145], v[140:141], v[100:101] op_sel_hi:[1,0,1]
	v_add_f32_dpp v148, v148, v148 quad_perm:[1,0,3,2] row_mask:0xf bank_mask:0xf bound_ctrl:1
	v_add_f32_dpp v149, v149, v149 quad_perm:[1,0,3,2] row_mask:0xf bank_mask:0xf bound_ctrl:1
	v_add_f32_dpp v150, v150, v150 quad_perm:[1,0,3,2] row_mask:0xf bank_mask:0xf bound_ctrl:1
	v_add_f32_dpp v151, v151, v151 quad_perm:[1,0,3,2] row_mask:0xf bank_mask:0xf bound_ctrl:1
	v_pk_fma_f32 v[102:103], v[144:145], v[140:141], v[102:103] op_sel:[0,1,0]
	v_add_f32_dpp v148, v148, v148 quad_perm:[2,3,0,1] row_mask:0xf bank_mask:0xf bound_ctrl:1
	v_add_f32_dpp v149, v149, v149 quad_perm:[2,3,0,1] row_mask:0xf bank_mask:0xf bound_ctrl:1
	v_add_f32_dpp v150, v150, v150 quad_perm:[2,3,0,1] row_mask:0xf bank_mask:0xf bound_ctrl:1
	v_add_f32_dpp v151, v151, v151 quad_perm:[2,3,0,1] row_mask:0xf bank_mask:0xf bound_ctrl:1
	v_pk_fma_f32 v[104:105], v[144:145], v[142:143], v[104:105] op_sel_hi:[1,0,1]
	v_add_f32_dpp v148, v148, v148 row_half_mirror row_mask:0xf bank_mask:0xf bound_ctrl:1
	v_add_f32_dpp v149, v149, v149 row_half_mirror row_mask:0xf bank_mask:0xf bound_ctrl:1
	v_add_f32_dpp v150, v150, v150 row_half_mirror row_mask:0xf bank_mask:0xf bound_ctrl:1
	v_add_f32_dpp v151, v151, v151 row_half_mirror row_mask:0xf bank_mask:0xf bound_ctrl:1
	v_pk_fma_f32 v[106:107], v[144:145], v[142:143], v[106:107] op_sel:[0,1,0]
	v_add_f32_dpp v148, v148, v148 row_mirror row_mask:0xf bank_mask:0xf bound_ctrl:1
	v_add_f32_dpp v149, v149, v149 row_mirror row_mask:0xf bank_mask:0xf bound_ctrl:1
	v_add_f32_dpp v150, v150, v150 row_mirror row_mask:0xf bank_mask:0xf bound_ctrl:1
	v_pk_fma_f32 v[100:101], v[148:149], v[136:137], v[100:101] op_sel_hi:[1,0,1]
	v_pk_fma_f32 v[102:103], v[148:149], v[136:137], v[102:103] op_sel:[0,1,0]
	v_pk_fma_f32 v[104:105], v[148:149], v[138:139], v[104:105] op_sel_hi:[1,0,1]
	v_pk_fma_f32 v[106:107], v[148:149], v[138:139], v[106:107] op_sel:[0,1,0]
	v_add_f32_dpp v151, v151, v151 row_mirror row_mask:0xf bank_mask:0xf bound_ctrl:1
	v_pk_fma_f32 v[152:153], v[148:149], v[146:147], v[150:151] op_sel_hi:[1,0,1]
	v_pk_fma_f32 v[152:153], v[144:145], v[146:147], v[152:153] op_sel:[0,1,0]
	v_cvt_pk_bf16_f32 v154, v152, v153
	s_waitcnt lgkmcnt(0)
	ds_read_b128 v[128:131], v156 offset:41904
	ds_read_b128 v[132:135], v156 offset:42160
	ds_read_b128 v[140:143], v156 offset:42928
	ds_read_b64 v[144:145], v157 offset:41904
	ds_read_b128 v[136:139], v156 offset:42672
	ds_read_b64 v[146:147], v158 offset:41904
	v_mov_b32_dpp v155, v154 row_shr:9 row_mask:0xf bank_mask:0xf
	v_pk_mul_f32 v[148:149], v[100:101], v[108:109] op_sel_hi:[1,0]
	v_pk_mul_f32 v[150:151], v[100:101], v[112:113] op_sel_hi:[1,0]
	v_pk_fma_f32 v[148:149], v[102:103], v[108:109], v[148:149] op_sel:[0,1,0]
	v_pk_fma_f32 v[150:151], v[102:103], v[112:113], v[150:151] op_sel:[0,1,0]
	v_pk_fma_f32 v[148:149], v[104:105], v[110:111], v[148:149] op_sel_hi:[1,0,1]
	v_pk_fma_f32 v[150:151], v[104:105], v[114:115], v[150:151] op_sel_hi:[1,0,1]
	v_pk_fma_f32 v[148:149], v[106:107], v[110:111], v[148:149] op_sel:[0,1,0]
	v_pk_fma_f32 v[150:151], v[106:107], v[114:115], v[150:151] op_sel:[0,1,0]
	v_pk_fma_f32 v[100:101], v[124:125], v[120:121], v[100:101] op_sel_hi:[1,0,1]
	v_add_f32_dpp v148, v148, v148 quad_perm:[1,0,3,2] row_mask:0xf bank_mask:0xf bound_ctrl:1
	v_add_f32_dpp v149, v149, v149 quad_perm:[1,0,3,2] row_mask:0xf bank_mask:0xf bound_ctrl:1
	v_add_f32_dpp v150, v150, v150 quad_perm:[1,0,3,2] row_mask:0xf bank_mask:0xf bound_ctrl:1
	v_add_f32_dpp v151, v151, v151 quad_perm:[1,0,3,2] row_mask:0xf bank_mask:0xf bound_ctrl:1
	v_pk_fma_f32 v[102:103], v[124:125], v[120:121], v[102:103] op_sel:[0,1,0]
	v_add_f32_dpp v148, v148, v148 quad_perm:[2,3,0,1] row_mask:0xf bank_mask:0xf bound_ctrl:1
	v_add_f32_dpp v149, v149, v149 quad_perm:[2,3,0,1] row_mask:0xf bank_mask:0xf bound_ctrl:1
	v_add_f32_dpp v150, v150, v150 quad_perm:[2,3,0,1] row_mask:0xf bank_mask:0xf bound_ctrl:1
	v_add_f32_dpp v151, v151, v151 quad_perm:[2,3,0,1] row_mask:0xf bank_mask:0xf bound_ctrl:1
	v_pk_fma_f32 v[104:105], v[124:125], v[122:123], v[104:105] op_sel_hi:[1,0,1]
	v_add_f32_dpp v148, v148, v148 row_half_mirror row_mask:0xf bank_mask:0xf bound_ctrl:1
	v_add_f32_dpp v149, v149, v149 row_half_mirror row_mask:0xf bank_mask:0xf bound_ctrl:1
	v_add_f32_dpp v150, v150, v150 row_half_mirror row_mask:0xf bank_mask:0xf bound_ctrl:1
	v_add_f32_dpp v151, v151, v151 row_half_mirror row_mask:0xf bank_mask:0xf bound_ctrl:1
	v_pk_fma_f32 v[106:107], v[124:125], v[122:123], v[106:107] op_sel:[0,1,0]
	v_add_f32_dpp v148, v148, v148 row_mirror row_mask:0xf bank_mask:0xf bound_ctrl:1
	v_add_f32_dpp v149, v149, v149 row_mirror row_mask:0xf bank_mask:0xf bound_ctrl:1
	v_add_f32_dpp v150, v150, v150 row_mirror row_mask:0xf bank_mask:0xf bound_ctrl:1
	v_pk_fma_f32 v[100:101], v[148:149], v[116:117], v[100:101] op_sel_hi:[1,0,1]
	v_pk_fma_f32 v[102:103], v[148:149], v[116:117], v[102:103] op_sel:[0,1,0]
	v_pk_fma_f32 v[104:105], v[148:149], v[118:119], v[104:105] op_sel_hi:[1,0,1]
	v_pk_fma_f32 v[106:107], v[148:149], v[118:119], v[106:107] op_sel:[0,1,0]
	v_add_f32_dpp v151, v151, v151 row_mirror row_mask:0xf bank_mask:0xf bound_ctrl:1
	v_pk_fma_f32 v[152:153], v[148:149], v[126:127], v[150:151] op_sel_hi:[1,0,1]
	v_pk_fma_f32 v[152:153], v[124:125], v[126:127], v[152:153] op_sel:[0,1,0]
	v_cvt_pk_bf16_f32 v154, v152, v153
	s_waitcnt lgkmcnt(0)
	ds_read_b128 v[108:111], v156 offset:43456
	ds_read_b128 v[112:115], v156 offset:43712
	ds_read_b128 v[120:123], v156 offset:44480
	ds_read_b64 v[124:125], v157 offset:43456
	ds_read_b128 v[116:119], v156 offset:44224
	ds_read_b64 v[126:127], v158 offset:43456
	v_mov_b32_dpp v155, v154 row_shr:10 row_mask:0xf bank_mask:0xf
	v_pk_mul_f32 v[148:149], v[100:101], v[128:129] op_sel_hi:[1,0]
	v_pk_mul_f32 v[150:151], v[100:101], v[132:133] op_sel_hi:[1,0]
	v_pk_fma_f32 v[148:149], v[102:103], v[128:129], v[148:149] op_sel:[0,1,0]
	v_pk_fma_f32 v[150:151], v[102:103], v[132:133], v[150:151] op_sel:[0,1,0]
	v_pk_fma_f32 v[148:149], v[104:105], v[130:131], v[148:149] op_sel_hi:[1,0,1]
	v_pk_fma_f32 v[150:151], v[104:105], v[134:135], v[150:151] op_sel_hi:[1,0,1]
	v_pk_fma_f32 v[148:149], v[106:107], v[130:131], v[148:149] op_sel:[0,1,0]
	v_pk_fma_f32 v[150:151], v[106:107], v[134:135], v[150:151] op_sel:[0,1,0]
	v_pk_fma_f32 v[100:101], v[144:145], v[140:141], v[100:101] op_sel_hi:[1,0,1]
	v_add_f32_dpp v148, v148, v148 quad_perm:[1,0,3,2] row_mask:0xf bank_mask:0xf bound_ctrl:1
	v_add_f32_dpp v149, v149, v149 quad_perm:[1,0,3,2] row_mask:0xf bank_mask:0xf bound_ctrl:1
	v_add_f32_dpp v150, v150, v150 quad_perm:[1,0,3,2] row_mask:0xf bank_mask:0xf bound_ctrl:1
	v_add_f32_dpp v151, v151, v151 quad_perm:[1,0,3,2] row_mask:0xf bank_mask:0xf bound_ctrl:1
	v_pk_fma_f32 v[102:103], v[144:145], v[140:141], v[102:103] op_sel:[0,1,0]
	v_add_f32_dpp v148, v148, v148 quad_perm:[2,3,0,1] row_mask:0xf bank_mask:0xf bound_ctrl:1
	v_add_f32_dpp v149, v149, v149 quad_perm:[2,3,0,1] row_mask:0xf bank_mask:0xf bound_ctrl:1
	v_add_f32_dpp v150, v150, v150 quad_perm:[2,3,0,1] row_mask:0xf bank_mask:0xf bound_ctrl:1
	v_add_f32_dpp v151, v151, v151 quad_perm:[2,3,0,1] row_mask:0xf bank_mask:0xf bound_ctrl:1
	v_pk_fma_f32 v[104:105], v[144:145], v[142:143], v[104:105] op_sel_hi:[1,0,1]
	v_add_f32_dpp v148, v148, v148 row_half_mirror row_mask:0xf bank_mask:0xf bound_ctrl:1
	v_add_f32_dpp v149, v149, v149 row_half_mirror row_mask:0xf bank_mask:0xf bound_ctrl:1
	v_add_f32_dpp v150, v150, v150 row_half_mirror row_mask:0xf bank_mask:0xf bound_ctrl:1
	v_add_f32_dpp v151, v151, v151 row_half_mirror row_mask:0xf bank_mask:0xf bound_ctrl:1
	v_pk_fma_f32 v[106:107], v[144:145], v[142:143], v[106:107] op_sel:[0,1,0]
	v_add_f32_dpp v148, v148, v148 row_mirror row_mask:0xf bank_mask:0xf bound_ctrl:1
	v_add_f32_dpp v149, v149, v149 row_mirror row_mask:0xf bank_mask:0xf bound_ctrl:1
	v_add_f32_dpp v150, v150, v150 row_mirror row_mask:0xf bank_mask:0xf bound_ctrl:1
	v_pk_fma_f32 v[100:101], v[148:149], v[136:137], v[100:101] op_sel_hi:[1,0,1]
	v_pk_fma_f32 v[102:103], v[148:149], v[136:137], v[102:103] op_sel:[0,1,0]
	v_pk_fma_f32 v[104:105], v[148:149], v[138:139], v[104:105] op_sel_hi:[1,0,1]
	v_pk_fma_f32 v[106:107], v[148:149], v[138:139], v[106:107] op_sel:[0,1,0]
	v_add_f32_dpp v151, v151, v151 row_mirror row_mask:0xf bank_mask:0xf bound_ctrl:1
	v_pk_fma_f32 v[152:153], v[148:149], v[146:147], v[150:151] op_sel_hi:[1,0,1]
	v_pk_fma_f32 v[152:153], v[144:145], v[146:147], v[152:153] op_sel:[0,1,0]
	v_cvt_pk_bf16_f32 v154, v152, v153
	s_waitcnt lgkmcnt(0)
	ds_read_b128 v[128:131], v156 offset:45008
	ds_read_b128 v[132:135], v156 offset:45264
	ds_read_b128 v[140:143], v156 offset:46032
	ds_read_b64 v[144:145], v157 offset:45008
	ds_read_b128 v[136:139], v156 offset:45776
	ds_read_b64 v[146:147], v158 offset:45008
	v_mov_b32_dpp v155, v154 row_shr:11 row_mask:0xf bank_mask:0xf
	v_pk_mul_f32 v[148:149], v[100:101], v[108:109] op_sel_hi:[1,0]
	v_pk_mul_f32 v[150:151], v[100:101], v[112:113] op_sel_hi:[1,0]
	v_pk_fma_f32 v[148:149], v[102:103], v[108:109], v[148:149] op_sel:[0,1,0]
	v_pk_fma_f32 v[150:151], v[102:103], v[112:113], v[150:151] op_sel:[0,1,0]
	v_pk_fma_f32 v[148:149], v[104:105], v[110:111], v[148:149] op_sel_hi:[1,0,1]
	v_pk_fma_f32 v[150:151], v[104:105], v[114:115], v[150:151] op_sel_hi:[1,0,1]
	v_pk_fma_f32 v[148:149], v[106:107], v[110:111], v[148:149] op_sel:[0,1,0]
	v_pk_fma_f32 v[150:151], v[106:107], v[114:115], v[150:151] op_sel:[0,1,0]
	v_pk_fma_f32 v[100:101], v[124:125], v[120:121], v[100:101] op_sel_hi:[1,0,1]
	v_add_f32_dpp v148, v148, v148 quad_perm:[1,0,3,2] row_mask:0xf bank_mask:0xf bound_ctrl:1
	v_add_f32_dpp v149, v149, v149 quad_perm:[1,0,3,2] row_mask:0xf bank_mask:0xf bound_ctrl:1
	v_add_f32_dpp v150, v150, v150 quad_perm:[1,0,3,2] row_mask:0xf bank_mask:0xf bound_ctrl:1
	v_add_f32_dpp v151, v151, v151 quad_perm:[1,0,3,2] row_mask:0xf bank_mask:0xf bound_ctrl:1
	v_pk_fma_f32 v[102:103], v[124:125], v[120:121], v[102:103] op_sel:[0,1,0]
	v_add_f32_dpp v148, v148, v148 quad_perm:[2,3,0,1] row_mask:0xf bank_mask:0xf bound_ctrl:1
	v_add_f32_dpp v149, v149, v149 quad_perm:[2,3,0,1] row_mask:0xf bank_mask:0xf bound_ctrl:1
	v_add_f32_dpp v150, v150, v150 quad_perm:[2,3,0,1] row_mask:0xf bank_mask:0xf bound_ctrl:1
	v_add_f32_dpp v151, v151, v151 quad_perm:[2,3,0,1] row_mask:0xf bank_mask:0xf bound_ctrl:1
	v_pk_fma_f32 v[104:105], v[124:125], v[122:123], v[104:105] op_sel_hi:[1,0,1]
	v_add_f32_dpp v148, v148, v148 row_half_mirror row_mask:0xf bank_mask:0xf bound_ctrl:1
	v_add_f32_dpp v149, v149, v149 row_half_mirror row_mask:0xf bank_mask:0xf bound_ctrl:1
	v_add_f32_dpp v150, v150, v150 row_half_mirror row_mask:0xf bank_mask:0xf bound_ctrl:1
	v_add_f32_dpp v151, v151, v151 row_half_mirror row_mask:0xf bank_mask:0xf bound_ctrl:1
	v_pk_fma_f32 v[106:107], v[124:125], v[122:123], v[106:107] op_sel:[0,1,0]
	v_add_f32_dpp v148, v148, v148 row_mirror row_mask:0xf bank_mask:0xf bound_ctrl:1
	v_add_f32_dpp v149, v149, v149 row_mirror row_mask:0xf bank_mask:0xf bound_ctrl:1
	v_add_f32_dpp v150, v150, v150 row_mirror row_mask:0xf bank_mask:0xf bound_ctrl:1
	v_pk_fma_f32 v[100:101], v[148:149], v[116:117], v[100:101] op_sel_hi:[1,0,1]
	v_pk_fma_f32 v[102:103], v[148:149], v[116:117], v[102:103] op_sel:[0,1,0]
	v_pk_fma_f32 v[104:105], v[148:149], v[118:119], v[104:105] op_sel_hi:[1,0,1]
	v_pk_fma_f32 v[106:107], v[148:149], v[118:119], v[106:107] op_sel:[0,1,0]
	v_add_f32_dpp v151, v151, v151 row_mirror row_mask:0xf bank_mask:0xf bound_ctrl:1
	v_pk_fma_f32 v[152:153], v[148:149], v[126:127], v[150:151] op_sel_hi:[1,0,1]
	v_pk_fma_f32 v[152:153], v[124:125], v[126:127], v[152:153] op_sel:[0,1,0]
	v_cvt_pk_bf16_f32 v154, v152, v153
	s_waitcnt lgkmcnt(0)
	ds_read_b128 v[108:111], v156 offset:46560
	ds_read_b128 v[112:115], v156 offset:46816
	ds_read_b128 v[120:123], v156 offset:47584
	ds_read_b64 v[124:125], v157 offset:46560
	ds_read_b128 v[116:119], v156 offset:47328
	ds_read_b64 v[126:127], v158 offset:46560
	v_mov_b32_dpp v155, v154 row_shr:12 row_mask:0xf bank_mask:0xf
	v_pk_mul_f32 v[148:149], v[100:101], v[128:129] op_sel_hi:[1,0]
	v_pk_mul_f32 v[150:151], v[100:101], v[132:133] op_sel_hi:[1,0]
	v_pk_fma_f32 v[148:149], v[102:103], v[128:129], v[148:149] op_sel:[0,1,0]
	v_pk_fma_f32 v[150:151], v[102:103], v[132:133], v[150:151] op_sel:[0,1,0]
	v_pk_fma_f32 v[148:149], v[104:105], v[130:131], v[148:149] op_sel_hi:[1,0,1]
	v_pk_fma_f32 v[150:151], v[104:105], v[134:135], v[150:151] op_sel_hi:[1,0,1]
	v_pk_fma_f32 v[148:149], v[106:107], v[130:131], v[148:149] op_sel:[0,1,0]
	v_pk_fma_f32 v[150:151], v[106:107], v[134:135], v[150:151] op_sel:[0,1,0]
	v_pk_fma_f32 v[100:101], v[144:145], v[140:141], v[100:101] op_sel_hi:[1,0,1]
	v_add_f32_dpp v148, v148, v148 quad_perm:[1,0,3,2] row_mask:0xf bank_mask:0xf bound_ctrl:1
	v_add_f32_dpp v149, v149, v149 quad_perm:[1,0,3,2] row_mask:0xf bank_mask:0xf bound_ctrl:1
	v_add_f32_dpp v150, v150, v150 quad_perm:[1,0,3,2] row_mask:0xf bank_mask:0xf bound_ctrl:1
	v_add_f32_dpp v151, v151, v151 quad_perm:[1,0,3,2] row_mask:0xf bank_mask:0xf bound_ctrl:1
	v_pk_fma_f32 v[102:103], v[144:145], v[140:141], v[102:103] op_sel:[0,1,0]
	v_add_f32_dpp v148, v148, v148 quad_perm:[2,3,0,1] row_mask:0xf bank_mask:0xf bound_ctrl:1
	v_add_f32_dpp v149, v149, v149 quad_perm:[2,3,0,1] row_mask:0xf bank_mask:0xf bound_ctrl:1
	v_add_f32_dpp v150, v150, v150 quad_perm:[2,3,0,1] row_mask:0xf bank_mask:0xf bound_ctrl:1
	v_add_f32_dpp v151, v151, v151 quad_perm:[2,3,0,1] row_mask:0xf bank_mask:0xf bound_ctrl:1
	v_pk_fma_f32 v[104:105], v[144:145], v[142:143], v[104:105] op_sel_hi:[1,0,1]
	v_add_f32_dpp v148, v148, v148 row_half_mirror row_mask:0xf bank_mask:0xf bound_ctrl:1
	v_add_f32_dpp v149, v149, v149 row_half_mirror row_mask:0xf bank_mask:0xf bound_ctrl:1
	v_add_f32_dpp v150, v150, v150 row_half_mirror row_mask:0xf bank_mask:0xf bound_ctrl:1
	v_add_f32_dpp v151, v151, v151 row_half_mirror row_mask:0xf bank_mask:0xf bound_ctrl:1
	v_pk_fma_f32 v[106:107], v[144:145], v[142:143], v[106:107] op_sel:[0,1,0]
	v_add_f32_dpp v148, v148, v148 row_mirror row_mask:0xf bank_mask:0xf bound_ctrl:1
	v_add_f32_dpp v149, v149, v149 row_mirror row_mask:0xf bank_mask:0xf bound_ctrl:1
	v_add_f32_dpp v150, v150, v150 row_mirror row_mask:0xf bank_mask:0xf bound_ctrl:1
	v_pk_fma_f32 v[100:101], v[148:149], v[136:137], v[100:101] op_sel_hi:[1,0,1]
	v_pk_fma_f32 v[102:103], v[148:149], v[136:137], v[102:103] op_sel:[0,1,0]
	v_pk_fma_f32 v[104:105], v[148:149], v[138:139], v[104:105] op_sel_hi:[1,0,1]
	v_pk_fma_f32 v[106:107], v[148:149], v[138:139], v[106:107] op_sel:[0,1,0]
	v_add_f32_dpp v151, v151, v151 row_mirror row_mask:0xf bank_mask:0xf bound_ctrl:1
	v_pk_fma_f32 v[152:153], v[148:149], v[146:147], v[150:151] op_sel_hi:[1,0,1]
	v_pk_fma_f32 v[152:153], v[144:145], v[146:147], v[152:153] op_sel:[0,1,0]
	v_cvt_pk_bf16_f32 v154, v152, v153
	s_waitcnt lgkmcnt(0)
	ds_read_b128 v[128:131], v156 offset:48112
	ds_read_b128 v[132:135], v156 offset:48368
	ds_read_b128 v[140:143], v156 offset:49136
	ds_read_b64 v[144:145], v157 offset:48112
	ds_read_b128 v[136:139], v156 offset:48880
	ds_read_b64 v[146:147], v158 offset:48112
	v_mov_b32_dpp v155, v154 row_shr:13 row_mask:0xf bank_mask:0xf
	v_pk_mul_f32 v[148:149], v[100:101], v[108:109] op_sel_hi:[1,0]
	v_pk_mul_f32 v[150:151], v[100:101], v[112:113] op_sel_hi:[1,0]
	v_pk_fma_f32 v[148:149], v[102:103], v[108:109], v[148:149] op_sel:[0,1,0]
	v_pk_fma_f32 v[150:151], v[102:103], v[112:113], v[150:151] op_sel:[0,1,0]
	v_pk_fma_f32 v[148:149], v[104:105], v[110:111], v[148:149] op_sel_hi:[1,0,1]
	v_pk_fma_f32 v[150:151], v[104:105], v[114:115], v[150:151] op_sel_hi:[1,0,1]
	v_pk_fma_f32 v[148:149], v[106:107], v[110:111], v[148:149] op_sel:[0,1,0]
	v_pk_fma_f32 v[150:151], v[106:107], v[114:115], v[150:151] op_sel:[0,1,0]
	v_pk_fma_f32 v[100:101], v[124:125], v[120:121], v[100:101] op_sel_hi:[1,0,1]
	v_add_f32_dpp v148, v148, v148 quad_perm:[1,0,3,2] row_mask:0xf bank_mask:0xf bound_ctrl:1
	v_add_f32_dpp v149, v149, v149 quad_perm:[1,0,3,2] row_mask:0xf bank_mask:0xf bound_ctrl:1
	v_add_f32_dpp v150, v150, v150 quad_perm:[1,0,3,2] row_mask:0xf bank_mask:0xf bound_ctrl:1
	v_add_f32_dpp v151, v151, v151 quad_perm:[1,0,3,2] row_mask:0xf bank_mask:0xf bound_ctrl:1
	v_pk_fma_f32 v[102:103], v[124:125], v[120:121], v[102:103] op_sel:[0,1,0]
	v_add_f32_dpp v148, v148, v148 quad_perm:[2,3,0,1] row_mask:0xf bank_mask:0xf bound_ctrl:1
	v_add_f32_dpp v149, v149, v149 quad_perm:[2,3,0,1] row_mask:0xf bank_mask:0xf bound_ctrl:1
	v_add_f32_dpp v150, v150, v150 quad_perm:[2,3,0,1] row_mask:0xf bank_mask:0xf bound_ctrl:1
	v_add_f32_dpp v151, v151, v151 quad_perm:[2,3,0,1] row_mask:0xf bank_mask:0xf bound_ctrl:1
	v_pk_fma_f32 v[104:105], v[124:125], v[122:123], v[104:105] op_sel_hi:[1,0,1]
	v_add_f32_dpp v148, v148, v148 row_half_mirror row_mask:0xf bank_mask:0xf bound_ctrl:1
	v_add_f32_dpp v149, v149, v149 row_half_mirror row_mask:0xf bank_mask:0xf bound_ctrl:1
	v_add_f32_dpp v150, v150, v150 row_half_mirror row_mask:0xf bank_mask:0xf bound_ctrl:1
	v_add_f32_dpp v151, v151, v151 row_half_mirror row_mask:0xf bank_mask:0xf bound_ctrl:1
	v_pk_fma_f32 v[106:107], v[124:125], v[122:123], v[106:107] op_sel:[0,1,0]
	v_add_f32_dpp v148, v148, v148 row_mirror row_mask:0xf bank_mask:0xf bound_ctrl:1
	v_add_f32_dpp v149, v149, v149 row_mirror row_mask:0xf bank_mask:0xf bound_ctrl:1
	v_add_f32_dpp v150, v150, v150 row_mirror row_mask:0xf bank_mask:0xf bound_ctrl:1
	v_pk_fma_f32 v[100:101], v[148:149], v[116:117], v[100:101] op_sel_hi:[1,0,1]
	v_pk_fma_f32 v[102:103], v[148:149], v[116:117], v[102:103] op_sel:[0,1,0]
	v_pk_fma_f32 v[104:105], v[148:149], v[118:119], v[104:105] op_sel_hi:[1,0,1]
	v_pk_fma_f32 v[106:107], v[148:149], v[118:119], v[106:107] op_sel:[0,1,0]
	v_add_f32_dpp v151, v151, v151 row_mirror row_mask:0xf bank_mask:0xf bound_ctrl:1
	v_pk_fma_f32 v[152:153], v[148:149], v[126:127], v[150:151] op_sel_hi:[1,0,1]
	v_pk_fma_f32 v[152:153], v[124:125], v[126:127], v[152:153] op_sel:[0,1,0]
	v_cvt_pk_bf16_f32 v154, v152, v153
	s_waitcnt lgkmcnt(0)
	ds_read_b128 v[204:207], v156 offset:48624
	s_nop 0
	v_mov_b32_dpp v155, v154 row_shr:14 row_mask:0xf bank_mask:0xf
	v_pk_mul_f32 v[148:149], v[100:101], v[128:129] op_sel_hi:[1,0]
	v_pk_mul_f32 v[150:151], v[100:101], v[132:133] op_sel_hi:[1,0]
	v_pk_fma_f32 v[148:149], v[102:103], v[128:129], v[148:149] op_sel:[0,1,0]
	v_pk_fma_f32 v[150:151], v[102:103], v[132:133], v[150:151] op_sel:[0,1,0]
	v_pk_fma_f32 v[148:149], v[104:105], v[130:131], v[148:149] op_sel_hi:[1,0,1]
	v_pk_fma_f32 v[150:151], v[104:105], v[134:135], v[150:151] op_sel_hi:[1,0,1]
	v_pk_fma_f32 v[148:149], v[106:107], v[130:131], v[148:149] op_sel:[0,1,0]
	v_pk_fma_f32 v[150:151], v[106:107], v[134:135], v[150:151] op_sel:[0,1,0]
	v_pk_fma_f32 v[100:101], v[144:145], v[140:141], v[100:101] op_sel_hi:[1,0,1]
	v_add_f32_dpp v148, v148, v148 quad_perm:[1,0,3,2] row_mask:0xf bank_mask:0xf bound_ctrl:1
	v_add_f32_dpp v149, v149, v149 quad_perm:[1,0,3,2] row_mask:0xf bank_mask:0xf bound_ctrl:1
	v_add_f32_dpp v150, v150, v150 quad_perm:[1,0,3,2] row_mask:0xf bank_mask:0xf bound_ctrl:1
	v_add_f32_dpp v151, v151, v151 quad_perm:[1,0,3,2] row_mask:0xf bank_mask:0xf bound_ctrl:1
	v_pk_fma_f32 v[102:103], v[144:145], v[140:141], v[102:103] op_sel:[0,1,0]
	v_add_f32_dpp v148, v148, v148 quad_perm:[2,3,0,1] row_mask:0xf bank_mask:0xf bound_ctrl:1
	v_add_f32_dpp v149, v149, v149 quad_perm:[2,3,0,1] row_mask:0xf bank_mask:0xf bound_ctrl:1
	v_add_f32_dpp v150, v150, v150 quad_perm:[2,3,0,1] row_mask:0xf bank_mask:0xf bound_ctrl:1
	v_add_f32_dpp v151, v151, v151 quad_perm:[2,3,0,1] row_mask:0xf bank_mask:0xf bound_ctrl:1
	v_pk_fma_f32 v[104:105], v[144:145], v[142:143], v[104:105] op_sel_hi:[1,0,1]
	v_add_f32_dpp v148, v148, v148 row_half_mirror row_mask:0xf bank_mask:0xf bound_ctrl:1
	v_add_f32_dpp v149, v149, v149 row_half_mirror row_mask:0xf bank_mask:0xf bound_ctrl:1
	v_add_f32_dpp v150, v150, v150 row_half_mirror row_mask:0xf bank_mask:0xf bound_ctrl:1
	v_add_f32_dpp v151, v151, v151 row_half_mirror row_mask:0xf bank_mask:0xf bound_ctrl:1
	v_pk_fma_f32 v[106:107], v[144:145], v[142:143], v[106:107] op_sel:[0,1,0]
	v_add_f32_dpp v148, v148, v148 row_mirror row_mask:0xf bank_mask:0xf bound_ctrl:1
	v_add_f32_dpp v149, v149, v149 row_mirror row_mask:0xf bank_mask:0xf bound_ctrl:1
	v_add_f32_dpp v150, v150, v150 row_mirror row_mask:0xf bank_mask:0xf bound_ctrl:1
	v_pk_fma_f32 v[100:101], v[148:149], v[136:137], v[100:101] op_sel_hi:[1,0,1]
	v_pk_fma_f32 v[102:103], v[148:149], v[136:137], v[102:103] op_sel:[0,1,0]
	v_pk_fma_f32 v[104:105], v[148:149], v[138:139], v[104:105] op_sel_hi:[1,0,1]
	v_pk_fma_f32 v[106:107], v[148:149], v[138:139], v[106:107] op_sel:[0,1,0]
	v_add_f32_dpp v151, v151, v151 row_mirror row_mask:0xf bank_mask:0xf bound_ctrl:1
	v_pk_fma_f32 v[152:153], v[148:149], v[146:147], v[150:151] op_sel_hi:[1,0,1]
	v_pk_fma_f32 v[152:153], v[144:145], v[146:147], v[152:153] op_sel:[0,1,0]
	v_cvt_pk_bf16_f32 v154, v152, v153
	s_waitcnt lgkmcnt(0)
	v_pk_mul_f32 v[100:101], v[100:101], v[204:205] op_sel_hi:[1,0]
	v_pk_mul_f32 v[102:103], v[102:103], v[204:205] op_sel:[0,1]
	v_pk_mul_f32 v[104:105], v[104:105], v[206:207] op_sel_hi:[1,0]
	v_pk_mul_f32 v[106:107], v[106:107], v[206:207] op_sel:[0,1]
	v_mov_b32_dpp v155, v154 row_shr:15 row_mask:0xf bank_mask:0xf
	global_store_dword v[160:161], v155, off
	s_cmp_lg_u32 s30, 63
	s_cbranch_scc1 .Lrwp_done
	v_mov_b32_e32 v14, v100
	v_mov_b32_e32 v15, v102
	v_mov_b32_e32 v16, v104
	v_mov_b32_e32 v17, v106
	v_mov_b32_e32 v10, v101
	v_mov_b32_e32 v11, v103
	v_mov_b32_e32 v12, v105
	v_mov_b32_e32 v13, v107
